# SGPR-base + lane-offset form for 56 K-loop LDS-DMA loads (drops their 64-bit VALU address adds) on top of the best attention/GEMM version
# speedup vs baseline: 1.0022x; 1.0012x over previous
.LBB0_368:
	s_ashr_i32 s55, s54, 31
	s_lshl_b64 s[2:3], s[54:55], 20
	s_add_u32 s58, s64, s2
	s_addc_u32 s59, s65, s3
	s_and_b64 s[2:3], s[38:39], exec
	s_cselect_b32 s40, s59, s19
	s_cselect_b32 s41, s58, s18
	s_ashr_i32 s57, s56, 31
	s_lshl_b64 s[2:3], s[56:57], 20
	s_add_u32 s60, s66, s2
	s_addc_u32 s61, s67, s3
	s_and_b64 s[2:3], s[38:39], exec
	s_mul_hi_i32 s5, s62, 0x78787879
	s_cselect_b32 s57, s61, s27
	s_cselect_b32 s4, s60, s26
	s_lshr_b32 s15, s5, 31
	s_ashr_i32 s5, s5, 3
	s_add_i32 s5, s5, s15
	s_mul_i32 s15, s5, 17
	s_mul_i32 s23, s5, 0xf400
	s_mul_hi_i32 s28, s5, 0xf400
	s_mul_hi_i32 s5, s14, 0x55555556
	s_sub_i32 s22, s62, s15
	s_lshr_b32 s15, s5, 31
	s_lshl_b32 s74, s62, 8
	s_add_i32 s20, s5, s15
	s_ashr_i32 s75, s74, 31
	s_lshl_b32 s24, s14, 8
	s_mul_i32 s5, s20, -3
	s_lshl_b64 s[2:3], s[74:75], 5
	s_ashr_i32 s25, s24, 31
	s_add_i32 s55, s5, s14
	s_cmp_lg_u32 s55, 0
	s_cselect_b64 s[14:15], -1, 0
	s_and_b64 s[16:17], s[44:45], s[14:15]
	s_lshl_b32 s14, s20, 8
	s_lshl_b32 s20, s55, 7
	s_addk_i32 s20, 0xff80
	s_ashr_i32 s15, s14, 31
	s_ashr_i32 s21, s20, 31
	s_cmp_lg_u32 s22, 0
	s_cselect_b32 s29, s28, 0
	s_cselect_b32 s28, s23, 0x7a000
	s_lshl_b64 s[22:23], s[14:15], 2
	s_add_u32 s15, s79, s22
	s_addc_u32 s22, s80, s23
	s_lshl_b64 s[20:21], s[20:21], 2
	s_add_u32 s20, s15, s20
	s_addc_u32 s21, s22, s21
	s_add_u32 s22, s81, s2
	s_addc_u32 s23, s82, s3
	s_lshl_b64 s[2:3], s[28:29], 2
	s_add_u32 s15, s83, s2
	s_addc_u32 s28, s84, s3
	s_lshl_b64 s[2:3], s[24:25], 2
	s_add_u32 s24, s15, s2
	s_addc_u32 s25, s28, s3
	s_add_u32 s15, s26, 0x100
	s_mov_b32 s5, 0
	s_addc_u32 s75, s27, 0
	s_add_u32 s26, s18, 0x100
	s_addc_u32 s27, s19, 0
	s_cmp_eq_u32 s5, 30
	s_cselect_b32 s31, s40, s27
	s_cselect_b32 s30, s41, s26
	s_cselect_b32 s29, s57, s75
	s_cselect_b32 s28, s4, s15
	s_add_i32 s2, 0, 0x10000
	v_add_u32_e32 v152, s2, v154
	s_add_i32 vcc_lo, 0, 0x14000
	ds_read_b128 v[140:143], v152
	ds_read_b128 v[144:147], v152 offset:1024
	ds_read_b128 v[148:151], v152 offset:2048
	ds_read_b128 v[156:159], v152 offset:3072
	v_add_u32_e32 v152, vcc_lo, v154
	ds_read_b128 v[160:163], v152
	ds_read_b128 v[164:167], v152 offset:1024
	ds_read_b128 v[168:171], v152 offset:2048
	ds_read_b128 v[172:175], v152 offset:3072
	v_lshl_add_u64 v[152:153], s[18:19], 0, v[136:137]
	s_add_i32 m0, s63, 0xc000
	ds_read_b128 v[176:179], v155
	ds_read_b128 v[180:183], v155 offset:1024
	ds_read_b128 v[184:187], v155 offset:2048
	ds_read_b128 v[188:191], v155 offset:3072
	ds_read_b128 v[192:195], v155 offset:4096
	ds_read_b128 v[196:199], v155 offset:5120
	ds_read_b128 v[200:203], v155 offset:6144
	ds_read_b128 v[204:207], v155 offset:7168
	global_load_lds_dwordx4 v[152:153], off
	v_lshl_add_u64 v[152:153], s[18:19], 0, v[138:139]
	s_add_i32 m0, s63, 0xe000
	s_nop 0
	global_load_lds_dwordx4 v[152:153], off
	s_waitcnt vmcnt(8)
	s_waitcnt lgkmcnt(0)
	s_barrier
	s_setprio 1
	s_waitcnt lgkmcnt(0)
	v_mfma_f32_16x16x32_bf16 v[96:99], v[140:143], v[176:179], 0
	v_mfma_f32_16x16x32_bf16 v[96:99], v[144:147], v[180:183], v[96:99]
	v_mfma_f32_16x16x32_bf16 v[124:127], v[140:143], v[184:187], 0
	v_mfma_f32_16x16x32_bf16 v[124:127], v[144:147], v[188:191], v[124:127]
	v_mfma_f32_16x16x32_bf16 v[120:123], v[140:143], v[192:195], 0
	v_mfma_f32_16x16x32_bf16 v[120:123], v[144:147], v[196:199], v[120:123]
	v_mfma_f32_16x16x32_bf16 v[84:87], v[140:143], v[200:203], 0
	v_mfma_f32_16x16x32_bf16 v[84:87], v[144:147], v[204:207], v[84:87]
	v_mfma_f32_16x16x32_bf16 v[56:59], v[148:151], v[176:179], 0
	v_mfma_f32_16x16x32_bf16 v[56:59], v[156:159], v[180:183], v[56:59]
	v_mfma_f32_16x16x32_bf16 v[116:119], v[148:151], v[184:187], 0
	v_mfma_f32_16x16x32_bf16 v[116:119], v[156:159], v[188:191], v[116:119]
	v_mfma_f32_16x16x32_bf16 v[112:115], v[148:151], v[192:195], 0
	v_mfma_f32_16x16x32_bf16 v[112:115], v[156:159], v[196:199], v[112:115]
	v_mfma_f32_16x16x32_bf16 v[48:51], v[148:151], v[200:203], 0
	v_mfma_f32_16x16x32_bf16 v[48:51], v[156:159], v[204:207], v[48:51]
	s_setprio 0
	s_setprio 1
	v_mfma_f32_16x16x32_bf16 v[100:103], v[160:163], v[176:179], 0
	v_mfma_f32_16x16x32_bf16 v[100:103], v[164:167], v[180:183], v[100:103]
	v_mfma_f32_16x16x32_bf16 v[88:91], v[160:163], v[184:187], 0
	v_mfma_f32_16x16x32_bf16 v[88:91], v[164:167], v[188:191], v[88:91]
	v_mfma_f32_16x16x32_bf16 v[72:75], v[160:163], v[192:195], 0
	v_mfma_f32_16x16x32_bf16 v[72:75], v[164:167], v[196:199], v[72:75]
	v_mfma_f32_16x16x32_bf16 v[64:67], v[160:163], v[200:203], 0
	v_mfma_f32_16x16x32_bf16 v[64:67], v[164:167], v[204:207], v[64:67]
	v_mfma_f32_16x16x32_bf16 v[60:63], v[168:171], v[176:179], 0
	v_mfma_f32_16x16x32_bf16 v[60:63], v[172:175], v[180:183], v[60:63]
	v_mfma_f32_16x16x32_bf16 v[44:47], v[168:171], v[184:187], 0
	v_mfma_f32_16x16x32_bf16 v[44:47], v[172:175], v[188:191], v[44:47]
	v_mfma_f32_16x16x32_bf16 v[32:35], v[168:171], v[192:195], 0
	v_mfma_f32_16x16x32_bf16 v[32:35], v[172:175], v[196:199], v[32:35]
	v_mfma_f32_16x16x32_bf16 v[24:27], v[168:171], v[200:203], 0
	v_mfma_f32_16x16x32_bf16 v[24:27], v[172:175], v[204:207], v[24:27]
	s_setprio 0
	s_barrier
	s_nop 1
	s_add_i32 s2, s2, s69
	v_lshl_add_u64 v[152:153], s[28:29], 0, v[130:131]
	s_mov_b32 m0, s2
	ds_read_b128 v[176:179], v155 offset:16384
	ds_read_b128 v[180:183], v155 offset:17408
	ds_read_b128 v[184:187], v155 offset:18432
	ds_read_b128 v[188:191], v155 offset:19456
	ds_read_b128 v[192:195], v155 offset:20480
	ds_read_b128 v[196:199], v155 offset:21504
	ds_read_b128 v[200:203], v155 offset:22528
	ds_read_b128 v[204:207], v155 offset:23552
	global_load_lds_dwordx4 v[152:153], off
	s_add_i32 m0, s2, 0x2000
	s_add_u32 s2, s28, 0x80000
	v_lshl_add_u64 v[208:209], s[28:29], 0, v[134:135]
	s_addc_u32 s3, s29, 0
	s_add_i32 s18, vcc_lo, s69
	global_load_lds_dwordx4 v[208:209], off
	s_mov_b32 m0, s18
	v_lshl_add_u64 v[214:215], s[30:31], 0, v[132:133]
	global_load_lds_dwordx4 v130, s[2:3]
	s_add_i32 m0, s18, 0x2000
	s_nop 0
	global_load_lds_dwordx4 v134, s[2:3]
	v_lshl_add_u64 v[210:211], s[30:31], 0, v[128:129]
	s_mov_b32 m0, s63
	s_nop 0
	global_load_lds_dwordx4 v[210:211], off
	s_mov_b32 m0, s70
	s_nop 0
	global_load_lds_dwordx4 v[214:215], off
	s_waitcnt vmcnt(8)
	s_waitcnt lgkmcnt(0)
	s_barrier
	s_setprio 1
	s_waitcnt lgkmcnt(0)
	v_mfma_f32_16x16x32_bf16 v[92:95], v[140:143], v[176:179], 0
	v_mfma_f32_16x16x32_bf16 v[92:95], v[144:147], v[180:183], v[92:95]
	v_mfma_f32_16x16x32_bf16 v[108:111], v[140:143], v[184:187], 0
	v_mfma_f32_16x16x32_bf16 v[108:111], v[144:147], v[188:191], v[108:111]
	v_mfma_f32_16x16x32_bf16 v[104:107], v[140:143], v[192:195], 0
	v_mfma_f32_16x16x32_bf16 v[104:107], v[144:147], v[196:199], v[104:107]
	v_mfma_f32_16x16x32_bf16 v[76:79], v[140:143], v[200:203], 0
	v_mfma_f32_16x16x32_bf16 v[76:79], v[144:147], v[204:207], v[76:79]
	v_mfma_f32_16x16x32_bf16 v[52:55], v[148:151], v[176:179], 0
	v_mfma_f32_16x16x32_bf16 v[52:55], v[156:159], v[180:183], v[52:55]
	v_mfma_f32_16x16x32_bf16 v[80:83], v[148:151], v[184:187], 0
	v_mfma_f32_16x16x32_bf16 v[80:83], v[156:159], v[188:191], v[80:83]
	v_mfma_f32_16x16x32_bf16 v[68:71], v[148:151], v[192:195], 0
	v_mfma_f32_16x16x32_bf16 v[68:71], v[156:159], v[196:199], v[68:71]
	v_mfma_f32_16x16x32_bf16 v[36:39], v[148:151], v[200:203], 0
	v_mfma_f32_16x16x32_bf16 v[36:39], v[156:159], v[204:207], v[36:39]
	s_setprio 0
	s_setprio 1
	v_mfma_f32_16x16x32_bf16 v[40:43], v[160:163], v[176:179], 0
	v_mfma_f32_16x16x32_bf16 v[40:43], v[164:167], v[180:183], v[40:43]
	v_mfma_f32_16x16x32_bf16 v[28:31], v[160:163], v[184:187], 0
	v_mfma_f32_16x16x32_bf16 v[28:31], v[164:167], v[188:191], v[28:31]
	v_mfma_f32_16x16x32_bf16 v[20:23], v[160:163], v[192:195], 0
	v_mfma_f32_16x16x32_bf16 v[20:23], v[164:167], v[196:199], v[20:23]
	v_mfma_f32_16x16x32_bf16 v[16:19], v[160:163], v[200:203], 0
	v_mfma_f32_16x16x32_bf16 v[16:19], v[164:167], v[204:207], v[16:19]
	v_mfma_f32_16x16x32_bf16 v[12:15], v[168:171], v[176:179], 0
	v_mfma_f32_16x16x32_bf16 v[12:15], v[172:175], v[180:183], v[12:15]
	v_mfma_f32_16x16x32_bf16 v[8:11], v[168:171], v[184:187], 0
	v_mfma_f32_16x16x32_bf16 v[8:11], v[172:175], v[188:191], v[8:11]
	v_mfma_f32_16x16x32_bf16 v[4:7], v[168:171], v[192:195], 0
	v_mfma_f32_16x16x32_bf16 v[4:7], v[172:175], v[196:199], v[4:7]
	v_mfma_f32_16x16x32_bf16 v[0:3], v[168:171], v[200:203], 0
	v_mfma_f32_16x16x32_bf16 v[0:3], v[172:175], v[204:207], v[0:3]
	s_setprio 0
	s_barrier
	s_nop 1
	s_add_i32 s18, 0, 0x18000
	s_add_i32 s19, 0, 0x1c000
	v_add_u32_e32 v156, s18, v154
	v_add_u32_e32 v172, s19, v154
	ds_read_b128 v[140:143], v156
	ds_read_b128 v[144:147], v156 offset:1024
	ds_read_b128 v[148:151], v156 offset:2048
	ds_read_b128 v[156:159], v156 offset:3072
	ds_read_b128 v[160:163], v172
	ds_read_b128 v[164:167], v172 offset:1024
	ds_read_b128 v[168:171], v172 offset:2048
	ds_read_b128 v[172:175], v172 offset:3072
	s_add_u32 s2, s30, 0x80000
	s_addc_u32 s3, s31, 0
	s_mov_b32 m0, s71
	ds_read_b128 v[176:179], v155 offset:32768
	ds_read_b128 v[180:183], v155 offset:33792
	ds_read_b128 v[184:187], v155 offset:34816
	ds_read_b128 v[188:191], v155 offset:35840
	ds_read_b128 v[192:195], v155 offset:36864
	ds_read_b128 v[196:199], v155 offset:37888
	ds_read_b128 v[200:203], v155 offset:38912
	ds_read_b128 v[204:207], v155 offset:39936
	global_load_lds_dwordx4 v128, s[2:3]
	v_lshl_add_u64 v[216:217], s[2:3], 0, v[132:133]
	s_mov_b32 m0, s76
	s_nop 0
	global_load_lds_dwordx4 v[216:217], off
	s_waitcnt vmcnt(8)
	s_waitcnt lgkmcnt(0)
	s_barrier
	s_setprio 1
	s_waitcnt lgkmcnt(0)
	v_mfma_f32_16x16x32_bf16 v[96:99], v[140:143], v[176:179], v[96:99]
	v_mfma_f32_16x16x32_bf16 v[96:99], v[144:147], v[180:183], v[96:99]
	v_mfma_f32_16x16x32_bf16 v[124:127], v[140:143], v[184:187], v[124:127]
	v_mfma_f32_16x16x32_bf16 v[124:127], v[144:147], v[188:191], v[124:127]
	v_mfma_f32_16x16x32_bf16 v[120:123], v[140:143], v[192:195], v[120:123]
	v_mfma_f32_16x16x32_bf16 v[120:123], v[144:147], v[196:199], v[120:123]
	v_mfma_f32_16x16x32_bf16 v[84:87], v[140:143], v[200:203], v[84:87]
	v_mfma_f32_16x16x32_bf16 v[84:87], v[144:147], v[204:207], v[84:87]
	v_mfma_f32_16x16x32_bf16 v[56:59], v[148:151], v[176:179], v[56:59]
	v_mfma_f32_16x16x32_bf16 v[56:59], v[156:159], v[180:183], v[56:59]
	v_mfma_f32_16x16x32_bf16 v[116:119], v[148:151], v[184:187], v[116:119]
	v_mfma_f32_16x16x32_bf16 v[116:119], v[156:159], v[188:191], v[116:119]
	v_mfma_f32_16x16x32_bf16 v[112:115], v[148:151], v[192:195], v[112:115]
	v_mfma_f32_16x16x32_bf16 v[112:115], v[156:159], v[196:199], v[112:115]
	v_mfma_f32_16x16x32_bf16 v[48:51], v[148:151], v[200:203], v[48:51]
	v_mfma_f32_16x16x32_bf16 v[48:51], v[156:159], v[204:207], v[48:51]
	s_setprio 0
	s_setprio 1
	v_mfma_f32_16x16x32_bf16 v[100:103], v[160:163], v[176:179], v[100:103]
	v_mfma_f32_16x16x32_bf16 v[100:103], v[164:167], v[180:183], v[100:103]
	v_mfma_f32_16x16x32_bf16 v[88:91], v[160:163], v[184:187], v[88:91]
	v_mfma_f32_16x16x32_bf16 v[88:91], v[164:167], v[188:191], v[88:91]
	v_mfma_f32_16x16x32_bf16 v[72:75], v[160:163], v[192:195], v[72:75]
	v_mfma_f32_16x16x32_bf16 v[72:75], v[164:167], v[196:199], v[72:75]
	v_mfma_f32_16x16x32_bf16 v[64:67], v[160:163], v[200:203], v[64:67]
	v_mfma_f32_16x16x32_bf16 v[64:67], v[164:167], v[204:207], v[64:67]
	v_mfma_f32_16x16x32_bf16 v[60:63], v[168:171], v[176:179], v[60:63]
	v_mfma_f32_16x16x32_bf16 v[60:63], v[172:175], v[180:183], v[60:63]
	v_mfma_f32_16x16x32_bf16 v[44:47], v[168:171], v[184:187], v[44:47]
	v_mfma_f32_16x16x32_bf16 v[44:47], v[172:175], v[188:191], v[44:47]
	v_mfma_f32_16x16x32_bf16 v[32:35], v[168:171], v[192:195], v[32:35]
	v_mfma_f32_16x16x32_bf16 v[32:35], v[172:175], v[196:199], v[32:35]
	v_mfma_f32_16x16x32_bf16 v[24:27], v[168:171], v[200:203], v[24:27]
	v_mfma_f32_16x16x32_bf16 v[24:27], v[172:175], v[204:207], v[24:27]
	s_setprio 0
	s_barrier
	s_nop 1
	s_add_i32 s2, s18, s69
	v_lshl_add_u64 v[152:153], v[152:153], 0, s[72:73]
	s_mov_b32 m0, s2
	ds_read_b128 v[176:179], v155 offset:49152
	ds_read_b128 v[180:183], v155 offset:50176
	ds_read_b128 v[184:187], v155 offset:51200
	ds_read_b128 v[188:191], v155 offset:52224
	ds_read_b128 v[192:195], v155 offset:53248
	ds_read_b128 v[196:199], v155 offset:54272
	ds_read_b128 v[200:203], v155 offset:55296
	ds_read_b128 v[204:207], v155 offset:56320
	global_load_lds_dwordx4 v[152:153], off
	s_add_i32 m0, s2, 0x2000
	s_add_u32 s2, s28, 0x80080
	v_lshl_add_u64 v[152:153], v[208:209], 0, s[72:73]
	s_addc_u32 s3, s29, 0
	s_add_i32 s18, s19, s69
	global_load_lds_dwordx4 v[152:153], off
	s_mov_b32 m0, s18
	s_nop 0
	global_load_lds_dwordx4 v130, s[2:3]
	s_add_i32 m0, s18, 0x2000
	s_nop 0
	global_load_lds_dwordx4 v134, s[2:3]
	v_lshl_add_u64 v[152:153], v[210:211], 0, s[72:73]
	s_mov_b32 m0, s87
	s_nop 0
	global_load_lds_dwordx4 v[152:153], off
	v_lshl_add_u64 v[152:153], v[214:215], 0, s[72:73]
	s_mov_b32 m0, s88
	s_nop 0
	global_load_lds_dwordx4 v[152:153], off
	s_waitcnt vmcnt(8)
	s_waitcnt lgkmcnt(0)
	s_barrier
	s_setprio 1
	s_waitcnt lgkmcnt(0)
	v_mfma_f32_16x16x32_bf16 v[92:95], v[140:143], v[176:179], v[92:95]
	v_mfma_f32_16x16x32_bf16 v[92:95], v[144:147], v[180:183], v[92:95]
	v_mfma_f32_16x16x32_bf16 v[108:111], v[140:143], v[184:187], v[108:111]
	v_mfma_f32_16x16x32_bf16 v[108:111], v[144:147], v[188:191], v[108:111]
	v_mfma_f32_16x16x32_bf16 v[104:107], v[140:143], v[192:195], v[104:107]
	v_mfma_f32_16x16x32_bf16 v[104:107], v[144:147], v[196:199], v[104:107]
	v_mfma_f32_16x16x32_bf16 v[76:79], v[140:143], v[200:203], v[76:79]
	v_mfma_f32_16x16x32_bf16 v[76:79], v[144:147], v[204:207], v[76:79]
	v_mfma_f32_16x16x32_bf16 v[52:55], v[148:151], v[176:179], v[52:55]
	v_mfma_f32_16x16x32_bf16 v[52:55], v[156:159], v[180:183], v[52:55]
	v_mfma_f32_16x16x32_bf16 v[80:83], v[148:151], v[184:187], v[80:83]
	v_mfma_f32_16x16x32_bf16 v[80:83], v[156:159], v[188:191], v[80:83]
	v_mfma_f32_16x16x32_bf16 v[68:71], v[148:151], v[192:195], v[68:71]
	v_mfma_f32_16x16x32_bf16 v[68:71], v[156:159], v[196:199], v[68:71]
	v_mfma_f32_16x16x32_bf16 v[36:39], v[148:151], v[200:203], v[36:39]
	v_mfma_f32_16x16x32_bf16 v[36:39], v[156:159], v[204:207], v[36:39]
	s_setprio 0
	s_setprio 1
	v_mfma_f32_16x16x32_bf16 v[40:43], v[160:163], v[176:179], v[40:43]
	v_mfma_f32_16x16x32_bf16 v[40:43], v[164:167], v[180:183], v[40:43]
	v_mfma_f32_16x16x32_bf16 v[28:31], v[160:163], v[184:187], v[28:31]
	v_mfma_f32_16x16x32_bf16 v[28:31], v[164:167], v[188:191], v[28:31]
	v_mfma_f32_16x16x32_bf16 v[20:23], v[160:163], v[192:195], v[20:23]
	v_mfma_f32_16x16x32_bf16 v[20:23], v[164:167], v[196:199], v[20:23]
	v_mfma_f32_16x16x32_bf16 v[16:19], v[160:163], v[200:203], v[16:19]
	v_mfma_f32_16x16x32_bf16 v[16:19], v[164:167], v[204:207], v[16:19]
	v_mfma_f32_16x16x32_bf16 v[12:15], v[168:171], v[176:179], v[12:15]
	v_mfma_f32_16x16x32_bf16 v[12:15], v[172:175], v[180:183], v[12:15]
	v_mfma_f32_16x16x32_bf16 v[8:11], v[168:171], v[184:187], v[8:11]
	v_mfma_f32_16x16x32_bf16 v[8:11], v[172:175], v[188:191], v[8:11]
	v_mfma_f32_16x16x32_bf16 v[4:7], v[168:171], v[192:195], v[4:7]
	v_mfma_f32_16x16x32_bf16 v[4:7], v[172:175], v[196:199], v[4:7]
	v_mfma_f32_16x16x32_bf16 v[0:3], v[168:171], v[200:203], v[0:3]
	v_mfma_f32_16x16x32_bf16 v[0:3], v[172:175], v[204:207], v[0:3]
	s_setprio 0
	s_barrier
	s_nop 1
	s_add_i32 s2, s5, 2
	s_add_u32 s15, s15, 0x100
	s_addc_u32 s75, s75, 0
	s_cmp_gt_u32 s5, 29
	s_mov_b64 s[18:19], s[26:27]
	s_mov_b32 s5, s2
	s_cbranch_scc1 .LBB0_384
	s_branch .LBB0_371

.LBB0_370:
	s_add_u32 s26, s18, 0x100
	s_addc_u32 s27, s19, 0
	s_cmp_eq_u32 s5, 30
	s_cselect_b32 s31, s40, s27
	s_cselect_b32 s30, s41, s26
	s_cselect_b32 s29, s57, s75
	s_cselect_b32 s28, s4, s15
	s_add_i32 s2, 0, 0x10000
	v_add_u32_e32 v152, s2, v154
	s_add_i32 vcc_lo, 0, 0x14000
	ds_read_b128 v[140:143], v152
	ds_read_b128 v[144:147], v152 offset:1024
	ds_read_b128 v[148:151], v152 offset:2048
	ds_read_b128 v[156:159], v152 offset:3072
	v_add_u32_e32 v152, vcc_lo, v154
	ds_read_b128 v[160:163], v152
	ds_read_b128 v[164:167], v152 offset:1024
	ds_read_b128 v[168:171], v152 offset:2048
	ds_read_b128 v[172:175], v152 offset:3072
	v_lshl_add_u64 v[152:153], s[18:19], 0, v[136:137]
	s_add_i32 m0, s63, 0xc000
	ds_read_b128 v[176:179], v155
	ds_read_b128 v[180:183], v155 offset:1024
	ds_read_b128 v[184:187], v155 offset:2048
	ds_read_b128 v[188:191], v155 offset:3072
	ds_read_b128 v[192:195], v155 offset:4096
	ds_read_b128 v[196:199], v155 offset:5120
	ds_read_b128 v[200:203], v155 offset:6144
	ds_read_b128 v[204:207], v155 offset:7168
	global_load_lds_dwordx4 v[152:153], off
	v_lshl_add_u64 v[152:153], s[18:19], 0, v[138:139]
	s_add_i32 m0, s63, 0xe000
	s_nop 0
	global_load_lds_dwordx4 v[152:153], off
	s_waitcnt vmcnt(8)
	s_waitcnt lgkmcnt(0)
	s_barrier
	s_setprio 1
	s_waitcnt lgkmcnt(0)
	v_mfma_f32_16x16x32_bf16 v[96:99], v[140:143], v[176:179], v[96:99]
	v_mfma_f32_16x16x32_bf16 v[96:99], v[144:147], v[180:183], v[96:99]
	v_mfma_f32_16x16x32_bf16 v[124:127], v[140:143], v[184:187], v[124:127]
	v_mfma_f32_16x16x32_bf16 v[124:127], v[144:147], v[188:191], v[124:127]
	v_mfma_f32_16x16x32_bf16 v[120:123], v[140:143], v[192:195], v[120:123]
	v_mfma_f32_16x16x32_bf16 v[120:123], v[144:147], v[196:199], v[120:123]
	v_mfma_f32_16x16x32_bf16 v[84:87], v[140:143], v[200:203], v[84:87]
	v_mfma_f32_16x16x32_bf16 v[84:87], v[144:147], v[204:207], v[84:87]
	v_mfma_f32_16x16x32_bf16 v[56:59], v[148:151], v[176:179], v[56:59]
	v_mfma_f32_16x16x32_bf16 v[56:59], v[156:159], v[180:183], v[56:59]
	v_mfma_f32_16x16x32_bf16 v[116:119], v[148:151], v[184:187], v[116:119]
	v_mfma_f32_16x16x32_bf16 v[116:119], v[156:159], v[188:191], v[116:119]
	v_mfma_f32_16x16x32_bf16 v[112:115], v[148:151], v[192:195], v[112:115]
	v_mfma_f32_16x16x32_bf16 v[112:115], v[156:159], v[196:199], v[112:115]
	v_mfma_f32_16x16x32_bf16 v[48:51], v[148:151], v[200:203], v[48:51]
	v_mfma_f32_16x16x32_bf16 v[48:51], v[156:159], v[204:207], v[48:51]
	s_setprio 0
	s_setprio 1
	v_mfma_f32_16x16x32_bf16 v[100:103], v[160:163], v[176:179], v[100:103]
	v_mfma_f32_16x16x32_bf16 v[100:103], v[164:167], v[180:183], v[100:103]
	v_mfma_f32_16x16x32_bf16 v[88:91], v[160:163], v[184:187], v[88:91]
	v_mfma_f32_16x16x32_bf16 v[88:91], v[164:167], v[188:191], v[88:91]
	v_mfma_f32_16x16x32_bf16 v[72:75], v[160:163], v[192:195], v[72:75]
	v_mfma_f32_16x16x32_bf16 v[72:75], v[164:167], v[196:199], v[72:75]
	v_mfma_f32_16x16x32_bf16 v[64:67], v[160:163], v[200:203], v[64:67]
	v_mfma_f32_16x16x32_bf16 v[64:67], v[164:167], v[204:207], v[64:67]
	v_mfma_f32_16x16x32_bf16 v[60:63], v[168:171], v[176:179], v[60:63]
	v_mfma_f32_16x16x32_bf16 v[60:63], v[172:175], v[180:183], v[60:63]
	v_mfma_f32_16x16x32_bf16 v[44:47], v[168:171], v[184:187], v[44:47]
	v_mfma_f32_16x16x32_bf16 v[44:47], v[172:175], v[188:191], v[44:47]
	v_mfma_f32_16x16x32_bf16 v[32:35], v[168:171], v[192:195], v[32:35]
	v_mfma_f32_16x16x32_bf16 v[32:35], v[172:175], v[196:199], v[32:35]
	v_mfma_f32_16x16x32_bf16 v[24:27], v[168:171], v[200:203], v[24:27]
	v_mfma_f32_16x16x32_bf16 v[24:27], v[172:175], v[204:207], v[24:27]
	s_setprio 0
	s_barrier
	s_nop 1
	s_add_i32 s2, s2, s69
	v_lshl_add_u64 v[152:153], s[28:29], 0, v[130:131]
	s_mov_b32 m0, s2
	ds_read_b128 v[176:179], v155 offset:16384
	ds_read_b128 v[180:183], v155 offset:17408
	ds_read_b128 v[184:187], v155 offset:18432
	ds_read_b128 v[188:191], v155 offset:19456
	ds_read_b128 v[192:195], v155 offset:20480
	ds_read_b128 v[196:199], v155 offset:21504
	ds_read_b128 v[200:203], v155 offset:22528
	ds_read_b128 v[204:207], v155 offset:23552
	global_load_lds_dwordx4 v[152:153], off
	s_add_i32 m0, s2, 0x2000
	s_add_u32 s2, s28, 0x80000
	v_lshl_add_u64 v[208:209], s[28:29], 0, v[134:135]
	s_addc_u32 s3, s29, 0
	s_add_i32 s18, vcc_lo, s69
	global_load_lds_dwordx4 v[208:209], off
	s_mov_b32 m0, s18
	v_lshl_add_u64 v[214:215], s[30:31], 0, v[132:133]
	global_load_lds_dwordx4 v130, s[2:3]
	s_add_i32 m0, s18, 0x2000
	s_nop 0
	global_load_lds_dwordx4 v134, s[2:3]
	v_lshl_add_u64 v[210:211], s[30:31], 0, v[128:129]
	s_mov_b32 m0, s63
	s_nop 0
	global_load_lds_dwordx4 v[210:211], off
	s_mov_b32 m0, s70
	s_nop 0
	global_load_lds_dwordx4 v[214:215], off
	s_waitcnt vmcnt(8)
	s_waitcnt lgkmcnt(0)
	s_barrier
	s_setprio 1
	s_waitcnt lgkmcnt(0)
	v_mfma_f32_16x16x32_bf16 v[92:95], v[140:143], v[176:179], v[92:95]
	v_mfma_f32_16x16x32_bf16 v[92:95], v[144:147], v[180:183], v[92:95]
	v_mfma_f32_16x16x32_bf16 v[108:111], v[140:143], v[184:187], v[108:111]
	v_mfma_f32_16x16x32_bf16 v[108:111], v[144:147], v[188:191], v[108:111]
	v_mfma_f32_16x16x32_bf16 v[104:107], v[140:143], v[192:195], v[104:107]
	v_mfma_f32_16x16x32_bf16 v[104:107], v[144:147], v[196:199], v[104:107]
	v_mfma_f32_16x16x32_bf16 v[76:79], v[140:143], v[200:203], v[76:79]
	v_mfma_f32_16x16x32_bf16 v[76:79], v[144:147], v[204:207], v[76:79]
	v_mfma_f32_16x16x32_bf16 v[52:55], v[148:151], v[176:179], v[52:55]
	v_mfma_f32_16x16x32_bf16 v[52:55], v[156:159], v[180:183], v[52:55]
	v_mfma_f32_16x16x32_bf16 v[80:83], v[148:151], v[184:187], v[80:83]
	v_mfma_f32_16x16x32_bf16 v[80:83], v[156:159], v[188:191], v[80:83]
	v_mfma_f32_16x16x32_bf16 v[68:71], v[148:151], v[192:195], v[68:71]
	v_mfma_f32_16x16x32_bf16 v[68:71], v[156:159], v[196:199], v[68:71]
	v_mfma_f32_16x16x32_bf16 v[36:39], v[148:151], v[200:203], v[36:39]
	v_mfma_f32_16x16x32_bf16 v[36:39], v[156:159], v[204:207], v[36:39]
	s_setprio 0
	s_setprio 1
	v_mfma_f32_16x16x32_bf16 v[40:43], v[160:163], v[176:179], v[40:43]
	v_mfma_f32_16x16x32_bf16 v[40:43], v[164:167], v[180:183], v[40:43]
	v_mfma_f32_16x16x32_bf16 v[28:31], v[160:163], v[184:187], v[28:31]
	v_mfma_f32_16x16x32_bf16 v[28:31], v[164:167], v[188:191], v[28:31]
	v_mfma_f32_16x16x32_bf16 v[20:23], v[160:163], v[192:195], v[20:23]
	v_mfma_f32_16x16x32_bf16 v[20:23], v[164:167], v[196:199], v[20:23]
	v_mfma_f32_16x16x32_bf16 v[16:19], v[160:163], v[200:203], v[16:19]
	v_mfma_f32_16x16x32_bf16 v[16:19], v[164:167], v[204:207], v[16:19]
	v_mfma_f32_16x16x32_bf16 v[12:15], v[168:171], v[176:179], v[12:15]
	v_mfma_f32_16x16x32_bf16 v[12:15], v[172:175], v[180:183], v[12:15]
	v_mfma_f32_16x16x32_bf16 v[8:11], v[168:171], v[184:187], v[8:11]
	v_mfma_f32_16x16x32_bf16 v[8:11], v[172:175], v[188:191], v[8:11]
	v_mfma_f32_16x16x32_bf16 v[4:7], v[168:171], v[192:195], v[4:7]
	v_mfma_f32_16x16x32_bf16 v[4:7], v[172:175], v[196:199], v[4:7]
	v_mfma_f32_16x16x32_bf16 v[0:3], v[168:171], v[200:203], v[0:3]
	v_mfma_f32_16x16x32_bf16 v[0:3], v[172:175], v[204:207], v[0:3]
	s_setprio 0
	s_barrier
	s_nop 1
	s_add_i32 s18, 0, 0x18000
	s_add_i32 s19, 0, 0x1c000
	v_add_u32_e32 v156, s18, v154
	v_add_u32_e32 v172, s19, v154
	ds_read_b128 v[140:143], v156
	ds_read_b128 v[144:147], v156 offset:1024
	ds_read_b128 v[148:151], v156 offset:2048
	ds_read_b128 v[156:159], v156 offset:3072
	ds_read_b128 v[160:163], v172
	ds_read_b128 v[164:167], v172 offset:1024
	ds_read_b128 v[168:171], v172 offset:2048
	ds_read_b128 v[172:175], v172 offset:3072
	s_add_u32 s2, s30, 0x80000
	s_addc_u32 s3, s31, 0
	s_mov_b32 m0, s71
	ds_read_b128 v[176:179], v155 offset:32768
	ds_read_b128 v[180:183], v155 offset:33792
	ds_read_b128 v[184:187], v155 offset:34816
	ds_read_b128 v[188:191], v155 offset:35840
	ds_read_b128 v[192:195], v155 offset:36864
	ds_read_b128 v[196:199], v155 offset:37888
	ds_read_b128 v[200:203], v155 offset:38912
	ds_read_b128 v[204:207], v155 offset:39936
	global_load_lds_dwordx4 v128, s[2:3]
	v_lshl_add_u64 v[216:217], s[2:3], 0, v[132:133]
	s_mov_b32 m0, s76
	s_nop 0
	global_load_lds_dwordx4 v[216:217], off
	s_waitcnt vmcnt(8)
	s_waitcnt lgkmcnt(0)
	s_barrier
	s_setprio 1
	s_waitcnt lgkmcnt(0)
	v_mfma_f32_16x16x32_bf16 v[96:99], v[140:143], v[176:179], v[96:99]
	v_mfma_f32_16x16x32_bf16 v[96:99], v[144:147], v[180:183], v[96:99]
	v_mfma_f32_16x16x32_bf16 v[124:127], v[140:143], v[184:187], v[124:127]
	v_mfma_f32_16x16x32_bf16 v[124:127], v[144:147], v[188:191], v[124:127]
	v_mfma_f32_16x16x32_bf16 v[120:123], v[140:143], v[192:195], v[120:123]
	v_mfma_f32_16x16x32_bf16 v[120:123], v[144:147], v[196:199], v[120:123]
	v_mfma_f32_16x16x32_bf16 v[84:87], v[140:143], v[200:203], v[84:87]
	v_mfma_f32_16x16x32_bf16 v[84:87], v[144:147], v[204:207], v[84:87]
	v_mfma_f32_16x16x32_bf16 v[56:59], v[148:151], v[176:179], v[56:59]
	v_mfma_f32_16x16x32_bf16 v[56:59], v[156:159], v[180:183], v[56:59]
	v_mfma_f32_16x16x32_bf16 v[116:119], v[148:151], v[184:187], v[116:119]
	v_mfma_f32_16x16x32_bf16 v[116:119], v[156:159], v[188:191], v[116:119]
	v_mfma_f32_16x16x32_bf16 v[112:115], v[148:151], v[192:195], v[112:115]
	v_mfma_f32_16x16x32_bf16 v[112:115], v[156:159], v[196:199], v[112:115]
	v_mfma_f32_16x16x32_bf16 v[48:51], v[148:151], v[200:203], v[48:51]
	v_mfma_f32_16x16x32_bf16 v[48:51], v[156:159], v[204:207], v[48:51]
	s_setprio 0
	s_setprio 1
	v_mfma_f32_16x16x32_bf16 v[100:103], v[160:163], v[176:179], v[100:103]
	v_mfma_f32_16x16x32_bf16 v[100:103], v[164:167], v[180:183], v[100:103]
	v_mfma_f32_16x16x32_bf16 v[88:91], v[160:163], v[184:187], v[88:91]
	v_mfma_f32_16x16x32_bf16 v[88:91], v[164:167], v[188:191], v[88:91]
	v_mfma_f32_16x16x32_bf16 v[72:75], v[160:163], v[192:195], v[72:75]
	v_mfma_f32_16x16x32_bf16 v[72:75], v[164:167], v[196:199], v[72:75]
	v_mfma_f32_16x16x32_bf16 v[64:67], v[160:163], v[200:203], v[64:67]
	v_mfma_f32_16x16x32_bf16 v[64:67], v[164:167], v[204:207], v[64:67]
	v_mfma_f32_16x16x32_bf16 v[60:63], v[168:171], v[176:179], v[60:63]
	v_mfma_f32_16x16x32_bf16 v[60:63], v[172:175], v[180:183], v[60:63]
	v_mfma_f32_16x16x32_bf16 v[44:47], v[168:171], v[184:187], v[44:47]
	v_mfma_f32_16x16x32_bf16 v[44:47], v[172:175], v[188:191], v[44:47]
	v_mfma_f32_16x16x32_bf16 v[32:35], v[168:171], v[192:195], v[32:35]
	v_mfma_f32_16x16x32_bf16 v[32:35], v[172:175], v[196:199], v[32:35]
	v_mfma_f32_16x16x32_bf16 v[24:27], v[168:171], v[200:203], v[24:27]
	v_mfma_f32_16x16x32_bf16 v[24:27], v[172:175], v[204:207], v[24:27]
	s_setprio 0
	s_barrier
	s_nop 1
	s_add_i32 s2, s18, s69
	v_lshl_add_u64 v[152:153], v[152:153], 0, s[72:73]
	s_mov_b32 m0, s2
	ds_read_b128 v[176:179], v155 offset:49152
	ds_read_b128 v[180:183], v155 offset:50176
	ds_read_b128 v[184:187], v155 offset:51200
	ds_read_b128 v[188:191], v155 offset:52224
	ds_read_b128 v[192:195], v155 offset:53248
	ds_read_b128 v[196:199], v155 offset:54272
	ds_read_b128 v[200:203], v155 offset:55296
	ds_read_b128 v[204:207], v155 offset:56320
	global_load_lds_dwordx4 v[152:153], off
	s_add_i32 m0, s2, 0x2000
	s_add_u32 s2, s28, 0x80080
	v_lshl_add_u64 v[152:153], v[208:209], 0, s[72:73]
	s_addc_u32 s3, s29, 0
	s_add_i32 s18, s19, s69
	global_load_lds_dwordx4 v[152:153], off
	s_mov_b32 m0, s18
	s_nop 0
	global_load_lds_dwordx4 v130, s[2:3]
	s_add_i32 m0, s18, 0x2000
	s_nop 0
	global_load_lds_dwordx4 v134, s[2:3]
	v_lshl_add_u64 v[152:153], v[210:211], 0, s[72:73]
	s_mov_b32 m0, s87
	s_nop 0
	global_load_lds_dwordx4 v[152:153], off
	v_lshl_add_u64 v[152:153], v[214:215], 0, s[72:73]
	s_mov_b32 m0, s88
	s_nop 0
	global_load_lds_dwordx4 v[152:153], off
	s_waitcnt vmcnt(8)
	s_waitcnt lgkmcnt(0)
	s_barrier
	s_setprio 1
	s_waitcnt lgkmcnt(0)
	v_mfma_f32_16x16x32_bf16 v[92:95], v[140:143], v[176:179], v[92:95]
	v_mfma_f32_16x16x32_bf16 v[92:95], v[144:147], v[180:183], v[92:95]
	v_mfma_f32_16x16x32_bf16 v[108:111], v[140:143], v[184:187], v[108:111]
	v_mfma_f32_16x16x32_bf16 v[108:111], v[144:147], v[188:191], v[108:111]
	v_mfma_f32_16x16x32_bf16 v[104:107], v[140:143], v[192:195], v[104:107]
	v_mfma_f32_16x16x32_bf16 v[104:107], v[144:147], v[196:199], v[104:107]
	v_mfma_f32_16x16x32_bf16 v[76:79], v[140:143], v[200:203], v[76:79]
	v_mfma_f32_16x16x32_bf16 v[76:79], v[144:147], v[204:207], v[76:79]
	v_mfma_f32_16x16x32_bf16 v[52:55], v[148:151], v[176:179], v[52:55]
	v_mfma_f32_16x16x32_bf16 v[52:55], v[156:159], v[180:183], v[52:55]
	v_mfma_f32_16x16x32_bf16 v[80:83], v[148:151], v[184:187], v[80:83]
	v_mfma_f32_16x16x32_bf16 v[80:83], v[156:159], v[188:191], v[80:83]
	v_mfma_f32_16x16x32_bf16 v[68:71], v[148:151], v[192:195], v[68:71]
	v_mfma_f32_16x16x32_bf16 v[68:71], v[156:159], v[196:199], v[68:71]
	v_mfma_f32_16x16x32_bf16 v[36:39], v[148:151], v[200:203], v[36:39]
	v_mfma_f32_16x16x32_bf16 v[36:39], v[156:159], v[204:207], v[36:39]
	s_setprio 0
	s_setprio 1
	v_mfma_f32_16x16x32_bf16 v[40:43], v[160:163], v[176:179], v[40:43]
	v_mfma_f32_16x16x32_bf16 v[40:43], v[164:167], v[180:183], v[40:43]
	v_mfma_f32_16x16x32_bf16 v[28:31], v[160:163], v[184:187], v[28:31]
	v_mfma_f32_16x16x32_bf16 v[28:31], v[164:167], v[188:191], v[28:31]
	v_mfma_f32_16x16x32_bf16 v[20:23], v[160:163], v[192:195], v[20:23]
	v_mfma_f32_16x16x32_bf16 v[20:23], v[164:167], v[196:199], v[20:23]
	v_mfma_f32_16x16x32_bf16 v[16:19], v[160:163], v[200:203], v[16:19]
	v_mfma_f32_16x16x32_bf16 v[16:19], v[164:167], v[204:207], v[16:19]
	v_mfma_f32_16x16x32_bf16 v[12:15], v[168:171], v[176:179], v[12:15]
	v_mfma_f32_16x16x32_bf16 v[12:15], v[172:175], v[180:183], v[12:15]
	v_mfma_f32_16x16x32_bf16 v[8:11], v[168:171], v[184:187], v[8:11]
	v_mfma_f32_16x16x32_bf16 v[8:11], v[172:175], v[188:191], v[8:11]
	v_mfma_f32_16x16x32_bf16 v[4:7], v[168:171], v[192:195], v[4:7]
	v_mfma_f32_16x16x32_bf16 v[4:7], v[172:175], v[196:199], v[4:7]
	v_mfma_f32_16x16x32_bf16 v[0:3], v[168:171], v[200:203], v[0:3]
	v_mfma_f32_16x16x32_bf16 v[0:3], v[172:175], v[204:207], v[0:3]
	s_setprio 0
	s_barrier
	s_nop 1
	s_add_i32 s2, s5, 2
	s_add_u32 s15, s15, 0x100
	s_addc_u32 s75, s75, 0
	s_cmp_gt_u32 s5, 29
	s_mov_b64 s[18:19], s[26:27]
	s_mov_b32 s5, s2
	s_cbranch_scc1 .LBB0_384

.LBB0_658:
	s_ashr_i32 s75, s74, 31
	s_add_i32 s45, s21, -2
	s_lshl_b64 s[2:3], s[74:75], 20
	s_add_u32 s9, s33, s2
	s_addc_u32 s12, s65, s3
	s_and_b64 s[2:3], s[38:39], exec
	s_cselect_b32 s17, s12, s11
	s_cselect_b32 s16, s9, s10
	s_ashr_i32 s9, s8, 31
	s_lshl_b64 s[2:3], s[8:9], 20
	s_add_u32 s9, s67, s2
	s_addc_u32 s12, s68, s3
	s_and_b64 s[2:3], s[38:39], exec
	s_cselect_b32 s18, s12, s35
	s_cselect_b32 s9, s9, s34
	s_ashr_i32 s41, s40, 31
	s_lshl_b64 s[2:3], s[40:41], 7
	s_and_b64 s[12:13], s[38:39], exec
	s_cselect_b32 s2, s2, 0
	s_cselect_b32 s3, s3, 0
	s_add_u32 s16, s16, s2
	s_addc_u32 s17, s17, s3
	s_add_u32 s12, s9, s2
	s_mul_hi_i32 s2, s42, 0x78787879
	s_addc_u32 s13, s18, s3
	s_lshr_b32 s3, s2, 31
	s_ashr_i32 s2, s2, 3
	s_add_i32 s20, s2, s3
	s_mul_i32 s2, s20, 17
	s_lshl_b32 s18, s44, 8
	s_sub_i32 s2, s42, s2
	s_ashr_i32 s19, s18, 31
	s_cmp_lg_u32 s2, 0
	s_cselect_b32 s2, s20, 8
	s_ashr_i32 s3, s2, 31
	s_lshl_b64 s[22:23], s[2:3], 13
	s_cmp_lg_u32 s21, 32
	s_cselect_b64 s[24:25], -1, 0
	s_cmp_eq_u32 s21, 32
	s_mul_hi_i32 s9, s2, 0xc000
	s_mul_i32 s30, s2, 0xc000
	s_cselect_b64 s[2:3], -1, 0
	s_and_b64 s[26:27], s[58:59], s[2:3]
	s_add_u32 s2, s77, s22
	s_addc_u32 s3, s78, s23
	s_lshl_b64 s[22:23], s[18:19], 2
	s_add_u32 s28, s2, s22
	s_addc_u32 s29, s3, s23
	s_add_u32 s2, s71, s30
	s_addc_u32 s3, s76, s9
	s_add_u32 s30, s2, s22
	s_addc_u32 s31, s3, s23
	s_add_u32 s9, s34, 0x100
	s_addc_u32 s19, s35, 0
	s_add_u32 s2, s10, 0x80080
	s_addc_u32 s3, s11, 0
	s_mov_b32 s41, 0
	v_lshl_add_u64 v[96:97], s[2:3], 0, v[210:211]
	v_lshl_add_u64 v[98:99], s[2:3], 0, v[218:219]
	s_mov_b64 s[34:35], 0
	s_add_i32 s2, s41, 2
	s_add_u32 s3, s10, s34
	s_addc_u32 s50, s11, s35
	s_add_u32 s3, s3, 0x100
	s_addc_u32 s50, s50, 0
	s_add_u32 s51, s9, s34
	s_addc_u32 s75, s19, s35
	s_cmp_eq_u32 s45, s41
	s_cselect_b32 s89, s17, s50
	s_cselect_b32 s88, s16, s3
	s_cselect_b32 vcc_hi, s13, s75
	s_cselect_b32 vcc_lo, s12, s51
	s_add_i32 s3, 0, 0x10000
	s_add_i32 s41, 0, 0x14000
	v_add_u32_e32 v136, s3, v220
	v_add_u32_e32 v160, s41, v220
	ds_read_b128 v[108:111], v136
	ds_read_b128 v[120:123], v136 offset:1024
	ds_read_b128 v[132:135], v136 offset:2048
	ds_read_b128 v[136:139], v136 offset:3072
	ds_read_b128 v[140:143], v160
	ds_read_b128 v[144:147], v160 offset:1024
	ds_read_b128 v[148:151], v160 offset:2048
	ds_read_b128 v[160:163], v160 offset:3072
	v_lshl_add_u64 v[196:197], v[96:97], 0, s[34:35]
	s_add_i32 m0, s15, 0xc000
	ds_read_b128 v[164:167], v223
	ds_read_b128 v[168:171], v223 offset:1024
	ds_read_b128 v[172:175], v223 offset:2048
	ds_read_b128 v[176:179], v223 offset:3072
	ds_read_b128 v[180:183], v223 offset:4096
	ds_read_b128 v[184:187], v223 offset:5120
	ds_read_b128 v[188:191], v223 offset:6144
	ds_read_b128 v[192:195], v223 offset:7168
	global_load_lds_dwordx4 v[196:197], off
	v_lshl_add_u64 v[196:197], v[98:99], 0, s[34:35]
	s_add_i32 m0, s15, 0xe000
	s_nop 0
	global_load_lds_dwordx4 v[196:197], off
	s_waitcnt vmcnt(8)
	s_waitcnt lgkmcnt(0)
	s_barrier
	s_setprio 1
	s_waitcnt lgkmcnt(0)
	v_mfma_f32_16x16x32_bf16 v[156:159], v[108:111], v[164:167], 0
	v_mfma_f32_16x16x32_bf16 v[156:159], v[120:123], v[168:171], v[156:159]
	v_mfma_f32_16x16x32_bf16 v[128:131], v[108:111], v[172:175], 0
	v_mfma_f32_16x16x32_bf16 v[128:131], v[120:123], v[176:179], v[128:131]
	v_mfma_f32_16x16x32_bf16 v[116:119], v[108:111], v[180:183], 0
	v_mfma_f32_16x16x32_bf16 v[116:119], v[120:123], v[184:187], v[116:119]
	v_mfma_f32_16x16x32_bf16 v[104:107], v[108:111], v[188:191], 0
	v_mfma_f32_16x16x32_bf16 v[104:107], v[120:123], v[192:195], v[104:107]
	v_mfma_f32_16x16x32_bf16 v[152:155], v[132:135], v[164:167], 0
	v_mfma_f32_16x16x32_bf16 v[152:155], v[136:139], v[168:171], v[152:155]
	v_mfma_f32_16x16x32_bf16 v[124:127], v[132:135], v[172:175], 0
	v_mfma_f32_16x16x32_bf16 v[124:127], v[136:139], v[176:179], v[124:127]
	v_mfma_f32_16x16x32_bf16 v[112:115], v[132:135], v[180:183], 0
	v_mfma_f32_16x16x32_bf16 v[112:115], v[136:139], v[184:187], v[112:115]
	v_mfma_f32_16x16x32_bf16 v[100:103], v[132:135], v[188:191], 0
	v_mfma_f32_16x16x32_bf16 v[100:103], v[136:139], v[192:195], v[100:103]
	s_setprio 0
	s_setprio 1
	v_mfma_f32_16x16x32_bf16 v[92:95], v[140:143], v[164:167], 0
	v_mfma_f32_16x16x32_bf16 v[92:95], v[144:147], v[168:171], v[92:95]
	v_mfma_f32_16x16x32_bf16 v[84:87], v[140:143], v[172:175], 0
	v_mfma_f32_16x16x32_bf16 v[84:87], v[144:147], v[176:179], v[84:87]
	v_mfma_f32_16x16x32_bf16 v[76:79], v[140:143], v[180:183], 0
	v_mfma_f32_16x16x32_bf16 v[76:79], v[144:147], v[184:187], v[76:79]
	v_mfma_f32_16x16x32_bf16 v[68:71], v[140:143], v[188:191], 0
	v_mfma_f32_16x16x32_bf16 v[68:71], v[144:147], v[192:195], v[68:71]
	v_mfma_f32_16x16x32_bf16 v[88:91], v[148:151], v[164:167], 0
	v_mfma_f32_16x16x32_bf16 v[88:91], v[160:163], v[168:171], v[88:91]
	v_mfma_f32_16x16x32_bf16 v[80:83], v[148:151], v[172:175], 0
	v_mfma_f32_16x16x32_bf16 v[80:83], v[160:163], v[176:179], v[80:83]
	v_mfma_f32_16x16x32_bf16 v[72:75], v[148:151], v[180:183], 0
	v_mfma_f32_16x16x32_bf16 v[72:75], v[160:163], v[184:187], v[72:75]
	v_mfma_f32_16x16x32_bf16 v[64:67], v[148:151], v[188:191], 0
	v_mfma_f32_16x16x32_bf16 v[64:67], v[160:163], v[192:195], v[64:67]
	s_setprio 0
	s_barrier
	s_nop 1
	s_add_i32 s3, s3, s64
	v_lshl_add_u64 v[196:197], vcc, 0, v[212:213]
	s_mov_b32 m0, s3
	ds_read_b128 v[164:167], v223 offset:16384
	ds_read_b128 v[168:171], v223 offset:17408
	ds_read_b128 v[172:175], v223 offset:18432
	ds_read_b128 v[176:179], v223 offset:19456
	ds_read_b128 v[180:183], v223 offset:20480
	ds_read_b128 v[184:187], v223 offset:21504
	ds_read_b128 v[188:191], v223 offset:22528
	ds_read_b128 v[192:195], v223 offset:23552
	global_load_lds_dwordx4 v[196:197], off
	s_add_i32 m0, s3, 0x2000
	s_add_u32 s50, vcc_lo, 0x80000
	v_lshl_add_u64 v[198:199], vcc, 0, v[208:209]
	s_addc_u32 s51, vcc_hi, 0
	s_add_i32 s3, s41, s64
	global_load_lds_dwordx4 v[198:199], off
	s_mov_b32 m0, s3
	v_lshl_add_u64 v[202:203], s[88:89], 0, v[206:207]
	global_load_lds_dwordx4 v212, s[50:51]
	s_add_i32 m0, s3, 0x2000
	s_nop 0
	global_load_lds_dwordx4 v208, s[50:51]
	v_lshl_add_u64 v[200:201], s[88:89], 0, v[204:205]
	s_mov_b32 m0, s15
	s_nop 0
	global_load_lds_dwordx4 v[200:201], off
	s_mov_b32 m0, s43
	s_nop 0
	global_load_lds_dwordx4 v[202:203], off
	s_waitcnt vmcnt(8)
	s_waitcnt lgkmcnt(0)
	s_barrier
	s_setprio 1
	s_waitcnt lgkmcnt(0)
	v_mfma_f32_16x16x32_bf16 v[60:63], v[108:111], v[164:167], 0
	v_mfma_f32_16x16x32_bf16 v[60:63], v[120:123], v[168:171], v[60:63]
	v_mfma_f32_16x16x32_bf16 v[52:55], v[108:111], v[172:175], 0
	v_mfma_f32_16x16x32_bf16 v[52:55], v[120:123], v[176:179], v[52:55]
	v_mfma_f32_16x16x32_bf16 v[44:47], v[108:111], v[180:183], 0
	v_mfma_f32_16x16x32_bf16 v[44:47], v[120:123], v[184:187], v[44:47]
	v_mfma_f32_16x16x32_bf16 v[36:39], v[108:111], v[188:191], 0
	v_mfma_f32_16x16x32_bf16 v[36:39], v[120:123], v[192:195], v[36:39]
	v_mfma_f32_16x16x32_bf16 v[56:59], v[132:135], v[164:167], 0
	v_mfma_f32_16x16x32_bf16 v[56:59], v[136:139], v[168:171], v[56:59]
	v_mfma_f32_16x16x32_bf16 v[48:51], v[132:135], v[172:175], 0
	v_mfma_f32_16x16x32_bf16 v[48:51], v[136:139], v[176:179], v[48:51]
	v_mfma_f32_16x16x32_bf16 v[40:43], v[132:135], v[180:183], 0
	v_mfma_f32_16x16x32_bf16 v[40:43], v[136:139], v[184:187], v[40:43]
	v_mfma_f32_16x16x32_bf16 v[32:35], v[132:135], v[188:191], 0
	v_mfma_f32_16x16x32_bf16 v[32:35], v[136:139], v[192:195], v[32:35]
	s_setprio 0
	s_setprio 1
	v_mfma_f32_16x16x32_bf16 v[28:31], v[140:143], v[164:167], 0
	v_mfma_f32_16x16x32_bf16 v[28:31], v[144:147], v[168:171], v[28:31]
	v_mfma_f32_16x16x32_bf16 v[20:23], v[140:143], v[172:175], 0
	v_mfma_f32_16x16x32_bf16 v[20:23], v[144:147], v[176:179], v[20:23]
	v_mfma_f32_16x16x32_bf16 v[12:15], v[140:143], v[180:183], 0
	v_mfma_f32_16x16x32_bf16 v[12:15], v[144:147], v[184:187], v[12:15]
	v_mfma_f32_16x16x32_bf16 v[4:7], v[140:143], v[188:191], 0
	v_mfma_f32_16x16x32_bf16 v[4:7], v[144:147], v[192:195], v[4:7]
	v_mfma_f32_16x16x32_bf16 v[24:27], v[148:151], v[164:167], 0
	v_mfma_f32_16x16x32_bf16 v[24:27], v[160:163], v[168:171], v[24:27]
	v_mfma_f32_16x16x32_bf16 v[16:19], v[148:151], v[172:175], 0
	v_mfma_f32_16x16x32_bf16 v[16:19], v[160:163], v[176:179], v[16:19]
	v_mfma_f32_16x16x32_bf16 v[8:11], v[148:151], v[180:183], 0
	v_mfma_f32_16x16x32_bf16 v[8:11], v[160:163], v[184:187], v[8:11]
	v_mfma_f32_16x16x32_bf16 v[0:3], v[148:151], v[188:191], 0
	v_mfma_f32_16x16x32_bf16 v[0:3], v[160:163], v[192:195], v[0:3]
	s_setprio 0
	s_barrier
	s_nop 1
	s_add_i32 s3, 0, 0x18000
	s_add_i32 s41, 0, 0x1c000
	v_add_u32_e32 v136, s3, v220
	v_add_u32_e32 v160, s41, v220
	ds_read_b128 v[108:111], v136
	ds_read_b128 v[120:123], v136 offset:1024
	ds_read_b128 v[132:135], v136 offset:2048
	ds_read_b128 v[136:139], v136 offset:3072
	ds_read_b128 v[140:143], v160
	ds_read_b128 v[144:147], v160 offset:1024
	ds_read_b128 v[148:151], v160 offset:2048
	ds_read_b128 v[160:163], v160 offset:3072
	s_add_u32 s50, s88, 0x80000
	s_addc_u32 s51, s89, 0
	s_mov_b32 m0, s69
	ds_read_b128 v[164:167], v223 offset:32768
	ds_read_b128 v[168:171], v223 offset:33792
	ds_read_b128 v[172:175], v223 offset:34816
	ds_read_b128 v[176:179], v223 offset:35840
	ds_read_b128 v[180:183], v223 offset:36864
	ds_read_b128 v[184:187], v223 offset:37888
	ds_read_b128 v[188:191], v223 offset:38912
	ds_read_b128 v[192:195], v223 offset:39936
	global_load_lds_dwordx4 v204, s[50:51]
	v_lshl_add_u64 v[214:215], s[50:51], 0, v[206:207]
	s_mov_b32 m0, s70
	s_nop 0
	global_load_lds_dwordx4 v[214:215], off
	s_waitcnt vmcnt(8)
	s_waitcnt lgkmcnt(0)
	s_barrier
	s_setprio 1
	s_waitcnt lgkmcnt(0)
	v_mfma_f32_16x16x32_bf16 v[156:159], v[108:111], v[164:167], v[156:159]
	v_mfma_f32_16x16x32_bf16 v[156:159], v[120:123], v[168:171], v[156:159]
	v_mfma_f32_16x16x32_bf16 v[128:131], v[108:111], v[172:175], v[128:131]
	v_mfma_f32_16x16x32_bf16 v[128:131], v[120:123], v[176:179], v[128:131]
	v_mfma_f32_16x16x32_bf16 v[116:119], v[108:111], v[180:183], v[116:119]
	v_mfma_f32_16x16x32_bf16 v[116:119], v[120:123], v[184:187], v[116:119]
	v_mfma_f32_16x16x32_bf16 v[104:107], v[108:111], v[188:191], v[104:107]
	v_mfma_f32_16x16x32_bf16 v[104:107], v[120:123], v[192:195], v[104:107]
	v_mfma_f32_16x16x32_bf16 v[152:155], v[132:135], v[164:167], v[152:155]
	v_mfma_f32_16x16x32_bf16 v[152:155], v[136:139], v[168:171], v[152:155]
	v_mfma_f32_16x16x32_bf16 v[124:127], v[132:135], v[172:175], v[124:127]
	v_mfma_f32_16x16x32_bf16 v[124:127], v[136:139], v[176:179], v[124:127]
	v_mfma_f32_16x16x32_bf16 v[112:115], v[132:135], v[180:183], v[112:115]
	v_mfma_f32_16x16x32_bf16 v[112:115], v[136:139], v[184:187], v[112:115]
	v_mfma_f32_16x16x32_bf16 v[100:103], v[132:135], v[188:191], v[100:103]
	v_mfma_f32_16x16x32_bf16 v[100:103], v[136:139], v[192:195], v[100:103]
	s_setprio 0
	s_setprio 1
	v_mfma_f32_16x16x32_bf16 v[92:95], v[140:143], v[164:167], v[92:95]
	v_mfma_f32_16x16x32_bf16 v[92:95], v[144:147], v[168:171], v[92:95]
	v_mfma_f32_16x16x32_bf16 v[84:87], v[140:143], v[172:175], v[84:87]
	v_mfma_f32_16x16x32_bf16 v[84:87], v[144:147], v[176:179], v[84:87]
	v_mfma_f32_16x16x32_bf16 v[76:79], v[140:143], v[180:183], v[76:79]
	v_mfma_f32_16x16x32_bf16 v[76:79], v[144:147], v[184:187], v[76:79]
	v_mfma_f32_16x16x32_bf16 v[68:71], v[140:143], v[188:191], v[68:71]
	v_mfma_f32_16x16x32_bf16 v[68:71], v[144:147], v[192:195], v[68:71]
	v_mfma_f32_16x16x32_bf16 v[88:91], v[148:151], v[164:167], v[88:91]
	v_mfma_f32_16x16x32_bf16 v[88:91], v[160:163], v[168:171], v[88:91]
	v_mfma_f32_16x16x32_bf16 v[80:83], v[148:151], v[172:175], v[80:83]
	v_mfma_f32_16x16x32_bf16 v[80:83], v[160:163], v[176:179], v[80:83]
	v_mfma_f32_16x16x32_bf16 v[72:75], v[148:151], v[180:183], v[72:75]
	v_mfma_f32_16x16x32_bf16 v[72:75], v[160:163], v[184:187], v[72:75]
	v_mfma_f32_16x16x32_bf16 v[64:67], v[148:151], v[188:191], v[64:67]
	v_mfma_f32_16x16x32_bf16 v[64:67], v[160:163], v[192:195], v[64:67]
	s_setprio 0
	s_barrier
	s_nop 1
	s_add_i32 s3, s3, s64
	v_lshl_add_u64 v[196:197], v[196:197], 0, s[72:73]
	s_mov_b32 m0, s3
	ds_read_b128 v[164:167], v223 offset:49152
	ds_read_b128 v[168:171], v223 offset:50176
	ds_read_b128 v[172:175], v223 offset:51200
	ds_read_b128 v[176:179], v223 offset:52224
	ds_read_b128 v[180:183], v223 offset:53248
	ds_read_b128 v[184:187], v223 offset:54272
	ds_read_b128 v[188:191], v223 offset:55296
	ds_read_b128 v[192:195], v223 offset:56320
	global_load_lds_dwordx4 v[196:197], off
	s_add_i32 m0, s3, 0x2000
	s_add_u32 s50, vcc_lo, 0x80080
	v_lshl_add_u64 v[196:197], v[198:199], 0, s[72:73]
	s_addc_u32 s51, vcc_hi, 0
	s_add_i32 s3, s41, s64
	global_load_lds_dwordx4 v[196:197], off
	s_mov_b32 m0, s3
	s_nop 0
	global_load_lds_dwordx4 v212, s[50:51]
	s_add_i32 m0, s3, 0x2000
	s_nop 0
	global_load_lds_dwordx4 v208, s[50:51]
	v_lshl_add_u64 v[196:197], v[200:201], 0, s[72:73]
	s_mov_b32 m0, s83
	s_nop 0
	global_load_lds_dwordx4 v[196:197], off
	v_lshl_add_u64 v[196:197], v[202:203], 0, s[72:73]
	s_mov_b32 m0, s84
	s_nop 0
	global_load_lds_dwordx4 v[196:197], off
	s_waitcnt vmcnt(8)
	s_waitcnt lgkmcnt(0)
	s_barrier
	s_setprio 1
	s_waitcnt lgkmcnt(0)
	v_mfma_f32_16x16x32_bf16 v[60:63], v[108:111], v[164:167], v[60:63]
	v_mfma_f32_16x16x32_bf16 v[60:63], v[120:123], v[168:171], v[60:63]
	v_mfma_f32_16x16x32_bf16 v[52:55], v[108:111], v[172:175], v[52:55]
	v_mfma_f32_16x16x32_bf16 v[52:55], v[120:123], v[176:179], v[52:55]
	v_mfma_f32_16x16x32_bf16 v[44:47], v[108:111], v[180:183], v[44:47]
	v_mfma_f32_16x16x32_bf16 v[44:47], v[120:123], v[184:187], v[44:47]
	v_mfma_f32_16x16x32_bf16 v[36:39], v[108:111], v[188:191], v[36:39]
	v_mfma_f32_16x16x32_bf16 v[36:39], v[120:123], v[192:195], v[36:39]
	v_mfma_f32_16x16x32_bf16 v[56:59], v[132:135], v[164:167], v[56:59]
	v_mfma_f32_16x16x32_bf16 v[56:59], v[136:139], v[168:171], v[56:59]
	v_mfma_f32_16x16x32_bf16 v[48:51], v[132:135], v[172:175], v[48:51]
	v_mfma_f32_16x16x32_bf16 v[48:51], v[136:139], v[176:179], v[48:51]
	v_mfma_f32_16x16x32_bf16 v[40:43], v[132:135], v[180:183], v[40:43]
	v_mfma_f32_16x16x32_bf16 v[40:43], v[136:139], v[184:187], v[40:43]
	v_mfma_f32_16x16x32_bf16 v[32:35], v[132:135], v[188:191], v[32:35]
	v_mfma_f32_16x16x32_bf16 v[32:35], v[136:139], v[192:195], v[32:35]
	s_setprio 0
	s_setprio 1
	v_mfma_f32_16x16x32_bf16 v[28:31], v[140:143], v[164:167], v[28:31]
	v_mfma_f32_16x16x32_bf16 v[28:31], v[144:147], v[168:171], v[28:31]
	v_mfma_f32_16x16x32_bf16 v[20:23], v[140:143], v[172:175], v[20:23]
	v_mfma_f32_16x16x32_bf16 v[20:23], v[144:147], v[176:179], v[20:23]
	v_mfma_f32_16x16x32_bf16 v[12:15], v[140:143], v[180:183], v[12:15]
	v_mfma_f32_16x16x32_bf16 v[12:15], v[144:147], v[184:187], v[12:15]
	v_mfma_f32_16x16x32_bf16 v[4:7], v[140:143], v[188:191], v[4:7]
	v_mfma_f32_16x16x32_bf16 v[4:7], v[144:147], v[192:195], v[4:7]
	v_mfma_f32_16x16x32_bf16 v[24:27], v[148:151], v[164:167], v[24:27]
	v_mfma_f32_16x16x32_bf16 v[24:27], v[160:163], v[168:171], v[24:27]
	v_mfma_f32_16x16x32_bf16 v[16:19], v[148:151], v[172:175], v[16:19]
	v_mfma_f32_16x16x32_bf16 v[16:19], v[160:163], v[176:179], v[16:19]
	v_mfma_f32_16x16x32_bf16 v[8:11], v[148:151], v[180:183], v[8:11]
	v_mfma_f32_16x16x32_bf16 v[8:11], v[160:163], v[184:187], v[8:11]
	v_mfma_f32_16x16x32_bf16 v[0:3], v[148:151], v[188:191], v[0:3]
	v_mfma_f32_16x16x32_bf16 v[0:3], v[160:163], v[192:195], v[0:3]
	s_setprio 0
	s_barrier
	s_nop 1
	s_add_u32 s34, s34, 0x100
	s_addc_u32 s35, s35, 0
	s_cmp_ge_i32 s2, s21
	s_mov_b32 s41, s2
	s_cbranch_scc1 .LBB0_666
	s_branch .LBB0_660
.LBB0_659:
	s_add_i32 s2, s41, 2
	s_add_u32 s3, s10, s34
	s_addc_u32 s50, s11, s35
	s_add_u32 s3, s3, 0x100
	s_addc_u32 s50, s50, 0
	s_add_u32 s51, s9, s34
	s_addc_u32 s75, s19, s35
	s_cmp_eq_u32 s45, s41
	s_cselect_b32 s89, s17, s50
	s_cselect_b32 s88, s16, s3
	s_cselect_b32 vcc_hi, s13, s75
	s_cselect_b32 vcc_lo, s12, s51
	s_add_i32 s3, 0, 0x10000
	s_add_i32 s41, 0, 0x14000
	v_add_u32_e32 v136, s3, v220
	v_add_u32_e32 v160, s41, v220
	ds_read_b128 v[108:111], v136
	ds_read_b128 v[120:123], v136 offset:1024
	ds_read_b128 v[132:135], v136 offset:2048
	ds_read_b128 v[136:139], v136 offset:3072
	ds_read_b128 v[140:143], v160
	ds_read_b128 v[144:147], v160 offset:1024
	ds_read_b128 v[148:151], v160 offset:2048
	ds_read_b128 v[160:163], v160 offset:3072
	v_lshl_add_u64 v[196:197], v[96:97], 0, s[34:35]
	s_add_i32 m0, s15, 0xc000
	ds_read_b128 v[164:167], v223
	ds_read_b128 v[168:171], v223 offset:1024
	ds_read_b128 v[172:175], v223 offset:2048
	ds_read_b128 v[176:179], v223 offset:3072
	ds_read_b128 v[180:183], v223 offset:4096
	ds_read_b128 v[184:187], v223 offset:5120
	ds_read_b128 v[188:191], v223 offset:6144
	ds_read_b128 v[192:195], v223 offset:7168
	global_load_lds_dwordx4 v[196:197], off
	v_lshl_add_u64 v[196:197], v[98:99], 0, s[34:35]
	s_add_i32 m0, s15, 0xe000
	s_nop 0
	global_load_lds_dwordx4 v[196:197], off
	s_waitcnt vmcnt(8)
	s_waitcnt lgkmcnt(0)
	s_barrier
	s_setprio 1
	s_waitcnt lgkmcnt(0)
	v_mfma_f32_16x16x32_bf16 v[156:159], v[108:111], v[164:167], v[156:159]
	v_mfma_f32_16x16x32_bf16 v[156:159], v[120:123], v[168:171], v[156:159]
	v_mfma_f32_16x16x32_bf16 v[128:131], v[108:111], v[172:175], v[128:131]
	v_mfma_f32_16x16x32_bf16 v[128:131], v[120:123], v[176:179], v[128:131]
	v_mfma_f32_16x16x32_bf16 v[116:119], v[108:111], v[180:183], v[116:119]
	v_mfma_f32_16x16x32_bf16 v[116:119], v[120:123], v[184:187], v[116:119]
	v_mfma_f32_16x16x32_bf16 v[104:107], v[108:111], v[188:191], v[104:107]
	v_mfma_f32_16x16x32_bf16 v[104:107], v[120:123], v[192:195], v[104:107]
	v_mfma_f32_16x16x32_bf16 v[152:155], v[132:135], v[164:167], v[152:155]
	v_mfma_f32_16x16x32_bf16 v[152:155], v[136:139], v[168:171], v[152:155]
	v_mfma_f32_16x16x32_bf16 v[124:127], v[132:135], v[172:175], v[124:127]
	v_mfma_f32_16x16x32_bf16 v[124:127], v[136:139], v[176:179], v[124:127]
	v_mfma_f32_16x16x32_bf16 v[112:115], v[132:135], v[180:183], v[112:115]
	v_mfma_f32_16x16x32_bf16 v[112:115], v[136:139], v[184:187], v[112:115]
	v_mfma_f32_16x16x32_bf16 v[100:103], v[132:135], v[188:191], v[100:103]
	v_mfma_f32_16x16x32_bf16 v[100:103], v[136:139], v[192:195], v[100:103]
	s_setprio 0
	s_setprio 1
	v_mfma_f32_16x16x32_bf16 v[92:95], v[140:143], v[164:167], v[92:95]
	v_mfma_f32_16x16x32_bf16 v[92:95], v[144:147], v[168:171], v[92:95]
	v_mfma_f32_16x16x32_bf16 v[84:87], v[140:143], v[172:175], v[84:87]
	v_mfma_f32_16x16x32_bf16 v[84:87], v[144:147], v[176:179], v[84:87]
	v_mfma_f32_16x16x32_bf16 v[76:79], v[140:143], v[180:183], v[76:79]
	v_mfma_f32_16x16x32_bf16 v[76:79], v[144:147], v[184:187], v[76:79]
	v_mfma_f32_16x16x32_bf16 v[68:71], v[140:143], v[188:191], v[68:71]
	v_mfma_f32_16x16x32_bf16 v[68:71], v[144:147], v[192:195], v[68:71]
	v_mfma_f32_16x16x32_bf16 v[88:91], v[148:151], v[164:167], v[88:91]
	v_mfma_f32_16x16x32_bf16 v[88:91], v[160:163], v[168:171], v[88:91]
	v_mfma_f32_16x16x32_bf16 v[80:83], v[148:151], v[172:175], v[80:83]
	v_mfma_f32_16x16x32_bf16 v[80:83], v[160:163], v[176:179], v[80:83]
	v_mfma_f32_16x16x32_bf16 v[72:75], v[148:151], v[180:183], v[72:75]
	v_mfma_f32_16x16x32_bf16 v[72:75], v[160:163], v[184:187], v[72:75]
	v_mfma_f32_16x16x32_bf16 v[64:67], v[148:151], v[188:191], v[64:67]
	v_mfma_f32_16x16x32_bf16 v[64:67], v[160:163], v[192:195], v[64:67]
	s_setprio 0
	s_barrier
	s_nop 1
	s_add_i32 s3, s3, s64
	v_lshl_add_u64 v[196:197], vcc, 0, v[212:213]
	s_mov_b32 m0, s3
	ds_read_b128 v[164:167], v223 offset:16384
	ds_read_b128 v[168:171], v223 offset:17408
	ds_read_b128 v[172:175], v223 offset:18432
	ds_read_b128 v[176:179], v223 offset:19456
	ds_read_b128 v[180:183], v223 offset:20480
	ds_read_b128 v[184:187], v223 offset:21504
	ds_read_b128 v[188:191], v223 offset:22528
	ds_read_b128 v[192:195], v223 offset:23552
	global_load_lds_dwordx4 v[196:197], off
	s_add_i32 m0, s3, 0x2000
	s_add_u32 s50, vcc_lo, 0x80000
	v_lshl_add_u64 v[198:199], vcc, 0, v[208:209]
	s_addc_u32 s51, vcc_hi, 0
	s_add_i32 s3, s41, s64
	global_load_lds_dwordx4 v[198:199], off
	s_mov_b32 m0, s3
	v_lshl_add_u64 v[202:203], s[88:89], 0, v[206:207]
	global_load_lds_dwordx4 v212, s[50:51]
	s_add_i32 m0, s3, 0x2000
	s_nop 0
	global_load_lds_dwordx4 v208, s[50:51]
	v_lshl_add_u64 v[200:201], s[88:89], 0, v[204:205]
	s_mov_b32 m0, s15
	s_nop 0
	global_load_lds_dwordx4 v[200:201], off
	s_mov_b32 m0, s43
	s_nop 0
	global_load_lds_dwordx4 v[202:203], off
	s_waitcnt vmcnt(8)
	s_waitcnt lgkmcnt(0)
	s_barrier
	s_setprio 1
	s_waitcnt lgkmcnt(0)
	v_mfma_f32_16x16x32_bf16 v[60:63], v[108:111], v[164:167], v[60:63]
	v_mfma_f32_16x16x32_bf16 v[60:63], v[120:123], v[168:171], v[60:63]
	v_mfma_f32_16x16x32_bf16 v[52:55], v[108:111], v[172:175], v[52:55]
	v_mfma_f32_16x16x32_bf16 v[52:55], v[120:123], v[176:179], v[52:55]
	v_mfma_f32_16x16x32_bf16 v[44:47], v[108:111], v[180:183], v[44:47]
	v_mfma_f32_16x16x32_bf16 v[44:47], v[120:123], v[184:187], v[44:47]
	v_mfma_f32_16x16x32_bf16 v[36:39], v[108:111], v[188:191], v[36:39]
	v_mfma_f32_16x16x32_bf16 v[36:39], v[120:123], v[192:195], v[36:39]
	v_mfma_f32_16x16x32_bf16 v[56:59], v[132:135], v[164:167], v[56:59]
	v_mfma_f32_16x16x32_bf16 v[56:59], v[136:139], v[168:171], v[56:59]
	v_mfma_f32_16x16x32_bf16 v[48:51], v[132:135], v[172:175], v[48:51]
	v_mfma_f32_16x16x32_bf16 v[48:51], v[136:139], v[176:179], v[48:51]
	v_mfma_f32_16x16x32_bf16 v[40:43], v[132:135], v[180:183], v[40:43]
	v_mfma_f32_16x16x32_bf16 v[40:43], v[136:139], v[184:187], v[40:43]
	v_mfma_f32_16x16x32_bf16 v[32:35], v[132:135], v[188:191], v[32:35]
	v_mfma_f32_16x16x32_bf16 v[32:35], v[136:139], v[192:195], v[32:35]
	s_setprio 0
	s_setprio 1
	v_mfma_f32_16x16x32_bf16 v[28:31], v[140:143], v[164:167], v[28:31]
	v_mfma_f32_16x16x32_bf16 v[28:31], v[144:147], v[168:171], v[28:31]
	v_mfma_f32_16x16x32_bf16 v[20:23], v[140:143], v[172:175], v[20:23]
	v_mfma_f32_16x16x32_bf16 v[20:23], v[144:147], v[176:179], v[20:23]
	v_mfma_f32_16x16x32_bf16 v[12:15], v[140:143], v[180:183], v[12:15]
	v_mfma_f32_16x16x32_bf16 v[12:15], v[144:147], v[184:187], v[12:15]
	v_mfma_f32_16x16x32_bf16 v[4:7], v[140:143], v[188:191], v[4:7]
	v_mfma_f32_16x16x32_bf16 v[4:7], v[144:147], v[192:195], v[4:7]
	v_mfma_f32_16x16x32_bf16 v[24:27], v[148:151], v[164:167], v[24:27]
	v_mfma_f32_16x16x32_bf16 v[24:27], v[160:163], v[168:171], v[24:27]
	v_mfma_f32_16x16x32_bf16 v[16:19], v[148:151], v[172:175], v[16:19]
	v_mfma_f32_16x16x32_bf16 v[16:19], v[160:163], v[176:179], v[16:19]
	v_mfma_f32_16x16x32_bf16 v[8:11], v[148:151], v[180:183], v[8:11]
	v_mfma_f32_16x16x32_bf16 v[8:11], v[160:163], v[184:187], v[8:11]
	v_mfma_f32_16x16x32_bf16 v[0:3], v[148:151], v[188:191], v[0:3]
	v_mfma_f32_16x16x32_bf16 v[0:3], v[160:163], v[192:195], v[0:3]
	s_setprio 0
	s_barrier
	s_nop 1
	s_add_i32 s3, 0, 0x18000
	s_add_i32 s41, 0, 0x1c000
	v_add_u32_e32 v136, s3, v220
	v_add_u32_e32 v160, s41, v220
	ds_read_b128 v[108:111], v136
	ds_read_b128 v[120:123], v136 offset:1024
	ds_read_b128 v[132:135], v136 offset:2048
	ds_read_b128 v[136:139], v136 offset:3072
	ds_read_b128 v[140:143], v160
	ds_read_b128 v[144:147], v160 offset:1024
	ds_read_b128 v[148:151], v160 offset:2048
	ds_read_b128 v[160:163], v160 offset:3072
	s_add_u32 s50, s88, 0x80000
	s_addc_u32 s51, s89, 0
	s_mov_b32 m0, s69
	ds_read_b128 v[164:167], v223 offset:32768
	ds_read_b128 v[168:171], v223 offset:33792
	ds_read_b128 v[172:175], v223 offset:34816
	ds_read_b128 v[176:179], v223 offset:35840
	ds_read_b128 v[180:183], v223 offset:36864
	ds_read_b128 v[184:187], v223 offset:37888
	ds_read_b128 v[188:191], v223 offset:38912
	ds_read_b128 v[192:195], v223 offset:39936
	global_load_lds_dwordx4 v204, s[50:51]
	v_lshl_add_u64 v[214:215], s[50:51], 0, v[206:207]
	s_mov_b32 m0, s70
	s_nop 0
	global_load_lds_dwordx4 v[214:215], off
	s_waitcnt vmcnt(8)
	s_waitcnt lgkmcnt(0)
	s_barrier
	s_setprio 1
	s_waitcnt lgkmcnt(0)
	v_mfma_f32_16x16x32_bf16 v[156:159], v[108:111], v[164:167], v[156:159]
	v_mfma_f32_16x16x32_bf16 v[156:159], v[120:123], v[168:171], v[156:159]
	v_mfma_f32_16x16x32_bf16 v[128:131], v[108:111], v[172:175], v[128:131]
	v_mfma_f32_16x16x32_bf16 v[128:131], v[120:123], v[176:179], v[128:131]
	v_mfma_f32_16x16x32_bf16 v[116:119], v[108:111], v[180:183], v[116:119]
	v_mfma_f32_16x16x32_bf16 v[116:119], v[120:123], v[184:187], v[116:119]
	v_mfma_f32_16x16x32_bf16 v[104:107], v[108:111], v[188:191], v[104:107]
	v_mfma_f32_16x16x32_bf16 v[104:107], v[120:123], v[192:195], v[104:107]
	v_mfma_f32_16x16x32_bf16 v[152:155], v[132:135], v[164:167], v[152:155]
	v_mfma_f32_16x16x32_bf16 v[152:155], v[136:139], v[168:171], v[152:155]
	v_mfma_f32_16x16x32_bf16 v[124:127], v[132:135], v[172:175], v[124:127]
	v_mfma_f32_16x16x32_bf16 v[124:127], v[136:139], v[176:179], v[124:127]
	v_mfma_f32_16x16x32_bf16 v[112:115], v[132:135], v[180:183], v[112:115]
	v_mfma_f32_16x16x32_bf16 v[112:115], v[136:139], v[184:187], v[112:115]
	v_mfma_f32_16x16x32_bf16 v[100:103], v[132:135], v[188:191], v[100:103]
	v_mfma_f32_16x16x32_bf16 v[100:103], v[136:139], v[192:195], v[100:103]
	s_setprio 0
	s_setprio 1
	v_mfma_f32_16x16x32_bf16 v[92:95], v[140:143], v[164:167], v[92:95]
	v_mfma_f32_16x16x32_bf16 v[92:95], v[144:147], v[168:171], v[92:95]
	v_mfma_f32_16x16x32_bf16 v[84:87], v[140:143], v[172:175], v[84:87]
	v_mfma_f32_16x16x32_bf16 v[84:87], v[144:147], v[176:179], v[84:87]
	v_mfma_f32_16x16x32_bf16 v[76:79], v[140:143], v[180:183], v[76:79]
	v_mfma_f32_16x16x32_bf16 v[76:79], v[144:147], v[184:187], v[76:79]
	v_mfma_f32_16x16x32_bf16 v[68:71], v[140:143], v[188:191], v[68:71]
	v_mfma_f32_16x16x32_bf16 v[68:71], v[144:147], v[192:195], v[68:71]
	v_mfma_f32_16x16x32_bf16 v[88:91], v[148:151], v[164:167], v[88:91]
	v_mfma_f32_16x16x32_bf16 v[88:91], v[160:163], v[168:171], v[88:91]
	v_mfma_f32_16x16x32_bf16 v[80:83], v[148:151], v[172:175], v[80:83]
	v_mfma_f32_16x16x32_bf16 v[80:83], v[160:163], v[176:179], v[80:83]
	v_mfma_f32_16x16x32_bf16 v[72:75], v[148:151], v[180:183], v[72:75]
	v_mfma_f32_16x16x32_bf16 v[72:75], v[160:163], v[184:187], v[72:75]
	v_mfma_f32_16x16x32_bf16 v[64:67], v[148:151], v[188:191], v[64:67]
	v_mfma_f32_16x16x32_bf16 v[64:67], v[160:163], v[192:195], v[64:67]
	s_setprio 0
	s_barrier
	s_nop 1
	s_add_i32 s3, s3, s64
	v_lshl_add_u64 v[196:197], v[196:197], 0, s[72:73]
	s_mov_b32 m0, s3
	ds_read_b128 v[164:167], v223 offset:49152
	ds_read_b128 v[168:171], v223 offset:50176
	ds_read_b128 v[172:175], v223 offset:51200
	ds_read_b128 v[176:179], v223 offset:52224
	ds_read_b128 v[180:183], v223 offset:53248
	ds_read_b128 v[184:187], v223 offset:54272
	ds_read_b128 v[188:191], v223 offset:55296
	ds_read_b128 v[192:195], v223 offset:56320
	global_load_lds_dwordx4 v[196:197], off
	s_add_i32 m0, s3, 0x2000
	s_add_u32 s50, vcc_lo, 0x80080
	v_lshl_add_u64 v[196:197], v[198:199], 0, s[72:73]
	s_addc_u32 s51, vcc_hi, 0
	s_add_i32 s3, s41, s64
	global_load_lds_dwordx4 v[196:197], off
	s_mov_b32 m0, s3
	s_nop 0
	global_load_lds_dwordx4 v212, s[50:51]
	s_add_i32 m0, s3, 0x2000
	s_nop 0
	global_load_lds_dwordx4 v208, s[50:51]
	v_lshl_add_u64 v[196:197], v[200:201], 0, s[72:73]
	s_mov_b32 m0, s83
	s_nop 0
	global_load_lds_dwordx4 v[196:197], off
	v_lshl_add_u64 v[196:197], v[202:203], 0, s[72:73]
	s_mov_b32 m0, s84
	s_nop 0
	global_load_lds_dwordx4 v[196:197], off
	s_waitcnt vmcnt(8)
	s_waitcnt lgkmcnt(0)
	s_barrier
	s_setprio 1
	s_waitcnt lgkmcnt(0)
	v_mfma_f32_16x16x32_bf16 v[60:63], v[108:111], v[164:167], v[60:63]
	v_mfma_f32_16x16x32_bf16 v[60:63], v[120:123], v[168:171], v[60:63]
	v_mfma_f32_16x16x32_bf16 v[52:55], v[108:111], v[172:175], v[52:55]
	v_mfma_f32_16x16x32_bf16 v[52:55], v[120:123], v[176:179], v[52:55]
	v_mfma_f32_16x16x32_bf16 v[44:47], v[108:111], v[180:183], v[44:47]
	v_mfma_f32_16x16x32_bf16 v[44:47], v[120:123], v[184:187], v[44:47]
	v_mfma_f32_16x16x32_bf16 v[36:39], v[108:111], v[188:191], v[36:39]
	v_mfma_f32_16x16x32_bf16 v[36:39], v[120:123], v[192:195], v[36:39]
	v_mfma_f32_16x16x32_bf16 v[56:59], v[132:135], v[164:167], v[56:59]
	v_mfma_f32_16x16x32_bf16 v[56:59], v[136:139], v[168:171], v[56:59]
	v_mfma_f32_16x16x32_bf16 v[48:51], v[132:135], v[172:175], v[48:51]
	v_mfma_f32_16x16x32_bf16 v[48:51], v[136:139], v[176:179], v[48:51]
	v_mfma_f32_16x16x32_bf16 v[40:43], v[132:135], v[180:183], v[40:43]
	v_mfma_f32_16x16x32_bf16 v[40:43], v[136:139], v[184:187], v[40:43]
	v_mfma_f32_16x16x32_bf16 v[32:35], v[132:135], v[188:191], v[32:35]
	v_mfma_f32_16x16x32_bf16 v[32:35], v[136:139], v[192:195], v[32:35]
	s_setprio 0
	s_setprio 1
	v_mfma_f32_16x16x32_bf16 v[28:31], v[140:143], v[164:167], v[28:31]
	v_mfma_f32_16x16x32_bf16 v[28:31], v[144:147], v[168:171], v[28:31]
	v_mfma_f32_16x16x32_bf16 v[20:23], v[140:143], v[172:175], v[20:23]
	v_mfma_f32_16x16x32_bf16 v[20:23], v[144:147], v[176:179], v[20:23]
	v_mfma_f32_16x16x32_bf16 v[12:15], v[140:143], v[180:183], v[12:15]
	v_mfma_f32_16x16x32_bf16 v[12:15], v[144:147], v[184:187], v[12:15]
	v_mfma_f32_16x16x32_bf16 v[4:7], v[140:143], v[188:191], v[4:7]
	v_mfma_f32_16x16x32_bf16 v[4:7], v[144:147], v[192:195], v[4:7]
	v_mfma_f32_16x16x32_bf16 v[24:27], v[148:151], v[164:167], v[24:27]
	v_mfma_f32_16x16x32_bf16 v[24:27], v[160:163], v[168:171], v[24:27]
	v_mfma_f32_16x16x32_bf16 v[16:19], v[148:151], v[172:175], v[16:19]
	v_mfma_f32_16x16x32_bf16 v[16:19], v[160:163], v[176:179], v[16:19]
	v_mfma_f32_16x16x32_bf16 v[8:11], v[148:151], v[180:183], v[8:11]
	v_mfma_f32_16x16x32_bf16 v[8:11], v[160:163], v[184:187], v[8:11]
	v_mfma_f32_16x16x32_bf16 v[0:3], v[148:151], v[188:191], v[0:3]
	v_mfma_f32_16x16x32_bf16 v[0:3], v[160:163], v[192:195], v[0:3]
	s_setprio 0
	s_barrier
	s_nop 1
	s_add_u32 s34, s34, 0x100
	s_addc_u32 s35, s35, 0
	s_cmp_ge_i32 s2, s21
	s_mov_b32 s41, s2
	s_cbranch_scc1 .LBB0_666

.LBB0_830:
	s_ashr_i32 s13, s12, 31
	s_lshl_b64 s[2:3], s[12:13], 20
	s_add_u32 s14, s33, s2
	s_addc_u32 s15, s34, s3
	s_and_b64 s[2:3], s[36:37], exec
	s_cselect_b32 s13, s15, s25
	s_cselect_b32 s63, s14, s24
	s_ashr_i32 s11, s10, 31
	s_lshl_b64 s[2:3], s[10:11], 20
	s_add_u32 s38, s35, s2
	s_addc_u32 s39, s40, s3
	s_and_b64 s[2:3], s[36:37], exec
	s_cselect_b32 s11, s39, s27
	s_cselect_b32 s64, s38, s26
	s_lshl_b32 s16, s18, 8
	s_ashr_i32 s17, s16, 31
	s_lshl_b64 s[2:3], s[16:17], 5
	s_mul_hi_i32 s17, s18, 0x78787879
	s_lshr_b32 s20, s17, 31
	s_ashr_i32 s17, s17, 3
	s_add_i32 s17, s17, s20
	s_mul_i32 s20, s17, 17
	s_sub_i32 s20, s18, s20
	s_lshl_b32 s18, s19, 8
	s_ashr_i32 s19, s18, 31
	s_mul_i32 s21, s17, 0xf400
	s_mul_hi_i32 s22, s17, 0xf400
	s_cmp_lg_u32 s20, 0
	s_cselect_b32 s23, s22, 0
	s_cselect_b32 s22, s21, 0x7a000
	s_add_u32 s20, s47, s2
	s_addc_u32 s21, s49, s3
	s_lshl_b64 s[2:3], s[22:23], 2
	s_add_u32 s22, s50, s2
	s_addc_u32 s23, s51, s3
	s_lshl_b64 s[2:3], s[18:19], 2
	s_add_u32 s22, s22, s2
	s_addc_u32 s23, s23, s3
	s_add_u32 s24, s24, 0x80080
	s_addc_u32 s25, s25, 0
	s_add_u32 s19, s26, 0x100
	s_mov_b32 s17, 0
	s_addc_u32 s65, s27, 0
	s_add_u32 s2, s24, 0xfff80080
	s_addc_u32 s3, s25, -1
	s_cmp_eq_u32 s17, 30
	s_cselect_b32 s29, s13, s3
	s_cselect_b32 s28, s63, s2
	s_cselect_b32 s27, s11, s65
	s_cselect_b32 s26, s64, s19
	s_add_i32 s2, 0, 0x10000
	v_add_u32_e32 v138, s2, v140
	s_add_i32 s66, 0, 0x14000
	ds_read_b128 v[142:145], v138
	ds_read_b128 v[146:149], v138 offset:1024
	ds_read_b128 v[150:153], v138 offset:2048
	ds_read_b128 v[154:157], v138 offset:3072
	v_add_u32_e32 v138, s66, v140
	ds_read_b128 v[158:161], v138
	ds_read_b128 v[162:165], v138 offset:1024
	ds_read_b128 v[166:169], v138 offset:2048
	ds_read_b128 v[170:173], v138 offset:3072
	s_add_i32 m0, s43, 0xc000
	ds_read_b128 v[174:177], v141
	ds_read_b128 v[178:181], v141 offset:1024
	ds_read_b128 v[182:185], v141 offset:2048
	ds_read_b128 v[186:189], v141 offset:3072
	ds_read_b128 v[190:193], v141 offset:4096
	ds_read_b128 v[194:197], v141 offset:5120
	ds_read_b128 v[198:201], v141 offset:6144
	ds_read_b128 v[202:205], v141 offset:7168
	global_load_lds_dwordx4 v134, s[24:25]
	s_add_i32 m0, s43, 0xe000
	s_nop 0
	global_load_lds_dwordx4 v136, s[24:25]
	s_waitcnt vmcnt(8)
	s_waitcnt lgkmcnt(0)
	s_barrier
	s_setprio 1
	s_waitcnt lgkmcnt(0)
	v_mfma_f32_16x16x32_bf16 v[124:127], v[142:145], v[174:177], 0
	v_mfma_f32_16x16x32_bf16 v[124:127], v[146:149], v[178:181], v[124:127]
	v_mfma_f32_16x16x32_bf16 v[120:123], v[142:145], v[182:185], 0
	v_mfma_f32_16x16x32_bf16 v[120:123], v[146:149], v[186:189], v[120:123]
	v_mfma_f32_16x16x32_bf16 v[116:119], v[142:145], v[190:193], 0
	v_mfma_f32_16x16x32_bf16 v[116:119], v[146:149], v[194:197], v[116:119]
	v_mfma_f32_16x16x32_bf16 v[112:115], v[142:145], v[198:201], 0
	v_mfma_f32_16x16x32_bf16 v[112:115], v[146:149], v[202:205], v[112:115]
	v_mfma_f32_16x16x32_bf16 v[108:111], v[150:153], v[174:177], 0
	v_mfma_f32_16x16x32_bf16 v[108:111], v[154:157], v[178:181], v[108:111]
	v_mfma_f32_16x16x32_bf16 v[104:107], v[150:153], v[182:185], 0
	v_mfma_f32_16x16x32_bf16 v[104:107], v[154:157], v[186:189], v[104:107]
	v_mfma_f32_16x16x32_bf16 v[100:103], v[150:153], v[190:193], 0
	v_mfma_f32_16x16x32_bf16 v[100:103], v[154:157], v[194:197], v[100:103]
	v_mfma_f32_16x16x32_bf16 v[96:99], v[150:153], v[198:201], 0
	v_mfma_f32_16x16x32_bf16 v[96:99], v[154:157], v[202:205], v[96:99]
	s_setprio 0
	s_setprio 1
	v_mfma_f32_16x16x32_bf16 v[84:87], v[158:161], v[174:177], 0
	v_mfma_f32_16x16x32_bf16 v[84:87], v[162:165], v[178:181], v[84:87]
	v_mfma_f32_16x16x32_bf16 v[76:79], v[158:161], v[182:185], 0
	v_mfma_f32_16x16x32_bf16 v[76:79], v[162:165], v[186:189], v[76:79]
	v_mfma_f32_16x16x32_bf16 v[64:67], v[158:161], v[190:193], 0
	v_mfma_f32_16x16x32_bf16 v[64:67], v[162:165], v[194:197], v[64:67]
	v_mfma_f32_16x16x32_bf16 v[56:59], v[158:161], v[198:201], 0
	v_mfma_f32_16x16x32_bf16 v[56:59], v[162:165], v[202:205], v[56:59]
	v_mfma_f32_16x16x32_bf16 v[52:55], v[166:169], v[174:177], 0
	v_mfma_f32_16x16x32_bf16 v[52:55], v[170:173], v[178:181], v[52:55]
	v_mfma_f32_16x16x32_bf16 v[44:47], v[166:169], v[182:185], 0
	v_mfma_f32_16x16x32_bf16 v[44:47], v[170:173], v[186:189], v[44:47]
	v_mfma_f32_16x16x32_bf16 v[36:39], v[166:169], v[190:193], 0
	v_mfma_f32_16x16x32_bf16 v[36:39], v[170:173], v[194:197], v[36:39]
	v_mfma_f32_16x16x32_bf16 v[32:35], v[166:169], v[198:201], 0
	v_mfma_f32_16x16x32_bf16 v[32:35], v[170:173], v[202:205], v[32:35]
	s_setprio 0
	s_barrier
	s_nop 1
	s_add_i32 s2, s2, s41
	v_lshl_add_u64 v[138:139], s[26:27], 0, v[212:213]
	s_mov_b32 m0, s2
	ds_read_b128 v[174:177], v141 offset:16384
	ds_read_b128 v[178:181], v141 offset:17408
	ds_read_b128 v[182:185], v141 offset:18432
	ds_read_b128 v[186:189], v141 offset:19456
	ds_read_b128 v[190:193], v141 offset:20480
	ds_read_b128 v[194:197], v141 offset:21504
	ds_read_b128 v[198:201], v141 offset:22528
	ds_read_b128 v[202:205], v141 offset:23552
	global_load_lds_dwordx4 v[138:139], off
	s_add_i32 m0, s2, 0x2000
	s_add_u32 s2, s26, 0x80000
	v_lshl_add_u64 v[206:207], s[26:27], 0, v[128:129]
	s_addc_u32 s3, s27, 0
	s_add_i32 s66, s66, s41
	global_load_lds_dwordx4 v[206:207], off
	s_mov_b32 m0, s66
	v_lshl_add_u64 v[210:211], s[28:29], 0, v[130:131]
	global_load_lds_dwordx4 v212, s[2:3]
	s_add_i32 m0, s66, 0x2000
	s_nop 0
	global_load_lds_dwordx4 v128, s[2:3]
	v_lshl_add_u64 v[208:209], s[28:29], 0, v[132:133]
	s_mov_b32 m0, s43
	s_nop 0
	global_load_lds_dwordx4 v[208:209], off
	s_mov_b32 m0, s44
	s_nop 0
	global_load_lds_dwordx4 v[210:211], off
	s_waitcnt vmcnt(8)
	s_waitcnt lgkmcnt(0)
	s_barrier
	s_setprio 1
	s_waitcnt lgkmcnt(0)
	v_mfma_f32_16x16x32_bf16 v[92:95], v[142:145], v[174:177], 0
	v_mfma_f32_16x16x32_bf16 v[92:95], v[146:149], v[178:181], v[92:95]
	v_mfma_f32_16x16x32_bf16 v[88:91], v[142:145], v[182:185], 0
	v_mfma_f32_16x16x32_bf16 v[88:91], v[146:149], v[186:189], v[88:91]
	v_mfma_f32_16x16x32_bf16 v[80:83], v[142:145], v[190:193], 0
	v_mfma_f32_16x16x32_bf16 v[80:83], v[146:149], v[194:197], v[80:83]
	v_mfma_f32_16x16x32_bf16 v[72:75], v[142:145], v[198:201], 0
	v_mfma_f32_16x16x32_bf16 v[72:75], v[146:149], v[202:205], v[72:75]
	v_mfma_f32_16x16x32_bf16 v[68:71], v[150:153], v[174:177], 0
	v_mfma_f32_16x16x32_bf16 v[68:71], v[154:157], v[178:181], v[68:71]
	v_mfma_f32_16x16x32_bf16 v[60:63], v[150:153], v[182:185], 0
	v_mfma_f32_16x16x32_bf16 v[60:63], v[154:157], v[186:189], v[60:63]
	v_mfma_f32_16x16x32_bf16 v[48:51], v[150:153], v[190:193], 0
	v_mfma_f32_16x16x32_bf16 v[48:51], v[154:157], v[194:197], v[48:51]
	v_mfma_f32_16x16x32_bf16 v[40:43], v[150:153], v[198:201], 0
	v_mfma_f32_16x16x32_bf16 v[40:43], v[154:157], v[202:205], v[40:43]
	s_setprio 0
	s_setprio 1
	v_mfma_f32_16x16x32_bf16 v[28:31], v[158:161], v[174:177], 0
	v_mfma_f32_16x16x32_bf16 v[28:31], v[162:165], v[178:181], v[28:31]
	v_mfma_f32_16x16x32_bf16 v[24:27], v[158:161], v[182:185], 0
	v_mfma_f32_16x16x32_bf16 v[24:27], v[162:165], v[186:189], v[24:27]
	v_mfma_f32_16x16x32_bf16 v[20:23], v[158:161], v[190:193], 0
	v_mfma_f32_16x16x32_bf16 v[20:23], v[162:165], v[194:197], v[20:23]
	v_mfma_f32_16x16x32_bf16 v[16:19], v[158:161], v[198:201], 0
	v_mfma_f32_16x16x32_bf16 v[16:19], v[162:165], v[202:205], v[16:19]
	v_mfma_f32_16x16x32_bf16 v[12:15], v[166:169], v[174:177], 0
	v_mfma_f32_16x16x32_bf16 v[12:15], v[170:173], v[178:181], v[12:15]
	v_mfma_f32_16x16x32_bf16 v[8:11], v[166:169], v[182:185], 0
	v_mfma_f32_16x16x32_bf16 v[8:11], v[170:173], v[186:189], v[8:11]
	v_mfma_f32_16x16x32_bf16 v[4:7], v[166:169], v[190:193], 0
	v_mfma_f32_16x16x32_bf16 v[4:7], v[170:173], v[194:197], v[4:7]
	v_mfma_f32_16x16x32_bf16 v[0:3], v[166:169], v[198:201], 0
	v_mfma_f32_16x16x32_bf16 v[0:3], v[170:173], v[202:205], v[0:3]
	s_setprio 0
	s_barrier
	s_nop 1
	s_add_i32 s66, 0, 0x18000
	s_add_i32 s67, 0, 0x1c000
	v_add_u32_e32 v154, s66, v140
	v_add_u32_e32 v170, s67, v140
	ds_read_b128 v[142:145], v154
	ds_read_b128 v[146:149], v154 offset:1024
	ds_read_b128 v[150:153], v154 offset:2048
	ds_read_b128 v[154:157], v154 offset:3072
	ds_read_b128 v[158:161], v170
	ds_read_b128 v[162:165], v170 offset:1024
	ds_read_b128 v[166:169], v170 offset:2048
	ds_read_b128 v[170:173], v170 offset:3072
	s_add_u32 s2, s28, 0x80000
	s_addc_u32 s3, s29, 0
	s_mov_b32 m0, s45
	ds_read_b128 v[174:177], v141 offset:32768
	ds_read_b128 v[178:181], v141 offset:33792
	ds_read_b128 v[182:185], v141 offset:34816
	ds_read_b128 v[186:189], v141 offset:35840
	ds_read_b128 v[190:193], v141 offset:36864
	ds_read_b128 v[194:197], v141 offset:37888
	ds_read_b128 v[198:201], v141 offset:38912
	ds_read_b128 v[202:205], v141 offset:39936
	global_load_lds_dwordx4 v132, s[2:3]
	v_lshl_add_u64 v[214:215], s[2:3], 0, v[130:131]
	s_mov_b32 m0, s46
	s_nop 0
	global_load_lds_dwordx4 v[214:215], off
	s_waitcnt vmcnt(8)
	s_waitcnt lgkmcnt(0)
	s_barrier
	s_setprio 1
	s_waitcnt lgkmcnt(0)
	v_mfma_f32_16x16x32_bf16 v[124:127], v[142:145], v[174:177], v[124:127]
	v_mfma_f32_16x16x32_bf16 v[124:127], v[146:149], v[178:181], v[124:127]
	v_mfma_f32_16x16x32_bf16 v[120:123], v[142:145], v[182:185], v[120:123]
	v_mfma_f32_16x16x32_bf16 v[120:123], v[146:149], v[186:189], v[120:123]
	v_mfma_f32_16x16x32_bf16 v[116:119], v[142:145], v[190:193], v[116:119]
	v_mfma_f32_16x16x32_bf16 v[116:119], v[146:149], v[194:197], v[116:119]
	v_mfma_f32_16x16x32_bf16 v[112:115], v[142:145], v[198:201], v[112:115]
	v_mfma_f32_16x16x32_bf16 v[112:115], v[146:149], v[202:205], v[112:115]
	v_mfma_f32_16x16x32_bf16 v[108:111], v[150:153], v[174:177], v[108:111]
	v_mfma_f32_16x16x32_bf16 v[108:111], v[154:157], v[178:181], v[108:111]
	v_mfma_f32_16x16x32_bf16 v[104:107], v[150:153], v[182:185], v[104:107]
	v_mfma_f32_16x16x32_bf16 v[104:107], v[154:157], v[186:189], v[104:107]
	v_mfma_f32_16x16x32_bf16 v[100:103], v[150:153], v[190:193], v[100:103]
	v_mfma_f32_16x16x32_bf16 v[100:103], v[154:157], v[194:197], v[100:103]
	v_mfma_f32_16x16x32_bf16 v[96:99], v[150:153], v[198:201], v[96:99]
	v_mfma_f32_16x16x32_bf16 v[96:99], v[154:157], v[202:205], v[96:99]
	s_setprio 0
	s_setprio 1
	v_mfma_f32_16x16x32_bf16 v[84:87], v[158:161], v[174:177], v[84:87]
	v_mfma_f32_16x16x32_bf16 v[84:87], v[162:165], v[178:181], v[84:87]
	v_mfma_f32_16x16x32_bf16 v[76:79], v[158:161], v[182:185], v[76:79]
	v_mfma_f32_16x16x32_bf16 v[76:79], v[162:165], v[186:189], v[76:79]
	v_mfma_f32_16x16x32_bf16 v[64:67], v[158:161], v[190:193], v[64:67]
	v_mfma_f32_16x16x32_bf16 v[64:67], v[162:165], v[194:197], v[64:67]
	v_mfma_f32_16x16x32_bf16 v[56:59], v[158:161], v[198:201], v[56:59]
	v_mfma_f32_16x16x32_bf16 v[56:59], v[162:165], v[202:205], v[56:59]
	v_mfma_f32_16x16x32_bf16 v[52:55], v[166:169], v[174:177], v[52:55]
	v_mfma_f32_16x16x32_bf16 v[52:55], v[170:173], v[178:181], v[52:55]
	v_mfma_f32_16x16x32_bf16 v[44:47], v[166:169], v[182:185], v[44:47]
	v_mfma_f32_16x16x32_bf16 v[44:47], v[170:173], v[186:189], v[44:47]
	v_mfma_f32_16x16x32_bf16 v[36:39], v[166:169], v[190:193], v[36:39]
	v_mfma_f32_16x16x32_bf16 v[36:39], v[170:173], v[194:197], v[36:39]
	v_mfma_f32_16x16x32_bf16 v[32:35], v[166:169], v[198:201], v[32:35]
	v_mfma_f32_16x16x32_bf16 v[32:35], v[170:173], v[202:205], v[32:35]
	s_setprio 0
	s_barrier
	s_nop 1
	s_add_i32 s2, s66, s41
	v_lshl_add_u64 v[138:139], v[138:139], 0, s[72:73]
	s_mov_b32 m0, s2
	ds_read_b128 v[174:177], v141 offset:49152
	ds_read_b128 v[178:181], v141 offset:50176
	ds_read_b128 v[182:185], v141 offset:51200
	ds_read_b128 v[186:189], v141 offset:52224
	ds_read_b128 v[190:193], v141 offset:53248
	ds_read_b128 v[194:197], v141 offset:54272
	ds_read_b128 v[198:201], v141 offset:55296
	ds_read_b128 v[202:205], v141 offset:56320
	global_load_lds_dwordx4 v[138:139], off
	s_add_i32 m0, s2, 0x2000
	s_add_u32 s2, s26, 0x80080
	v_lshl_add_u64 v[138:139], v[206:207], 0, s[72:73]
	s_addc_u32 s3, s27, 0
	s_add_i32 s26, s67, s41
	global_load_lds_dwordx4 v[138:139], off
	s_mov_b32 m0, s26
	s_nop 0
	global_load_lds_dwordx4 v212, s[2:3]
	s_add_i32 m0, s26, 0x2000
	s_nop 0
	global_load_lds_dwordx4 v128, s[2:3]
	v_lshl_add_u64 v[138:139], v[208:209], 0, s[72:73]
	s_mov_b32 m0, s54
	s_nop 0
	global_load_lds_dwordx4 v[138:139], off
	v_lshl_add_u64 v[138:139], v[210:211], 0, s[72:73]
	s_mov_b32 m0, s55
	s_nop 0
	global_load_lds_dwordx4 v[138:139], off
	s_waitcnt vmcnt(8)
	s_waitcnt lgkmcnt(0)
	s_barrier
	s_setprio 1
	s_waitcnt lgkmcnt(0)
	v_mfma_f32_16x16x32_bf16 v[92:95], v[142:145], v[174:177], v[92:95]
	v_mfma_f32_16x16x32_bf16 v[92:95], v[146:149], v[178:181], v[92:95]
	v_mfma_f32_16x16x32_bf16 v[88:91], v[142:145], v[182:185], v[88:91]
	v_mfma_f32_16x16x32_bf16 v[88:91], v[146:149], v[186:189], v[88:91]
	v_mfma_f32_16x16x32_bf16 v[80:83], v[142:145], v[190:193], v[80:83]
	v_mfma_f32_16x16x32_bf16 v[80:83], v[146:149], v[194:197], v[80:83]
	v_mfma_f32_16x16x32_bf16 v[72:75], v[142:145], v[198:201], v[72:75]
	v_mfma_f32_16x16x32_bf16 v[72:75], v[146:149], v[202:205], v[72:75]
	v_mfma_f32_16x16x32_bf16 v[68:71], v[150:153], v[174:177], v[68:71]
	v_mfma_f32_16x16x32_bf16 v[68:71], v[154:157], v[178:181], v[68:71]
	v_mfma_f32_16x16x32_bf16 v[60:63], v[150:153], v[182:185], v[60:63]
	v_mfma_f32_16x16x32_bf16 v[60:63], v[154:157], v[186:189], v[60:63]
	v_mfma_f32_16x16x32_bf16 v[48:51], v[150:153], v[190:193], v[48:51]
	v_mfma_f32_16x16x32_bf16 v[48:51], v[154:157], v[194:197], v[48:51]
	v_mfma_f32_16x16x32_bf16 v[40:43], v[150:153], v[198:201], v[40:43]
	v_mfma_f32_16x16x32_bf16 v[40:43], v[154:157], v[202:205], v[40:43]
	s_setprio 0
	s_setprio 1
	v_mfma_f32_16x16x32_bf16 v[28:31], v[158:161], v[174:177], v[28:31]
	v_mfma_f32_16x16x32_bf16 v[28:31], v[162:165], v[178:181], v[28:31]
	v_mfma_f32_16x16x32_bf16 v[24:27], v[158:161], v[182:185], v[24:27]
	v_mfma_f32_16x16x32_bf16 v[24:27], v[162:165], v[186:189], v[24:27]
	v_mfma_f32_16x16x32_bf16 v[20:23], v[158:161], v[190:193], v[20:23]
	v_mfma_f32_16x16x32_bf16 v[20:23], v[162:165], v[194:197], v[20:23]
	v_mfma_f32_16x16x32_bf16 v[16:19], v[158:161], v[198:201], v[16:19]
	v_mfma_f32_16x16x32_bf16 v[16:19], v[162:165], v[202:205], v[16:19]
	v_mfma_f32_16x16x32_bf16 v[12:15], v[166:169], v[174:177], v[12:15]
	v_mfma_f32_16x16x32_bf16 v[12:15], v[170:173], v[178:181], v[12:15]
	v_mfma_f32_16x16x32_bf16 v[8:11], v[166:169], v[182:185], v[8:11]
	v_mfma_f32_16x16x32_bf16 v[8:11], v[170:173], v[186:189], v[8:11]
	v_mfma_f32_16x16x32_bf16 v[4:7], v[166:169], v[190:193], v[4:7]
	v_mfma_f32_16x16x32_bf16 v[4:7], v[170:173], v[194:197], v[4:7]
	v_mfma_f32_16x16x32_bf16 v[0:3], v[166:169], v[198:201], v[0:3]
	v_mfma_f32_16x16x32_bf16 v[0:3], v[170:173], v[202:205], v[0:3]
	s_setprio 0
	s_barrier
	s_nop 1
	s_add_i32 s2, s17, 2
	s_add_u32 s24, s24, 0x100
	s_addc_u32 s25, s25, 0
	s_add_u32 s19, s19, 0x100
	s_addc_u32 s65, s65, 0
	s_cmp_gt_u32 s17, 29
	s_mov_b32 s17, s2
	s_cbranch_scc1 .LBB0_842
	s_branch .LBB0_832
.LBB0_831:
	s_add_u32 s2, s24, 0xfff80080
	s_addc_u32 s3, s25, -1
	s_cmp_eq_u32 s17, 30
	s_cselect_b32 s29, s13, s3
	s_cselect_b32 s28, s63, s2
	s_cselect_b32 s27, s11, s65
	s_cselect_b32 s26, s64, s19
	s_add_i32 s2, 0, 0x10000
	v_add_u32_e32 v138, s2, v140
	s_add_i32 s66, 0, 0x14000
	ds_read_b128 v[142:145], v138
	ds_read_b128 v[146:149], v138 offset:1024
	ds_read_b128 v[150:153], v138 offset:2048
	ds_read_b128 v[154:157], v138 offset:3072
	v_add_u32_e32 v138, s66, v140
	ds_read_b128 v[158:161], v138
	ds_read_b128 v[162:165], v138 offset:1024
	ds_read_b128 v[166:169], v138 offset:2048
	ds_read_b128 v[170:173], v138 offset:3072
	s_add_i32 m0, s43, 0xc000
	ds_read_b128 v[174:177], v141
	ds_read_b128 v[178:181], v141 offset:1024
	ds_read_b128 v[182:185], v141 offset:2048
	ds_read_b128 v[186:189], v141 offset:3072
	ds_read_b128 v[190:193], v141 offset:4096
	ds_read_b128 v[194:197], v141 offset:5120
	ds_read_b128 v[198:201], v141 offset:6144
	ds_read_b128 v[202:205], v141 offset:7168
	global_load_lds_dwordx4 v134, s[24:25]
	s_add_i32 m0, s43, 0xe000
	s_nop 0
	global_load_lds_dwordx4 v136, s[24:25]
	s_waitcnt vmcnt(8)
	s_waitcnt lgkmcnt(0)
	s_barrier
	s_setprio 1
	s_waitcnt lgkmcnt(0)
	v_mfma_f32_16x16x32_bf16 v[124:127], v[142:145], v[174:177], v[124:127]
	v_mfma_f32_16x16x32_bf16 v[124:127], v[146:149], v[178:181], v[124:127]
	v_mfma_f32_16x16x32_bf16 v[120:123], v[142:145], v[182:185], v[120:123]
	v_mfma_f32_16x16x32_bf16 v[120:123], v[146:149], v[186:189], v[120:123]
	v_mfma_f32_16x16x32_bf16 v[116:119], v[142:145], v[190:193], v[116:119]
	v_mfma_f32_16x16x32_bf16 v[116:119], v[146:149], v[194:197], v[116:119]
	v_mfma_f32_16x16x32_bf16 v[112:115], v[142:145], v[198:201], v[112:115]
	v_mfma_f32_16x16x32_bf16 v[112:115], v[146:149], v[202:205], v[112:115]
	v_mfma_f32_16x16x32_bf16 v[108:111], v[150:153], v[174:177], v[108:111]
	v_mfma_f32_16x16x32_bf16 v[108:111], v[154:157], v[178:181], v[108:111]
	v_mfma_f32_16x16x32_bf16 v[104:107], v[150:153], v[182:185], v[104:107]
	v_mfma_f32_16x16x32_bf16 v[104:107], v[154:157], v[186:189], v[104:107]
	v_mfma_f32_16x16x32_bf16 v[100:103], v[150:153], v[190:193], v[100:103]
	v_mfma_f32_16x16x32_bf16 v[100:103], v[154:157], v[194:197], v[100:103]
	v_mfma_f32_16x16x32_bf16 v[96:99], v[150:153], v[198:201], v[96:99]
	v_mfma_f32_16x16x32_bf16 v[96:99], v[154:157], v[202:205], v[96:99]
	s_setprio 0
	s_setprio 1
	v_mfma_f32_16x16x32_bf16 v[84:87], v[158:161], v[174:177], v[84:87]
	v_mfma_f32_16x16x32_bf16 v[84:87], v[162:165], v[178:181], v[84:87]
	v_mfma_f32_16x16x32_bf16 v[76:79], v[158:161], v[182:185], v[76:79]
	v_mfma_f32_16x16x32_bf16 v[76:79], v[162:165], v[186:189], v[76:79]
	v_mfma_f32_16x16x32_bf16 v[64:67], v[158:161], v[190:193], v[64:67]
	v_mfma_f32_16x16x32_bf16 v[64:67], v[162:165], v[194:197], v[64:67]
	v_mfma_f32_16x16x32_bf16 v[56:59], v[158:161], v[198:201], v[56:59]
	v_mfma_f32_16x16x32_bf16 v[56:59], v[162:165], v[202:205], v[56:59]
	v_mfma_f32_16x16x32_bf16 v[52:55], v[166:169], v[174:177], v[52:55]
	v_mfma_f32_16x16x32_bf16 v[52:55], v[170:173], v[178:181], v[52:55]
	v_mfma_f32_16x16x32_bf16 v[44:47], v[166:169], v[182:185], v[44:47]
	v_mfma_f32_16x16x32_bf16 v[44:47], v[170:173], v[186:189], v[44:47]
	v_mfma_f32_16x16x32_bf16 v[36:39], v[166:169], v[190:193], v[36:39]
	v_mfma_f32_16x16x32_bf16 v[36:39], v[170:173], v[194:197], v[36:39]
	v_mfma_f32_16x16x32_bf16 v[32:35], v[166:169], v[198:201], v[32:35]
	v_mfma_f32_16x16x32_bf16 v[32:35], v[170:173], v[202:205], v[32:35]
	s_setprio 0
	s_barrier
	s_nop 1
	s_add_i32 s2, s2, s41
	v_lshl_add_u64 v[138:139], s[26:27], 0, v[212:213]
	s_mov_b32 m0, s2
	ds_read_b128 v[174:177], v141 offset:16384
	ds_read_b128 v[178:181], v141 offset:17408
	ds_read_b128 v[182:185], v141 offset:18432
	ds_read_b128 v[186:189], v141 offset:19456
	ds_read_b128 v[190:193], v141 offset:20480
	ds_read_b128 v[194:197], v141 offset:21504
	ds_read_b128 v[198:201], v141 offset:22528
	ds_read_b128 v[202:205], v141 offset:23552
	global_load_lds_dwordx4 v[138:139], off
	s_add_i32 m0, s2, 0x2000
	s_add_u32 s2, s26, 0x80000
	v_lshl_add_u64 v[206:207], s[26:27], 0, v[128:129]
	s_addc_u32 s3, s27, 0
	s_add_i32 s66, s66, s41
	global_load_lds_dwordx4 v[206:207], off
	s_mov_b32 m0, s66
	v_lshl_add_u64 v[210:211], s[28:29], 0, v[130:131]
	global_load_lds_dwordx4 v212, s[2:3]
	s_add_i32 m0, s66, 0x2000
	s_nop 0
	global_load_lds_dwordx4 v128, s[2:3]
	v_lshl_add_u64 v[208:209], s[28:29], 0, v[132:133]
	s_mov_b32 m0, s43
	s_nop 0
	global_load_lds_dwordx4 v[208:209], off
	s_mov_b32 m0, s44
	s_nop 0
	global_load_lds_dwordx4 v[210:211], off
	s_waitcnt vmcnt(8)
	s_waitcnt lgkmcnt(0)
	s_barrier
	s_setprio 1
	s_waitcnt lgkmcnt(0)
	v_mfma_f32_16x16x32_bf16 v[92:95], v[142:145], v[174:177], v[92:95]
	v_mfma_f32_16x16x32_bf16 v[92:95], v[146:149], v[178:181], v[92:95]
	v_mfma_f32_16x16x32_bf16 v[88:91], v[142:145], v[182:185], v[88:91]
	v_mfma_f32_16x16x32_bf16 v[88:91], v[146:149], v[186:189], v[88:91]
	v_mfma_f32_16x16x32_bf16 v[80:83], v[142:145], v[190:193], v[80:83]
	v_mfma_f32_16x16x32_bf16 v[80:83], v[146:149], v[194:197], v[80:83]
	v_mfma_f32_16x16x32_bf16 v[72:75], v[142:145], v[198:201], v[72:75]
	v_mfma_f32_16x16x32_bf16 v[72:75], v[146:149], v[202:205], v[72:75]
	v_mfma_f32_16x16x32_bf16 v[68:71], v[150:153], v[174:177], v[68:71]
	v_mfma_f32_16x16x32_bf16 v[68:71], v[154:157], v[178:181], v[68:71]
	v_mfma_f32_16x16x32_bf16 v[60:63], v[150:153], v[182:185], v[60:63]
	v_mfma_f32_16x16x32_bf16 v[60:63], v[154:157], v[186:189], v[60:63]
	v_mfma_f32_16x16x32_bf16 v[48:51], v[150:153], v[190:193], v[48:51]
	v_mfma_f32_16x16x32_bf16 v[48:51], v[154:157], v[194:197], v[48:51]
	v_mfma_f32_16x16x32_bf16 v[40:43], v[150:153], v[198:201], v[40:43]
	v_mfma_f32_16x16x32_bf16 v[40:43], v[154:157], v[202:205], v[40:43]
	s_setprio 0
	s_setprio 1
	v_mfma_f32_16x16x32_bf16 v[28:31], v[158:161], v[174:177], v[28:31]
	v_mfma_f32_16x16x32_bf16 v[28:31], v[162:165], v[178:181], v[28:31]
	v_mfma_f32_16x16x32_bf16 v[24:27], v[158:161], v[182:185], v[24:27]
	v_mfma_f32_16x16x32_bf16 v[24:27], v[162:165], v[186:189], v[24:27]
	v_mfma_f32_16x16x32_bf16 v[20:23], v[158:161], v[190:193], v[20:23]
	v_mfma_f32_16x16x32_bf16 v[20:23], v[162:165], v[194:197], v[20:23]
	v_mfma_f32_16x16x32_bf16 v[16:19], v[158:161], v[198:201], v[16:19]
	v_mfma_f32_16x16x32_bf16 v[16:19], v[162:165], v[202:205], v[16:19]
	v_mfma_f32_16x16x32_bf16 v[12:15], v[166:169], v[174:177], v[12:15]
	v_mfma_f32_16x16x32_bf16 v[12:15], v[170:173], v[178:181], v[12:15]
	v_mfma_f32_16x16x32_bf16 v[8:11], v[166:169], v[182:185], v[8:11]
	v_mfma_f32_16x16x32_bf16 v[8:11], v[170:173], v[186:189], v[8:11]
	v_mfma_f32_16x16x32_bf16 v[4:7], v[166:169], v[190:193], v[4:7]
	v_mfma_f32_16x16x32_bf16 v[4:7], v[170:173], v[194:197], v[4:7]
	v_mfma_f32_16x16x32_bf16 v[0:3], v[166:169], v[198:201], v[0:3]
	v_mfma_f32_16x16x32_bf16 v[0:3], v[170:173], v[202:205], v[0:3]
	s_setprio 0
	s_barrier
	s_nop 1
	s_add_i32 s66, 0, 0x18000
	s_add_i32 s67, 0, 0x1c000
	v_add_u32_e32 v154, s66, v140
	v_add_u32_e32 v170, s67, v140
	ds_read_b128 v[142:145], v154
	ds_read_b128 v[146:149], v154 offset:1024
	ds_read_b128 v[150:153], v154 offset:2048
	ds_read_b128 v[154:157], v154 offset:3072
	ds_read_b128 v[158:161], v170
	ds_read_b128 v[162:165], v170 offset:1024
	ds_read_b128 v[166:169], v170 offset:2048
	ds_read_b128 v[170:173], v170 offset:3072
	s_add_u32 s2, s28, 0x80000
	s_addc_u32 s3, s29, 0
	s_mov_b32 m0, s45
	ds_read_b128 v[174:177], v141 offset:32768
	ds_read_b128 v[178:181], v141 offset:33792
	ds_read_b128 v[182:185], v141 offset:34816
	ds_read_b128 v[186:189], v141 offset:35840
	ds_read_b128 v[190:193], v141 offset:36864
	ds_read_b128 v[194:197], v141 offset:37888
	ds_read_b128 v[198:201], v141 offset:38912
	ds_read_b128 v[202:205], v141 offset:39936
	global_load_lds_dwordx4 v132, s[2:3]
	v_lshl_add_u64 v[214:215], s[2:3], 0, v[130:131]
	s_mov_b32 m0, s46
	s_nop 0
	global_load_lds_dwordx4 v[214:215], off
	s_waitcnt vmcnt(8)
	s_waitcnt lgkmcnt(0)
	s_barrier
	s_setprio 1
	s_waitcnt lgkmcnt(0)
	v_mfma_f32_16x16x32_bf16 v[124:127], v[142:145], v[174:177], v[124:127]
	v_mfma_f32_16x16x32_bf16 v[124:127], v[146:149], v[178:181], v[124:127]
	v_mfma_f32_16x16x32_bf16 v[120:123], v[142:145], v[182:185], v[120:123]
	v_mfma_f32_16x16x32_bf16 v[120:123], v[146:149], v[186:189], v[120:123]
	v_mfma_f32_16x16x32_bf16 v[116:119], v[142:145], v[190:193], v[116:119]
	v_mfma_f32_16x16x32_bf16 v[116:119], v[146:149], v[194:197], v[116:119]
	v_mfma_f32_16x16x32_bf16 v[112:115], v[142:145], v[198:201], v[112:115]
	v_mfma_f32_16x16x32_bf16 v[112:115], v[146:149], v[202:205], v[112:115]
	v_mfma_f32_16x16x32_bf16 v[108:111], v[150:153], v[174:177], v[108:111]
	v_mfma_f32_16x16x32_bf16 v[108:111], v[154:157], v[178:181], v[108:111]
	v_mfma_f32_16x16x32_bf16 v[104:107], v[150:153], v[182:185], v[104:107]
	v_mfma_f32_16x16x32_bf16 v[104:107], v[154:157], v[186:189], v[104:107]
	v_mfma_f32_16x16x32_bf16 v[100:103], v[150:153], v[190:193], v[100:103]
	v_mfma_f32_16x16x32_bf16 v[100:103], v[154:157], v[194:197], v[100:103]
	v_mfma_f32_16x16x32_bf16 v[96:99], v[150:153], v[198:201], v[96:99]
	v_mfma_f32_16x16x32_bf16 v[96:99], v[154:157], v[202:205], v[96:99]
	s_setprio 0
	s_setprio 1
	v_mfma_f32_16x16x32_bf16 v[84:87], v[158:161], v[174:177], v[84:87]
	v_mfma_f32_16x16x32_bf16 v[84:87], v[162:165], v[178:181], v[84:87]
	v_mfma_f32_16x16x32_bf16 v[76:79], v[158:161], v[182:185], v[76:79]
	v_mfma_f32_16x16x32_bf16 v[76:79], v[162:165], v[186:189], v[76:79]
	v_mfma_f32_16x16x32_bf16 v[64:67], v[158:161], v[190:193], v[64:67]
	v_mfma_f32_16x16x32_bf16 v[64:67], v[162:165], v[194:197], v[64:67]
	v_mfma_f32_16x16x32_bf16 v[56:59], v[158:161], v[198:201], v[56:59]
	v_mfma_f32_16x16x32_bf16 v[56:59], v[162:165], v[202:205], v[56:59]
	v_mfma_f32_16x16x32_bf16 v[52:55], v[166:169], v[174:177], v[52:55]
	v_mfma_f32_16x16x32_bf16 v[52:55], v[170:173], v[178:181], v[52:55]
	v_mfma_f32_16x16x32_bf16 v[44:47], v[166:169], v[182:185], v[44:47]
	v_mfma_f32_16x16x32_bf16 v[44:47], v[170:173], v[186:189], v[44:47]
	v_mfma_f32_16x16x32_bf16 v[36:39], v[166:169], v[190:193], v[36:39]
	v_mfma_f32_16x16x32_bf16 v[36:39], v[170:173], v[194:197], v[36:39]
	v_mfma_f32_16x16x32_bf16 v[32:35], v[166:169], v[198:201], v[32:35]
	v_mfma_f32_16x16x32_bf16 v[32:35], v[170:173], v[202:205], v[32:35]
	s_setprio 0
	s_barrier
	s_nop 1
	s_add_i32 s2, s66, s41
	v_lshl_add_u64 v[138:139], v[138:139], 0, s[72:73]
	s_mov_b32 m0, s2
	ds_read_b128 v[174:177], v141 offset:49152
	ds_read_b128 v[178:181], v141 offset:50176
	ds_read_b128 v[182:185], v141 offset:51200
	ds_read_b128 v[186:189], v141 offset:52224
	ds_read_b128 v[190:193], v141 offset:53248
	ds_read_b128 v[194:197], v141 offset:54272
	ds_read_b128 v[198:201], v141 offset:55296
	ds_read_b128 v[202:205], v141 offset:56320
	global_load_lds_dwordx4 v[138:139], off
	s_add_i32 m0, s2, 0x2000
	s_add_u32 s2, s26, 0x80080
	v_lshl_add_u64 v[138:139], v[206:207], 0, s[72:73]
	s_addc_u32 s3, s27, 0
	s_add_i32 s26, s67, s41
	global_load_lds_dwordx4 v[138:139], off
	s_mov_b32 m0, s26
	s_nop 0
	global_load_lds_dwordx4 v212, s[2:3]
	s_add_i32 m0, s26, 0x2000
	s_nop 0
	global_load_lds_dwordx4 v128, s[2:3]
	v_lshl_add_u64 v[138:139], v[208:209], 0, s[72:73]
	s_mov_b32 m0, s54
	s_nop 0
	global_load_lds_dwordx4 v[138:139], off
	v_lshl_add_u64 v[138:139], v[210:211], 0, s[72:73]
	s_mov_b32 m0, s55
	s_nop 0
	global_load_lds_dwordx4 v[138:139], off
	s_waitcnt vmcnt(8)
	s_waitcnt lgkmcnt(0)
	s_barrier
	s_setprio 1
	s_waitcnt lgkmcnt(0)
	v_mfma_f32_16x16x32_bf16 v[92:95], v[142:145], v[174:177], v[92:95]
	v_mfma_f32_16x16x32_bf16 v[92:95], v[146:149], v[178:181], v[92:95]
	v_mfma_f32_16x16x32_bf16 v[88:91], v[142:145], v[182:185], v[88:91]
	v_mfma_f32_16x16x32_bf16 v[88:91], v[146:149], v[186:189], v[88:91]
	v_mfma_f32_16x16x32_bf16 v[80:83], v[142:145], v[190:193], v[80:83]
	v_mfma_f32_16x16x32_bf16 v[80:83], v[146:149], v[194:197], v[80:83]
	v_mfma_f32_16x16x32_bf16 v[72:75], v[142:145], v[198:201], v[72:75]
	v_mfma_f32_16x16x32_bf16 v[72:75], v[146:149], v[202:205], v[72:75]
	v_mfma_f32_16x16x32_bf16 v[68:71], v[150:153], v[174:177], v[68:71]
	v_mfma_f32_16x16x32_bf16 v[68:71], v[154:157], v[178:181], v[68:71]
	v_mfma_f32_16x16x32_bf16 v[60:63], v[150:153], v[182:185], v[60:63]
	v_mfma_f32_16x16x32_bf16 v[60:63], v[154:157], v[186:189], v[60:63]
	v_mfma_f32_16x16x32_bf16 v[48:51], v[150:153], v[190:193], v[48:51]
	v_mfma_f32_16x16x32_bf16 v[48:51], v[154:157], v[194:197], v[48:51]
	v_mfma_f32_16x16x32_bf16 v[40:43], v[150:153], v[198:201], v[40:43]
	v_mfma_f32_16x16x32_bf16 v[40:43], v[154:157], v[202:205], v[40:43]
	s_setprio 0
	s_setprio 1
	v_mfma_f32_16x16x32_bf16 v[28:31], v[158:161], v[174:177], v[28:31]
	v_mfma_f32_16x16x32_bf16 v[28:31], v[162:165], v[178:181], v[28:31]
	v_mfma_f32_16x16x32_bf16 v[24:27], v[158:161], v[182:185], v[24:27]
	v_mfma_f32_16x16x32_bf16 v[24:27], v[162:165], v[186:189], v[24:27]
	v_mfma_f32_16x16x32_bf16 v[20:23], v[158:161], v[190:193], v[20:23]
	v_mfma_f32_16x16x32_bf16 v[20:23], v[162:165], v[194:197], v[20:23]
	v_mfma_f32_16x16x32_bf16 v[16:19], v[158:161], v[198:201], v[16:19]
	v_mfma_f32_16x16x32_bf16 v[16:19], v[162:165], v[202:205], v[16:19]
	v_mfma_f32_16x16x32_bf16 v[12:15], v[166:169], v[174:177], v[12:15]
	v_mfma_f32_16x16x32_bf16 v[12:15], v[170:173], v[178:181], v[12:15]
	v_mfma_f32_16x16x32_bf16 v[8:11], v[166:169], v[182:185], v[8:11]
	v_mfma_f32_16x16x32_bf16 v[8:11], v[170:173], v[186:189], v[8:11]
	v_mfma_f32_16x16x32_bf16 v[4:7], v[166:169], v[190:193], v[4:7]
	v_mfma_f32_16x16x32_bf16 v[4:7], v[170:173], v[194:197], v[4:7]
	v_mfma_f32_16x16x32_bf16 v[0:3], v[166:169], v[198:201], v[0:3]
	v_mfma_f32_16x16x32_bf16 v[0:3], v[170:173], v[202:205], v[0:3]
	s_setprio 0
	s_barrier
	s_nop 1
	s_add_i32 s2, s17, 2
	s_add_u32 s24, s24, 0x100
	s_addc_u32 s25, s25, 0
	s_add_u32 s19, s19, 0x100
	s_addc_u32 s65, s65, 0
	s_cmp_gt_u32 s17, 29
	s_mov_b32 s17, s2
	s_cbranch_scc1 .LBB0_842

.LBB0_1238:
	s_ashr_i32 s63, s62, 31
	s_add_i32 s45, s19, -2
	s_lshl_b64 s[2:3], s[62:63], 20
	s_add_u32 s9, s33, s2
	s_addc_u32 s10, s65, s3
	s_and_b64 s[2:3], s[36:37], exec
	s_cselect_b32 s12, s10, s75
	s_cselect_b32 s13, s9, s74
	s_ashr_i32 s9, s8, 31
	s_lshl_b64 s[2:3], s[8:9], 20
	s_add_u32 s9, s67, s2
	s_addc_u32 s10, s68, s3
	s_and_b64 s[2:3], s[36:37], exec
	s_cselect_b32 s16, s10, s31
	s_cselect_b32 s9, s9, s30
	s_ashr_i32 s39, s38, 31
	s_lshl_b64 s[2:3], s[38:39], 7
	s_and_b64 s[10:11], s[36:37], exec
	s_cselect_b32 s2, s2, 0
	s_cselect_b32 s3, s3, 0
	s_add_u32 s10, s13, s2
	s_addc_u32 s11, s12, s3
	s_add_u32 s12, s9, s2
	s_mul_hi_i32 s2, s42, 0x78787879
	s_addc_u32 s13, s16, s3
	s_lshr_b32 s3, s2, 31
	s_ashr_i32 s2, s2, 3
	s_add_i32 s18, s2, s3
	s_mul_i32 s2, s18, 17
	s_lshl_b32 s16, s44, 8
	s_sub_i32 s2, s42, s2
	s_ashr_i32 s17, s16, 31
	s_cmp_lg_u32 s2, 0
	s_cselect_b32 s2, s18, 8
	s_ashr_i32 s3, s2, 31
	s_lshl_b64 s[20:21], s[2:3], 13
	s_cmp_lg_u32 s19, 32
	s_cselect_b64 s[22:23], -1, 0
	s_cmp_eq_u32 s19, 32
	s_mul_hi_i32 s9, s2, 0xc000
	s_mul_i32 s28, s2, 0xc000
	s_cselect_b64 s[2:3], -1, 0
	s_and_b64 s[24:25], s[56:57], s[2:3]
	s_add_u32 s2, s77, s20
	s_addc_u32 s3, s78, s21
	s_lshl_b64 s[20:21], s[16:17], 2
	s_add_u32 s26, s2, s20
	s_addc_u32 s27, s3, s21
	s_add_u32 s2, s71, s28
	s_addc_u32 s3, s76, s9
	s_add_u32 s28, s2, s20
	s_addc_u32 s29, s3, s21
	s_add_u32 s9, s30, 0x100
	s_addc_u32 s17, s31, 0
	s_add_u32 s2, s74, 0x80080
	s_addc_u32 s3, s75, 0
	s_mov_b32 s34, 0
	v_lshl_add_u64 v[96:97], s[2:3], 0, v[210:211]
	v_lshl_add_u64 v[98:99], s[2:3], 0, v[218:219]
	s_mov_b64 s[30:31], 0
	s_add_i32 s2, s34, 2
	s_add_u32 s3, s74, s30
	s_addc_u32 s35, s75, s31
	s_add_u32 s3, s3, 0x100
	s_addc_u32 s35, s35, 0
	s_add_u32 s39, s9, s30
	s_addc_u32 s63, s17, s31
	s_cmp_eq_u32 s45, s34
	s_cselect_b32 s89, s11, s35
	s_cselect_b32 s88, s10, s3
	s_cselect_b32 s35, s13, s63
	s_cselect_b32 s34, s12, s39
	s_add_i32 s3, 0, 0x10000
	s_add_i32 s39, 0, 0x14000
	v_add_u32_e32 v136, s3, v220
	v_add_u32_e32 v160, s39, v220
	ds_read_b128 v[108:111], v136
	ds_read_b128 v[120:123], v136 offset:1024
	ds_read_b128 v[132:135], v136 offset:2048
	ds_read_b128 v[136:139], v136 offset:3072
	ds_read_b128 v[140:143], v160
	ds_read_b128 v[144:147], v160 offset:1024
	ds_read_b128 v[148:151], v160 offset:2048
	ds_read_b128 v[160:163], v160 offset:3072
	v_lshl_add_u64 v[196:197], v[96:97], 0, s[30:31]
	s_add_i32 m0, s15, 0xc000
	ds_read_b128 v[164:167], v223
	ds_read_b128 v[168:171], v223 offset:1024
	ds_read_b128 v[172:175], v223 offset:2048
	ds_read_b128 v[176:179], v223 offset:3072
	ds_read_b128 v[180:183], v223 offset:4096
	ds_read_b128 v[184:187], v223 offset:5120
	ds_read_b128 v[188:191], v223 offset:6144
	ds_read_b128 v[192:195], v223 offset:7168
	global_load_lds_dwordx4 v[196:197], off
	v_lshl_add_u64 v[196:197], v[98:99], 0, s[30:31]
	s_add_i32 m0, s15, 0xe000
	s_nop 0
	global_load_lds_dwordx4 v[196:197], off
	s_waitcnt vmcnt(8)
	s_waitcnt lgkmcnt(0)
	s_barrier
	s_setprio 1
	s_waitcnt lgkmcnt(0)
	v_mfma_f32_16x16x32_bf16 v[156:159], v[108:111], v[164:167], 0
	v_mfma_f32_16x16x32_bf16 v[156:159], v[120:123], v[168:171], v[156:159]
	v_mfma_f32_16x16x32_bf16 v[128:131], v[108:111], v[172:175], 0
	v_mfma_f32_16x16x32_bf16 v[128:131], v[120:123], v[176:179], v[128:131]
	v_mfma_f32_16x16x32_bf16 v[116:119], v[108:111], v[180:183], 0
	v_mfma_f32_16x16x32_bf16 v[116:119], v[120:123], v[184:187], v[116:119]
	v_mfma_f32_16x16x32_bf16 v[104:107], v[108:111], v[188:191], 0
	v_mfma_f32_16x16x32_bf16 v[104:107], v[120:123], v[192:195], v[104:107]
	v_mfma_f32_16x16x32_bf16 v[152:155], v[132:135], v[164:167], 0
	v_mfma_f32_16x16x32_bf16 v[152:155], v[136:139], v[168:171], v[152:155]
	v_mfma_f32_16x16x32_bf16 v[124:127], v[132:135], v[172:175], 0
	v_mfma_f32_16x16x32_bf16 v[124:127], v[136:139], v[176:179], v[124:127]
	v_mfma_f32_16x16x32_bf16 v[112:115], v[132:135], v[180:183], 0
	v_mfma_f32_16x16x32_bf16 v[112:115], v[136:139], v[184:187], v[112:115]
	v_mfma_f32_16x16x32_bf16 v[100:103], v[132:135], v[188:191], 0
	v_mfma_f32_16x16x32_bf16 v[100:103], v[136:139], v[192:195], v[100:103]
	s_setprio 0
	s_setprio 1
	v_mfma_f32_16x16x32_bf16 v[92:95], v[140:143], v[164:167], 0
	v_mfma_f32_16x16x32_bf16 v[92:95], v[144:147], v[168:171], v[92:95]
	v_mfma_f32_16x16x32_bf16 v[84:87], v[140:143], v[172:175], 0
	v_mfma_f32_16x16x32_bf16 v[84:87], v[144:147], v[176:179], v[84:87]
	v_mfma_f32_16x16x32_bf16 v[76:79], v[140:143], v[180:183], 0
	v_mfma_f32_16x16x32_bf16 v[76:79], v[144:147], v[184:187], v[76:79]
	v_mfma_f32_16x16x32_bf16 v[68:71], v[140:143], v[188:191], 0
	v_mfma_f32_16x16x32_bf16 v[68:71], v[144:147], v[192:195], v[68:71]
	v_mfma_f32_16x16x32_bf16 v[88:91], v[148:151], v[164:167], 0
	v_mfma_f32_16x16x32_bf16 v[88:91], v[160:163], v[168:171], v[88:91]
	v_mfma_f32_16x16x32_bf16 v[80:83], v[148:151], v[172:175], 0
	v_mfma_f32_16x16x32_bf16 v[80:83], v[160:163], v[176:179], v[80:83]
	v_mfma_f32_16x16x32_bf16 v[72:75], v[148:151], v[180:183], 0
	v_mfma_f32_16x16x32_bf16 v[72:75], v[160:163], v[184:187], v[72:75]
	v_mfma_f32_16x16x32_bf16 v[64:67], v[148:151], v[188:191], 0
	v_mfma_f32_16x16x32_bf16 v[64:67], v[160:163], v[192:195], v[64:67]
	s_setprio 0
	s_barrier
	s_nop 1
	s_add_i32 s3, s3, s64
	v_lshl_add_u64 v[196:197], s[34:35], 0, v[212:213]
	s_mov_b32 m0, s3
	ds_read_b128 v[164:167], v223 offset:16384
	ds_read_b128 v[168:171], v223 offset:17408
	ds_read_b128 v[172:175], v223 offset:18432
	ds_read_b128 v[176:179], v223 offset:19456
	ds_read_b128 v[180:183], v223 offset:20480
	ds_read_b128 v[184:187], v223 offset:21504
	ds_read_b128 v[188:191], v223 offset:22528
	ds_read_b128 v[192:195], v223 offset:23552
	global_load_lds_dwordx4 v[196:197], off
	s_add_i32 m0, s3, 0x2000
	s_add_u32 vcc_lo, s34, 0x80000
	v_lshl_add_u64 v[198:199], s[34:35], 0, v[208:209]
	s_addc_u32 vcc_hi, s35, 0
	s_add_i32 s3, s39, s64
	global_load_lds_dwordx4 v[198:199], off
	v_lshl_add_u64 v[200:201], vcc, 0, v[212:213]
	s_mov_b32 m0, s3
	v_lshl_add_u64 v[202:203], s[88:89], 0, v[206:207]
	global_load_lds_dwordx4 v[200:201], off
	v_lshl_add_u64 v[200:201], vcc, 0, v[208:209]
	s_add_i32 m0, s3, 0x2000
	s_nop 0
	global_load_lds_dwordx4 v[200:201], off
	v_lshl_add_u64 v[200:201], s[88:89], 0, v[204:205]
	s_mov_b32 m0, s15
	s_nop 0
	global_load_lds_dwordx4 v[200:201], off
	s_mov_b32 m0, s43
	s_nop 0
	global_load_lds_dwordx4 v[202:203], off
	s_waitcnt vmcnt(8)
	s_waitcnt lgkmcnt(0)
	s_barrier
	s_setprio 1
	s_waitcnt lgkmcnt(0)
	v_mfma_f32_16x16x32_bf16 v[60:63], v[108:111], v[164:167], 0
	v_mfma_f32_16x16x32_bf16 v[60:63], v[120:123], v[168:171], v[60:63]
	v_mfma_f32_16x16x32_bf16 v[52:55], v[108:111], v[172:175], 0
	v_mfma_f32_16x16x32_bf16 v[52:55], v[120:123], v[176:179], v[52:55]
	v_mfma_f32_16x16x32_bf16 v[44:47], v[108:111], v[180:183], 0
	v_mfma_f32_16x16x32_bf16 v[44:47], v[120:123], v[184:187], v[44:47]
	v_mfma_f32_16x16x32_bf16 v[36:39], v[108:111], v[188:191], 0
	v_mfma_f32_16x16x32_bf16 v[36:39], v[120:123], v[192:195], v[36:39]
	v_mfma_f32_16x16x32_bf16 v[56:59], v[132:135], v[164:167], 0
	v_mfma_f32_16x16x32_bf16 v[56:59], v[136:139], v[168:171], v[56:59]
	v_mfma_f32_16x16x32_bf16 v[48:51], v[132:135], v[172:175], 0
	v_mfma_f32_16x16x32_bf16 v[48:51], v[136:139], v[176:179], v[48:51]
	v_mfma_f32_16x16x32_bf16 v[40:43], v[132:135], v[180:183], 0
	v_mfma_f32_16x16x32_bf16 v[40:43], v[136:139], v[184:187], v[40:43]
	v_mfma_f32_16x16x32_bf16 v[32:35], v[132:135], v[188:191], 0
	v_mfma_f32_16x16x32_bf16 v[32:35], v[136:139], v[192:195], v[32:35]
	s_setprio 0
	s_setprio 1
	v_mfma_f32_16x16x32_bf16 v[28:31], v[140:143], v[164:167], 0
	v_mfma_f32_16x16x32_bf16 v[28:31], v[144:147], v[168:171], v[28:31]
	v_mfma_f32_16x16x32_bf16 v[20:23], v[140:143], v[172:175], 0
	v_mfma_f32_16x16x32_bf16 v[20:23], v[144:147], v[176:179], v[20:23]
	v_mfma_f32_16x16x32_bf16 v[12:15], v[140:143], v[180:183], 0
	v_mfma_f32_16x16x32_bf16 v[12:15], v[144:147], v[184:187], v[12:15]
	v_mfma_f32_16x16x32_bf16 v[4:7], v[140:143], v[188:191], 0
	v_mfma_f32_16x16x32_bf16 v[4:7], v[144:147], v[192:195], v[4:7]
	v_mfma_f32_16x16x32_bf16 v[24:27], v[148:151], v[164:167], 0
	v_mfma_f32_16x16x32_bf16 v[24:27], v[160:163], v[168:171], v[24:27]
	v_mfma_f32_16x16x32_bf16 v[16:19], v[148:151], v[172:175], 0
	v_mfma_f32_16x16x32_bf16 v[16:19], v[160:163], v[176:179], v[16:19]
	v_mfma_f32_16x16x32_bf16 v[8:11], v[148:151], v[180:183], 0
	v_mfma_f32_16x16x32_bf16 v[8:11], v[160:163], v[184:187], v[8:11]
	v_mfma_f32_16x16x32_bf16 v[0:3], v[148:151], v[188:191], 0
	v_mfma_f32_16x16x32_bf16 v[0:3], v[160:163], v[192:195], v[0:3]
	s_setprio 0
	s_barrier
	s_nop 1
	s_add_i32 s3, 0, 0x18000
	s_add_i32 s39, 0, 0x1c000
	v_add_u32_e32 v136, s3, v220
	v_add_u32_e32 v160, s39, v220
	ds_read_b128 v[108:111], v136
	ds_read_b128 v[120:123], v136 offset:1024
	ds_read_b128 v[132:135], v136 offset:2048
	ds_read_b128 v[136:139], v136 offset:3072
	ds_read_b128 v[140:143], v160
	ds_read_b128 v[144:147], v160 offset:1024
	ds_read_b128 v[148:151], v160 offset:2048
	ds_read_b128 v[160:163], v160 offset:3072
	s_add_u32 s88, s88, 0x80000
	s_addc_u32 s89, s89, 0
	s_mov_b32 m0, s69
	ds_read_b128 v[164:167], v223 offset:32768
	ds_read_b128 v[168:171], v223 offset:33792
	ds_read_b128 v[172:175], v223 offset:34816
	ds_read_b128 v[176:179], v223 offset:35840
	ds_read_b128 v[180:183], v223 offset:36864
	ds_read_b128 v[184:187], v223 offset:37888
	ds_read_b128 v[188:191], v223 offset:38912
	ds_read_b128 v[192:195], v223 offset:39936
	global_load_lds_dwordx4 v204, s[88:89]
	v_lshl_add_u64 v[214:215], s[88:89], 0, v[206:207]
	s_mov_b32 m0, s70
	s_nop 0
	global_load_lds_dwordx4 v[214:215], off
	s_waitcnt vmcnt(8)
	s_waitcnt lgkmcnt(0)
	s_barrier
	s_setprio 1
	s_waitcnt lgkmcnt(0)
	v_mfma_f32_16x16x32_bf16 v[156:159], v[108:111], v[164:167], v[156:159]
	v_mfma_f32_16x16x32_bf16 v[156:159], v[120:123], v[168:171], v[156:159]
	v_mfma_f32_16x16x32_bf16 v[128:131], v[108:111], v[172:175], v[128:131]
	v_mfma_f32_16x16x32_bf16 v[128:131], v[120:123], v[176:179], v[128:131]
	v_mfma_f32_16x16x32_bf16 v[116:119], v[108:111], v[180:183], v[116:119]
	v_mfma_f32_16x16x32_bf16 v[116:119], v[120:123], v[184:187], v[116:119]
	v_mfma_f32_16x16x32_bf16 v[104:107], v[108:111], v[188:191], v[104:107]
	v_mfma_f32_16x16x32_bf16 v[104:107], v[120:123], v[192:195], v[104:107]
	v_mfma_f32_16x16x32_bf16 v[152:155], v[132:135], v[164:167], v[152:155]
	v_mfma_f32_16x16x32_bf16 v[152:155], v[136:139], v[168:171], v[152:155]
	v_mfma_f32_16x16x32_bf16 v[124:127], v[132:135], v[172:175], v[124:127]
	v_mfma_f32_16x16x32_bf16 v[124:127], v[136:139], v[176:179], v[124:127]
	v_mfma_f32_16x16x32_bf16 v[112:115], v[132:135], v[180:183], v[112:115]
	v_mfma_f32_16x16x32_bf16 v[112:115], v[136:139], v[184:187], v[112:115]
	v_mfma_f32_16x16x32_bf16 v[100:103], v[132:135], v[188:191], v[100:103]
	v_mfma_f32_16x16x32_bf16 v[100:103], v[136:139], v[192:195], v[100:103]
	s_setprio 0
	s_setprio 1
	v_mfma_f32_16x16x32_bf16 v[92:95], v[140:143], v[164:167], v[92:95]
	v_mfma_f32_16x16x32_bf16 v[92:95], v[144:147], v[168:171], v[92:95]
	v_mfma_f32_16x16x32_bf16 v[84:87], v[140:143], v[172:175], v[84:87]
	v_mfma_f32_16x16x32_bf16 v[84:87], v[144:147], v[176:179], v[84:87]
	v_mfma_f32_16x16x32_bf16 v[76:79], v[140:143], v[180:183], v[76:79]
	v_mfma_f32_16x16x32_bf16 v[76:79], v[144:147], v[184:187], v[76:79]
	v_mfma_f32_16x16x32_bf16 v[68:71], v[140:143], v[188:191], v[68:71]
	v_mfma_f32_16x16x32_bf16 v[68:71], v[144:147], v[192:195], v[68:71]
	v_mfma_f32_16x16x32_bf16 v[88:91], v[148:151], v[164:167], v[88:91]
	v_mfma_f32_16x16x32_bf16 v[88:91], v[160:163], v[168:171], v[88:91]
	v_mfma_f32_16x16x32_bf16 v[80:83], v[148:151], v[172:175], v[80:83]
	v_mfma_f32_16x16x32_bf16 v[80:83], v[160:163], v[176:179], v[80:83]
	v_mfma_f32_16x16x32_bf16 v[72:75], v[148:151], v[180:183], v[72:75]
	v_mfma_f32_16x16x32_bf16 v[72:75], v[160:163], v[184:187], v[72:75]
	v_mfma_f32_16x16x32_bf16 v[64:67], v[148:151], v[188:191], v[64:67]
	v_mfma_f32_16x16x32_bf16 v[64:67], v[160:163], v[192:195], v[64:67]
	s_setprio 0
	s_barrier
	s_nop 1
	s_add_i32 s3, s3, s64
	v_lshl_add_u64 v[196:197], v[196:197], 0, s[72:73]
	s_mov_b32 m0, s3
	ds_read_b128 v[164:167], v223 offset:49152
	ds_read_b128 v[168:171], v223 offset:50176
	ds_read_b128 v[172:175], v223 offset:51200
	ds_read_b128 v[176:179], v223 offset:52224
	ds_read_b128 v[180:183], v223 offset:53248
	ds_read_b128 v[184:187], v223 offset:54272
	ds_read_b128 v[188:191], v223 offset:55296
	ds_read_b128 v[192:195], v223 offset:56320
	global_load_lds_dwordx4 v[196:197], off
	s_add_i32 m0, s3, 0x2000
	s_add_u32 s34, s34, 0x80080
	v_lshl_add_u64 v[196:197], v[198:199], 0, s[72:73]
	s_addc_u32 s35, s35, 0
	s_add_i32 s3, s39, s64
	global_load_lds_dwordx4 v[196:197], off
	s_mov_b32 m0, s3
	s_nop 0
	global_load_lds_dwordx4 v212, s[34:35]
	s_add_i32 m0, s3, 0x2000
	s_nop 0
	global_load_lds_dwordx4 v208, s[34:35]
	v_lshl_add_u64 v[196:197], v[200:201], 0, s[72:73]
	s_mov_b32 m0, s83
	s_nop 0
	global_load_lds_dwordx4 v[196:197], off
	v_lshl_add_u64 v[196:197], v[202:203], 0, s[72:73]
	s_mov_b32 m0, s84
	s_nop 0
	global_load_lds_dwordx4 v[196:197], off
	s_waitcnt vmcnt(8)
	s_waitcnt lgkmcnt(0)
	s_barrier
	s_setprio 1
	s_waitcnt lgkmcnt(0)
	v_mfma_f32_16x16x32_bf16 v[60:63], v[108:111], v[164:167], v[60:63]
	v_mfma_f32_16x16x32_bf16 v[60:63], v[120:123], v[168:171], v[60:63]
	v_mfma_f32_16x16x32_bf16 v[52:55], v[108:111], v[172:175], v[52:55]
	v_mfma_f32_16x16x32_bf16 v[52:55], v[120:123], v[176:179], v[52:55]
	v_mfma_f32_16x16x32_bf16 v[44:47], v[108:111], v[180:183], v[44:47]
	v_mfma_f32_16x16x32_bf16 v[44:47], v[120:123], v[184:187], v[44:47]
	v_mfma_f32_16x16x32_bf16 v[36:39], v[108:111], v[188:191], v[36:39]
	v_mfma_f32_16x16x32_bf16 v[36:39], v[120:123], v[192:195], v[36:39]
	v_mfma_f32_16x16x32_bf16 v[56:59], v[132:135], v[164:167], v[56:59]
	v_mfma_f32_16x16x32_bf16 v[56:59], v[136:139], v[168:171], v[56:59]
	v_mfma_f32_16x16x32_bf16 v[48:51], v[132:135], v[172:175], v[48:51]
	v_mfma_f32_16x16x32_bf16 v[48:51], v[136:139], v[176:179], v[48:51]
	v_mfma_f32_16x16x32_bf16 v[40:43], v[132:135], v[180:183], v[40:43]
	v_mfma_f32_16x16x32_bf16 v[40:43], v[136:139], v[184:187], v[40:43]
	v_mfma_f32_16x16x32_bf16 v[32:35], v[132:135], v[188:191], v[32:35]
	v_mfma_f32_16x16x32_bf16 v[32:35], v[136:139], v[192:195], v[32:35]
	s_setprio 0
	s_setprio 1
	v_mfma_f32_16x16x32_bf16 v[28:31], v[140:143], v[164:167], v[28:31]
	v_mfma_f32_16x16x32_bf16 v[28:31], v[144:147], v[168:171], v[28:31]
	v_mfma_f32_16x16x32_bf16 v[20:23], v[140:143], v[172:175], v[20:23]
	v_mfma_f32_16x16x32_bf16 v[20:23], v[144:147], v[176:179], v[20:23]
	v_mfma_f32_16x16x32_bf16 v[12:15], v[140:143], v[180:183], v[12:15]
	v_mfma_f32_16x16x32_bf16 v[12:15], v[144:147], v[184:187], v[12:15]
	v_mfma_f32_16x16x32_bf16 v[4:7], v[140:143], v[188:191], v[4:7]
	v_mfma_f32_16x16x32_bf16 v[4:7], v[144:147], v[192:195], v[4:7]
	v_mfma_f32_16x16x32_bf16 v[24:27], v[148:151], v[164:167], v[24:27]
	v_mfma_f32_16x16x32_bf16 v[24:27], v[160:163], v[168:171], v[24:27]
	v_mfma_f32_16x16x32_bf16 v[16:19], v[148:151], v[172:175], v[16:19]
	v_mfma_f32_16x16x32_bf16 v[16:19], v[160:163], v[176:179], v[16:19]
	v_mfma_f32_16x16x32_bf16 v[8:11], v[148:151], v[180:183], v[8:11]
	v_mfma_f32_16x16x32_bf16 v[8:11], v[160:163], v[184:187], v[8:11]
	v_mfma_f32_16x16x32_bf16 v[0:3], v[148:151], v[188:191], v[0:3]
	v_mfma_f32_16x16x32_bf16 v[0:3], v[160:163], v[192:195], v[0:3]
	s_setprio 0
	s_barrier
	s_nop 1
	s_add_u32 s30, s30, 0x100
	s_addc_u32 s31, s31, 0
	s_cmp_ge_i32 s2, s19
	s_mov_b32 s34, s2
	s_cbranch_scc1 .LBB0_1246
	s_branch .LBB0_1240
.LBB0_1239:
	s_add_i32 s2, s34, 2
	s_add_u32 s3, s74, s30
	s_addc_u32 s35, s75, s31
	s_add_u32 s3, s3, 0x100
	s_addc_u32 s35, s35, 0
	s_add_u32 s39, s9, s30
	s_addc_u32 s63, s17, s31
	s_cmp_eq_u32 s45, s34
	s_cselect_b32 s89, s11, s35
	s_cselect_b32 s88, s10, s3
	s_cselect_b32 s35, s13, s63
	s_cselect_b32 s34, s12, s39
	s_add_i32 s3, 0, 0x10000
	s_add_i32 s39, 0, 0x14000
	v_add_u32_e32 v136, s3, v220
	v_add_u32_e32 v160, s39, v220
	ds_read_b128 v[108:111], v136
	ds_read_b128 v[120:123], v136 offset:1024
	ds_read_b128 v[132:135], v136 offset:2048
	ds_read_b128 v[136:139], v136 offset:3072
	ds_read_b128 v[140:143], v160
	ds_read_b128 v[144:147], v160 offset:1024
	ds_read_b128 v[148:151], v160 offset:2048
	ds_read_b128 v[160:163], v160 offset:3072
	v_lshl_add_u64 v[196:197], v[96:97], 0, s[30:31]
	s_add_i32 m0, s15, 0xc000
	ds_read_b128 v[164:167], v223
	ds_read_b128 v[168:171], v223 offset:1024
	ds_read_b128 v[172:175], v223 offset:2048
	ds_read_b128 v[176:179], v223 offset:3072
	ds_read_b128 v[180:183], v223 offset:4096
	ds_read_b128 v[184:187], v223 offset:5120
	ds_read_b128 v[188:191], v223 offset:6144
	ds_read_b128 v[192:195], v223 offset:7168
	global_load_lds_dwordx4 v[196:197], off
	v_lshl_add_u64 v[196:197], v[98:99], 0, s[30:31]
	s_add_i32 m0, s15, 0xe000
	s_nop 0
	global_load_lds_dwordx4 v[196:197], off
	s_waitcnt vmcnt(8)
	s_waitcnt lgkmcnt(0)
	s_barrier
	s_setprio 1
	s_waitcnt lgkmcnt(0)
	v_mfma_f32_16x16x32_bf16 v[156:159], v[108:111], v[164:167], v[156:159]
	v_mfma_f32_16x16x32_bf16 v[156:159], v[120:123], v[168:171], v[156:159]
	v_mfma_f32_16x16x32_bf16 v[128:131], v[108:111], v[172:175], v[128:131]
	v_mfma_f32_16x16x32_bf16 v[128:131], v[120:123], v[176:179], v[128:131]
	v_mfma_f32_16x16x32_bf16 v[116:119], v[108:111], v[180:183], v[116:119]
	v_mfma_f32_16x16x32_bf16 v[116:119], v[120:123], v[184:187], v[116:119]
	v_mfma_f32_16x16x32_bf16 v[104:107], v[108:111], v[188:191], v[104:107]
	v_mfma_f32_16x16x32_bf16 v[104:107], v[120:123], v[192:195], v[104:107]
	v_mfma_f32_16x16x32_bf16 v[152:155], v[132:135], v[164:167], v[152:155]
	v_mfma_f32_16x16x32_bf16 v[152:155], v[136:139], v[168:171], v[152:155]
	v_mfma_f32_16x16x32_bf16 v[124:127], v[132:135], v[172:175], v[124:127]
	v_mfma_f32_16x16x32_bf16 v[124:127], v[136:139], v[176:179], v[124:127]
	v_mfma_f32_16x16x32_bf16 v[112:115], v[132:135], v[180:183], v[112:115]
	v_mfma_f32_16x16x32_bf16 v[112:115], v[136:139], v[184:187], v[112:115]
	v_mfma_f32_16x16x32_bf16 v[100:103], v[132:135], v[188:191], v[100:103]
	v_mfma_f32_16x16x32_bf16 v[100:103], v[136:139], v[192:195], v[100:103]
	s_setprio 0
	s_setprio 1
	v_mfma_f32_16x16x32_bf16 v[92:95], v[140:143], v[164:167], v[92:95]
	v_mfma_f32_16x16x32_bf16 v[92:95], v[144:147], v[168:171], v[92:95]
	v_mfma_f32_16x16x32_bf16 v[84:87], v[140:143], v[172:175], v[84:87]
	v_mfma_f32_16x16x32_bf16 v[84:87], v[144:147], v[176:179], v[84:87]
	v_mfma_f32_16x16x32_bf16 v[76:79], v[140:143], v[180:183], v[76:79]
	v_mfma_f32_16x16x32_bf16 v[76:79], v[144:147], v[184:187], v[76:79]
	v_mfma_f32_16x16x32_bf16 v[68:71], v[140:143], v[188:191], v[68:71]
	v_mfma_f32_16x16x32_bf16 v[68:71], v[144:147], v[192:195], v[68:71]
	v_mfma_f32_16x16x32_bf16 v[88:91], v[148:151], v[164:167], v[88:91]
	v_mfma_f32_16x16x32_bf16 v[88:91], v[160:163], v[168:171], v[88:91]
	v_mfma_f32_16x16x32_bf16 v[80:83], v[148:151], v[172:175], v[80:83]
	v_mfma_f32_16x16x32_bf16 v[80:83], v[160:163], v[176:179], v[80:83]
	v_mfma_f32_16x16x32_bf16 v[72:75], v[148:151], v[180:183], v[72:75]
	v_mfma_f32_16x16x32_bf16 v[72:75], v[160:163], v[184:187], v[72:75]
	v_mfma_f32_16x16x32_bf16 v[64:67], v[148:151], v[188:191], v[64:67]
	v_mfma_f32_16x16x32_bf16 v[64:67], v[160:163], v[192:195], v[64:67]
	s_setprio 0
	s_barrier
	s_nop 1
	s_add_i32 s3, s3, s64
	v_lshl_add_u64 v[196:197], s[34:35], 0, v[212:213]
	s_mov_b32 m0, s3
	ds_read_b128 v[164:167], v223 offset:16384
	ds_read_b128 v[168:171], v223 offset:17408
	ds_read_b128 v[172:175], v223 offset:18432
	ds_read_b128 v[176:179], v223 offset:19456
	ds_read_b128 v[180:183], v223 offset:20480
	ds_read_b128 v[184:187], v223 offset:21504
	ds_read_b128 v[188:191], v223 offset:22528
	ds_read_b128 v[192:195], v223 offset:23552
	global_load_lds_dwordx4 v[196:197], off
	s_add_i32 m0, s3, 0x2000
	s_add_u32 vcc_lo, s34, 0x80000
	v_lshl_add_u64 v[198:199], s[34:35], 0, v[208:209]
	s_addc_u32 vcc_hi, s35, 0
	s_add_i32 s3, s39, s64
	global_load_lds_dwordx4 v[198:199], off
	v_lshl_add_u64 v[200:201], vcc, 0, v[212:213]
	s_mov_b32 m0, s3
	v_lshl_add_u64 v[202:203], s[88:89], 0, v[206:207]
	global_load_lds_dwordx4 v[200:201], off
	v_lshl_add_u64 v[200:201], vcc, 0, v[208:209]
	s_add_i32 m0, s3, 0x2000
	s_nop 0
	global_load_lds_dwordx4 v[200:201], off
	v_lshl_add_u64 v[200:201], s[88:89], 0, v[204:205]
	s_mov_b32 m0, s15
	s_nop 0
	global_load_lds_dwordx4 v[200:201], off
	s_mov_b32 m0, s43
	s_nop 0
	global_load_lds_dwordx4 v[202:203], off
	s_waitcnt vmcnt(8)
	s_waitcnt lgkmcnt(0)
	s_barrier
	s_setprio 1
	s_waitcnt lgkmcnt(0)
	v_mfma_f32_16x16x32_bf16 v[60:63], v[108:111], v[164:167], v[60:63]
	v_mfma_f32_16x16x32_bf16 v[60:63], v[120:123], v[168:171], v[60:63]
	v_mfma_f32_16x16x32_bf16 v[52:55], v[108:111], v[172:175], v[52:55]
	v_mfma_f32_16x16x32_bf16 v[52:55], v[120:123], v[176:179], v[52:55]
	v_mfma_f32_16x16x32_bf16 v[44:47], v[108:111], v[180:183], v[44:47]
	v_mfma_f32_16x16x32_bf16 v[44:47], v[120:123], v[184:187], v[44:47]
	v_mfma_f32_16x16x32_bf16 v[36:39], v[108:111], v[188:191], v[36:39]
	v_mfma_f32_16x16x32_bf16 v[36:39], v[120:123], v[192:195], v[36:39]
	v_mfma_f32_16x16x32_bf16 v[56:59], v[132:135], v[164:167], v[56:59]
	v_mfma_f32_16x16x32_bf16 v[56:59], v[136:139], v[168:171], v[56:59]
	v_mfma_f32_16x16x32_bf16 v[48:51], v[132:135], v[172:175], v[48:51]
	v_mfma_f32_16x16x32_bf16 v[48:51], v[136:139], v[176:179], v[48:51]
	v_mfma_f32_16x16x32_bf16 v[40:43], v[132:135], v[180:183], v[40:43]
	v_mfma_f32_16x16x32_bf16 v[40:43], v[136:139], v[184:187], v[40:43]
	v_mfma_f32_16x16x32_bf16 v[32:35], v[132:135], v[188:191], v[32:35]
	v_mfma_f32_16x16x32_bf16 v[32:35], v[136:139], v[192:195], v[32:35]
	s_setprio 0
	s_setprio 1
	v_mfma_f32_16x16x32_bf16 v[28:31], v[140:143], v[164:167], v[28:31]
	v_mfma_f32_16x16x32_bf16 v[28:31], v[144:147], v[168:171], v[28:31]
	v_mfma_f32_16x16x32_bf16 v[20:23], v[140:143], v[172:175], v[20:23]
	v_mfma_f32_16x16x32_bf16 v[20:23], v[144:147], v[176:179], v[20:23]
	v_mfma_f32_16x16x32_bf16 v[12:15], v[140:143], v[180:183], v[12:15]
	v_mfma_f32_16x16x32_bf16 v[12:15], v[144:147], v[184:187], v[12:15]
	v_mfma_f32_16x16x32_bf16 v[4:7], v[140:143], v[188:191], v[4:7]
	v_mfma_f32_16x16x32_bf16 v[4:7], v[144:147], v[192:195], v[4:7]
	v_mfma_f32_16x16x32_bf16 v[24:27], v[148:151], v[164:167], v[24:27]
	v_mfma_f32_16x16x32_bf16 v[24:27], v[160:163], v[168:171], v[24:27]
	v_mfma_f32_16x16x32_bf16 v[16:19], v[148:151], v[172:175], v[16:19]
	v_mfma_f32_16x16x32_bf16 v[16:19], v[160:163], v[176:179], v[16:19]
	v_mfma_f32_16x16x32_bf16 v[8:11], v[148:151], v[180:183], v[8:11]
	v_mfma_f32_16x16x32_bf16 v[8:11], v[160:163], v[184:187], v[8:11]
	v_mfma_f32_16x16x32_bf16 v[0:3], v[148:151], v[188:191], v[0:3]
	v_mfma_f32_16x16x32_bf16 v[0:3], v[160:163], v[192:195], v[0:3]
	s_setprio 0
	s_barrier
	s_nop 1
	s_add_i32 s3, 0, 0x18000
	s_add_i32 s39, 0, 0x1c000
	v_add_u32_e32 v136, s3, v220
	v_add_u32_e32 v160, s39, v220
	ds_read_b128 v[108:111], v136
	ds_read_b128 v[120:123], v136 offset:1024
	ds_read_b128 v[132:135], v136 offset:2048
	ds_read_b128 v[136:139], v136 offset:3072
	ds_read_b128 v[140:143], v160
	ds_read_b128 v[144:147], v160 offset:1024
	ds_read_b128 v[148:151], v160 offset:2048
	ds_read_b128 v[160:163], v160 offset:3072
	s_add_u32 s88, s88, 0x80000
	s_addc_u32 s89, s89, 0
	s_mov_b32 m0, s69
	ds_read_b128 v[164:167], v223 offset:32768
	ds_read_b128 v[168:171], v223 offset:33792
	ds_read_b128 v[172:175], v223 offset:34816
	ds_read_b128 v[176:179], v223 offset:35840
	ds_read_b128 v[180:183], v223 offset:36864
	ds_read_b128 v[184:187], v223 offset:37888
	ds_read_b128 v[188:191], v223 offset:38912
	ds_read_b128 v[192:195], v223 offset:39936
	global_load_lds_dwordx4 v204, s[88:89]
	v_lshl_add_u64 v[214:215], s[88:89], 0, v[206:207]
	s_mov_b32 m0, s70
	s_nop 0
	global_load_lds_dwordx4 v[214:215], off
	s_waitcnt vmcnt(8)
	s_waitcnt lgkmcnt(0)
	s_barrier
	s_setprio 1
	s_waitcnt lgkmcnt(0)
	v_mfma_f32_16x16x32_bf16 v[156:159], v[108:111], v[164:167], v[156:159]
	v_mfma_f32_16x16x32_bf16 v[156:159], v[120:123], v[168:171], v[156:159]
	v_mfma_f32_16x16x32_bf16 v[128:131], v[108:111], v[172:175], v[128:131]
	v_mfma_f32_16x16x32_bf16 v[128:131], v[120:123], v[176:179], v[128:131]
	v_mfma_f32_16x16x32_bf16 v[116:119], v[108:111], v[180:183], v[116:119]
	v_mfma_f32_16x16x32_bf16 v[116:119], v[120:123], v[184:187], v[116:119]
	v_mfma_f32_16x16x32_bf16 v[104:107], v[108:111], v[188:191], v[104:107]
	v_mfma_f32_16x16x32_bf16 v[104:107], v[120:123], v[192:195], v[104:107]
	v_mfma_f32_16x16x32_bf16 v[152:155], v[132:135], v[164:167], v[152:155]
	v_mfma_f32_16x16x32_bf16 v[152:155], v[136:139], v[168:171], v[152:155]
	v_mfma_f32_16x16x32_bf16 v[124:127], v[132:135], v[172:175], v[124:127]
	v_mfma_f32_16x16x32_bf16 v[124:127], v[136:139], v[176:179], v[124:127]
	v_mfma_f32_16x16x32_bf16 v[112:115], v[132:135], v[180:183], v[112:115]
	v_mfma_f32_16x16x32_bf16 v[112:115], v[136:139], v[184:187], v[112:115]
	v_mfma_f32_16x16x32_bf16 v[100:103], v[132:135], v[188:191], v[100:103]
	v_mfma_f32_16x16x32_bf16 v[100:103], v[136:139], v[192:195], v[100:103]
	s_setprio 0
	s_setprio 1
	v_mfma_f32_16x16x32_bf16 v[92:95], v[140:143], v[164:167], v[92:95]
	v_mfma_f32_16x16x32_bf16 v[92:95], v[144:147], v[168:171], v[92:95]
	v_mfma_f32_16x16x32_bf16 v[84:87], v[140:143], v[172:175], v[84:87]
	v_mfma_f32_16x16x32_bf16 v[84:87], v[144:147], v[176:179], v[84:87]
	v_mfma_f32_16x16x32_bf16 v[76:79], v[140:143], v[180:183], v[76:79]
	v_mfma_f32_16x16x32_bf16 v[76:79], v[144:147], v[184:187], v[76:79]
	v_mfma_f32_16x16x32_bf16 v[68:71], v[140:143], v[188:191], v[68:71]
	v_mfma_f32_16x16x32_bf16 v[68:71], v[144:147], v[192:195], v[68:71]
	v_mfma_f32_16x16x32_bf16 v[88:91], v[148:151], v[164:167], v[88:91]
	v_mfma_f32_16x16x32_bf16 v[88:91], v[160:163], v[168:171], v[88:91]
	v_mfma_f32_16x16x32_bf16 v[80:83], v[148:151], v[172:175], v[80:83]
	v_mfma_f32_16x16x32_bf16 v[80:83], v[160:163], v[176:179], v[80:83]
	v_mfma_f32_16x16x32_bf16 v[72:75], v[148:151], v[180:183], v[72:75]
	v_mfma_f32_16x16x32_bf16 v[72:75], v[160:163], v[184:187], v[72:75]
	v_mfma_f32_16x16x32_bf16 v[64:67], v[148:151], v[188:191], v[64:67]
	v_mfma_f32_16x16x32_bf16 v[64:67], v[160:163], v[192:195], v[64:67]
	s_setprio 0
	s_barrier
	s_nop 1
	s_add_i32 s3, s3, s64
	v_lshl_add_u64 v[196:197], v[196:197], 0, s[72:73]
	s_mov_b32 m0, s3
	ds_read_b128 v[164:167], v223 offset:49152
	ds_read_b128 v[168:171], v223 offset:50176
	ds_read_b128 v[172:175], v223 offset:51200
	ds_read_b128 v[176:179], v223 offset:52224
	ds_read_b128 v[180:183], v223 offset:53248
	ds_read_b128 v[184:187], v223 offset:54272
	ds_read_b128 v[188:191], v223 offset:55296
	ds_read_b128 v[192:195], v223 offset:56320
	global_load_lds_dwordx4 v[196:197], off
	s_add_i32 m0, s3, 0x2000
	s_add_u32 s34, s34, 0x80080
	v_lshl_add_u64 v[196:197], v[198:199], 0, s[72:73]
	s_addc_u32 s35, s35, 0
	s_add_i32 s3, s39, s64
	global_load_lds_dwordx4 v[196:197], off
	s_mov_b32 m0, s3
	s_nop 0
	global_load_lds_dwordx4 v212, s[34:35]
	s_add_i32 m0, s3, 0x2000
	s_nop 0
	global_load_lds_dwordx4 v208, s[34:35]
	v_lshl_add_u64 v[196:197], v[200:201], 0, s[72:73]
	s_mov_b32 m0, s83
	s_nop 0
	global_load_lds_dwordx4 v[196:197], off
	v_lshl_add_u64 v[196:197], v[202:203], 0, s[72:73]
	s_mov_b32 m0, s84
	s_nop 0
	global_load_lds_dwordx4 v[196:197], off
	s_waitcnt vmcnt(8)
	s_waitcnt lgkmcnt(0)
	s_barrier
	s_setprio 1
	s_waitcnt lgkmcnt(0)
	v_mfma_f32_16x16x32_bf16 v[60:63], v[108:111], v[164:167], v[60:63]
	v_mfma_f32_16x16x32_bf16 v[60:63], v[120:123], v[168:171], v[60:63]
	v_mfma_f32_16x16x32_bf16 v[52:55], v[108:111], v[172:175], v[52:55]
	v_mfma_f32_16x16x32_bf16 v[52:55], v[120:123], v[176:179], v[52:55]
	v_mfma_f32_16x16x32_bf16 v[44:47], v[108:111], v[180:183], v[44:47]
	v_mfma_f32_16x16x32_bf16 v[44:47], v[120:123], v[184:187], v[44:47]
	v_mfma_f32_16x16x32_bf16 v[36:39], v[108:111], v[188:191], v[36:39]
	v_mfma_f32_16x16x32_bf16 v[36:39], v[120:123], v[192:195], v[36:39]
	v_mfma_f32_16x16x32_bf16 v[56:59], v[132:135], v[164:167], v[56:59]
	v_mfma_f32_16x16x32_bf16 v[56:59], v[136:139], v[168:171], v[56:59]
	v_mfma_f32_16x16x32_bf16 v[48:51], v[132:135], v[172:175], v[48:51]
	v_mfma_f32_16x16x32_bf16 v[48:51], v[136:139], v[176:179], v[48:51]
	v_mfma_f32_16x16x32_bf16 v[40:43], v[132:135], v[180:183], v[40:43]
	v_mfma_f32_16x16x32_bf16 v[40:43], v[136:139], v[184:187], v[40:43]
	v_mfma_f32_16x16x32_bf16 v[32:35], v[132:135], v[188:191], v[32:35]
	v_mfma_f32_16x16x32_bf16 v[32:35], v[136:139], v[192:195], v[32:35]
	s_setprio 0
	s_setprio 1
	v_mfma_f32_16x16x32_bf16 v[28:31], v[140:143], v[164:167], v[28:31]
	v_mfma_f32_16x16x32_bf16 v[28:31], v[144:147], v[168:171], v[28:31]
	v_mfma_f32_16x16x32_bf16 v[20:23], v[140:143], v[172:175], v[20:23]
	v_mfma_f32_16x16x32_bf16 v[20:23], v[144:147], v[176:179], v[20:23]
	v_mfma_f32_16x16x32_bf16 v[12:15], v[140:143], v[180:183], v[12:15]
	v_mfma_f32_16x16x32_bf16 v[12:15], v[144:147], v[184:187], v[12:15]
	v_mfma_f32_16x16x32_bf16 v[4:7], v[140:143], v[188:191], v[4:7]
	v_mfma_f32_16x16x32_bf16 v[4:7], v[144:147], v[192:195], v[4:7]
	v_mfma_f32_16x16x32_bf16 v[24:27], v[148:151], v[164:167], v[24:27]
	v_mfma_f32_16x16x32_bf16 v[24:27], v[160:163], v[168:171], v[24:27]
	v_mfma_f32_16x16x32_bf16 v[16:19], v[148:151], v[172:175], v[16:19]
	v_mfma_f32_16x16x32_bf16 v[16:19], v[160:163], v[176:179], v[16:19]
	v_mfma_f32_16x16x32_bf16 v[8:11], v[148:151], v[180:183], v[8:11]
	v_mfma_f32_16x16x32_bf16 v[8:11], v[160:163], v[184:187], v[8:11]
	v_mfma_f32_16x16x32_bf16 v[0:3], v[148:151], v[188:191], v[0:3]
	v_mfma_f32_16x16x32_bf16 v[0:3], v[160:163], v[192:195], v[0:3]
	s_setprio 0
	s_barrier
	s_nop 1
	s_add_u32 s30, s30, 0x100
	s_addc_u32 s31, s31, 0
	s_cmp_ge_i32 s2, s19
	s_mov_b32 s34, s2
	s_cbranch_scc1 .LBB0_1246

.LBB0_1412:
	s_ashr_i32 s59, s58, 31
	s_lshl_b64 s[2:3], s[58:59], 20
	s_add_u32 s60, s31, s2
	s_addc_u32 s61, s35, s3
	s_and_b64 s[2:3], s[36:37], exec
	s_cselect_b32 s5, s61, s75
	s_cselect_b32 s59, s60, s74
	s_ashr_i32 s57, s56, 31
	s_lshl_b64 s[2:3], s[56:57], 20
	s_add_u32 s62, s49, s2
	s_addc_u32 s63, s66, s3
	s_and_b64 s[2:3], s[36:37], exec
	s_cselect_b32 s57, s63, s15
	s_cselect_b32 s30, s62, s14
	s_lshl_b32 s8, s10, 8
	s_ashr_i32 s9, s8, 31
	s_lshl_b64 s[2:3], s[8:9], 5
	s_mul_hi_i32 s9, s10, 0x78787879
	s_lshr_b32 s13, s9, 31
	s_ashr_i32 s9, s9, 3
	s_add_i32 s9, s9, s13
	s_mul_i32 s13, s9, 17
	s_lshl_b32 s18, s12, 8
	s_lshl_b32 s12, s12, 7
	s_sub_i32 s16, s10, s13
	s_ashr_i32 s19, s18, 31
	s_ashr_i32 s13, s12, 31
	s_mul_i32 s17, s9, 0xf400
	s_mul_hi_i32 s20, s9, 0xf400
	s_cmp_lg_u32 s16, 0
	s_cselect_b32 s21, s20, 0
	s_cselect_b32 s20, s17, 0x7a000
	s_add_u32 s16, s91, s2
	s_addc_u32 s17, s95, s3
	s_lshl_b64 s[2:3], s[20:21], 2
	s_add_u32 s20, s97, s2
	s_addc_u32 s21, s33, s3
	s_lshl_b64 s[2:3], s[18:19], 2
	s_add_u32 s18, s20, s2
	s_mov_b32 s9, 0
	s_addc_u32 s19, s21, s3
	s_lshl_b32 s2, s9, 7
	s_add_u32 s3, s74, s2
	s_addc_u32 s24, s75, 0
	s_add_u32 s20, s3, 0x100
	s_addc_u32 s21, s24, 0
	s_add_u32 s2, s14, s2
	s_addc_u32 s22, s15, 0
	s_add_u32 s2, s2, 0x100
	s_addc_u32 s25, s22, 0
	s_cmp_eq_u32 s9, 30
	s_cselect_b32 s23, s5, s21
	s_cselect_b32 s22, s59, s20
	s_cselect_b32 s21, s57, s25
	s_cselect_b32 s20, s30, s2
	s_add_i32 s25, 0, 0x10000
	s_add_i32 s26, 0, 0x14000
	v_add_u32_e32 v28, s25, v226
	v_add_u32_e32 v44, s26, v226
	ds_read_b128 v[16:19], v28
	ds_read_b128 v[20:23], v28 offset:1024
	ds_read_b128 v[24:27], v28 offset:2048
	ds_read_b128 v[28:31], v28 offset:3072
	ds_read_b128 v[32:35], v44
	ds_read_b128 v[36:39], v44 offset:1024
	ds_read_b128 v[40:43], v44 offset:2048
	ds_read_b128 v[44:47], v44 offset:3072
	s_add_u32 s2, s3, 0x80080
	s_addc_u32 s3, s24, 0
	s_add_i32 m0, s11, 0xc000
	ds_read_b128 v[48:51], v227
	ds_read_b128 v[52:55], v227 offset:1024
	ds_read_b128 v[56:59], v227 offset:2048
	ds_read_b128 v[60:63], v227 offset:3072
	ds_read_b128 v[136:139], v227 offset:4096
	ds_read_b128 v[140:143], v227 offset:5120
	ds_read_b128 v[144:147], v227 offset:6144
	ds_read_b128 v[148:151], v227 offset:7168
	global_load_lds_dwordx4 v218, s[2:3]
	v_lshl_add_u64 v[152:153], s[2:3], 0, v[222:223]
	s_add_i32 m0, s11, 0xe000
	s_nop 0
	global_load_lds_dwordx4 v[152:153], off
	s_waitcnt vmcnt(8)
	s_waitcnt lgkmcnt(0)
	s_barrier
	s_setprio 1
	s_waitcnt lgkmcnt(0)
	v_mfma_f32_16x16x32_bf16 v[152:155], v[16:19], v[48:51], 0
	v_mfma_f32_16x16x32_bf16 v[152:155], v[20:23], v[52:55], v[152:155]
	v_mfma_f32_16x16x32_bf16 v[160:163], v[16:19], v[56:59], 0
	v_mfma_f32_16x16x32_bf16 v[160:163], v[20:23], v[60:63], v[160:163]
	v_mfma_f32_16x16x32_bf16 v[108:111], v[16:19], v[136:139], 0
	v_mfma_f32_16x16x32_bf16 v[108:111], v[20:23], v[140:143], v[108:111]
	v_mfma_f32_16x16x32_bf16 v[164:167], v[16:19], v[144:147], 0
	v_mfma_f32_16x16x32_bf16 v[168:171], v[20:23], v[148:151], v[164:167]
	v_mfma_f32_16x16x32_bf16 v[64:67], v[24:27], v[48:51], 0
	v_mfma_f32_16x16x32_bf16 v[64:67], v[28:31], v[52:55], v[64:67]
	v_mfma_f32_16x16x32_bf16 v[156:159], v[24:27], v[56:59], 0
	v_mfma_f32_16x16x32_bf16 v[156:159], v[28:31], v[60:63], v[156:159]
	v_mfma_f32_16x16x32_bf16 v[104:107], v[24:27], v[136:139], 0
	v_mfma_f32_16x16x32_bf16 v[104:107], v[28:31], v[140:143], v[104:107]
	v_mfma_f32_16x16x32_bf16 v[68:71], v[24:27], v[144:147], 0
	v_mfma_f32_16x16x32_bf16 v[68:71], v[28:31], v[148:151], v[68:71]
	s_setprio 0
	s_setprio 1
	v_mfma_f32_16x16x32_bf16 v[88:91], v[32:35], v[48:51], 0
	v_mfma_f32_16x16x32_bf16 v[88:91], v[36:39], v[52:55], v[88:91]
	v_mfma_f32_16x16x32_bf16 v[48:51], v[40:43], v[48:51], 0
	v_mfma_f32_16x16x32_bf16 v[48:51], v[44:47], v[52:55], v[48:51]
	v_mfma_f32_16x16x32_bf16 v[72:75], v[40:43], v[136:139], 0
	v_mfma_f32_16x16x32_bf16 v[96:99], v[44:47], v[140:143], v[72:75]
	v_mfma_f32_16x16x32_bf16 v[72:75], v[32:35], v[144:147], 0
	v_mfma_f32_16x16x32_bf16 v[92:95], v[36:39], v[148:151], v[72:75]
	v_mfma_f32_16x16x32_bf16 v[52:55], v[32:35], v[56:59], 0
	v_mfma_f32_16x16x32_bf16 v[52:55], v[36:39], v[60:63], v[52:55]
	v_mfma_f32_16x16x32_bf16 v[56:59], v[40:43], v[56:59], 0
	v_mfma_f32_16x16x32_bf16 v[56:59], v[44:47], v[60:63], v[56:59]
	v_mfma_f32_16x16x32_bf16 v[72:75], v[40:43], v[144:147], 0
	v_mfma_f32_16x16x32_bf16 v[76:79], v[44:47], v[148:151], v[72:75]
	v_mfma_f32_16x16x32_bf16 v[60:63], v[32:35], v[136:139], 0
	v_mfma_f32_16x16x32_bf16 v[60:63], v[36:39], v[140:143], v[60:63]
	s_setprio 0
	s_barrier
	s_nop 1
	s_add_i32 s2, s25, s79
	v_lshl_add_u64 v[214:215], s[20:21], 0, v[220:221]
	s_mov_b32 m0, s2
	ds_read_b128 v[72:75], v227 offset:16384
	ds_read_b128 v[100:103], v227 offset:17408
	ds_read_b128 v[128:131], v227 offset:18432
	ds_read_b128 v[132:135], v227 offset:19456
	ds_read_b128 v[136:139], v227 offset:20480
	ds_read_b128 v[140:143], v227 offset:21504
	ds_read_b128 v[144:147], v227 offset:22528
	ds_read_b128 v[148:151], v227 offset:23552
	global_load_lds_dwordx4 v[214:215], off
	s_add_i32 m0, s2, 0x2000
	s_add_u32 s2, s20, 0x80000
	v_lshl_add_u64 v[216:217], s[20:21], 0, v[224:225]
	s_addc_u32 s3, s21, 0
	s_add_i32 s24, s26, s79
	global_load_lds_dwordx4 v[216:217], off
	s_mov_b32 m0, s24
	v_lshl_add_u64 v[230:231], s[22:23], 0, v[218:219]
	global_load_lds_dwordx4 v220, s[2:3]
	v_lshl_add_u64 v[164:165], s[2:3], 0, v[224:225]
	s_add_i32 m0, s24, 0x2000
	v_lshl_add_u64 v[232:233], s[22:23], 0, v[222:223]
	global_load_lds_dwordx4 v[164:165], off
	s_mov_b32 m0, s11
	s_nop 0
	global_load_lds_dwordx4 v[230:231], off
	s_mov_b32 m0, s88
	s_nop 0
	global_load_lds_dwordx4 v[232:233], off
	s_waitcnt vmcnt(8)
	s_waitcnt lgkmcnt(0)
	s_barrier
	s_setprio 1
	s_waitcnt lgkmcnt(0)
	v_mfma_f32_16x16x32_bf16 v[80:83], v[16:19], v[72:75], 0
	v_mfma_f32_16x16x32_bf16 v[80:83], v[20:23], v[100:103], v[80:83]
	v_mfma_f32_16x16x32_bf16 v[12:15], v[16:19], v[128:131], 0
	v_mfma_f32_16x16x32_bf16 v[12:15], v[20:23], v[132:135], v[12:15]
	v_mfma_f32_16x16x32_bf16 v[124:127], v[16:19], v[136:139], 0
	v_mfma_f32_16x16x32_bf16 v[124:127], v[20:23], v[140:143], v[124:127]
	v_mfma_f32_16x16x32_bf16 v[8:11], v[24:27], v[128:131], 0
	v_mfma_f32_16x16x32_bf16 v[8:11], v[28:31], v[132:135], v[8:11]
	v_mfma_f32_16x16x32_bf16 v[120:123], v[24:27], v[136:139], 0
	v_mfma_f32_16x16x32_bf16 v[120:123], v[28:31], v[140:143], v[120:123]
	v_mfma_f32_16x16x32_bf16 v[16:19], v[16:19], v[144:147], 0
	v_mfma_f32_16x16x32_bf16 v[16:19], v[20:23], v[148:151], v[16:19]
	v_mfma_f32_16x16x32_bf16 v[164:167], v[24:27], v[72:75], 0
	v_mfma_f32_16x16x32_bf16 v[176:179], v[28:31], v[100:103], v[164:167]
	v_mfma_f32_16x16x32_bf16 v[20:23], v[24:27], v[144:147], 0
	v_mfma_f32_16x16x32_bf16 v[20:23], v[28:31], v[148:151], v[20:23]
	s_setprio 0
	s_setprio 1
	v_mfma_f32_16x16x32_bf16 v[24:27], v[32:35], v[72:75], 0
	v_mfma_f32_16x16x32_bf16 v[24:27], v[36:39], v[100:103], v[24:27]
	v_mfma_f32_16x16x32_bf16 v[4:7], v[32:35], v[128:131], 0
	v_mfma_f32_16x16x32_bf16 v[4:7], v[36:39], v[132:135], v[4:7]
	v_mfma_f32_16x16x32_bf16 v[28:31], v[40:43], v[72:75], 0
	v_mfma_f32_16x16x32_bf16 v[28:31], v[44:47], v[100:103], v[28:31]
	v_mfma_f32_16x16x32_bf16 v[72:75], v[32:35], v[136:139], 0
	v_mfma_f32_16x16x32_bf16 v[116:119], v[36:39], v[140:143], v[72:75]
	v_mfma_f32_16x16x32_bf16 v[0:3], v[40:43], v[128:131], 0
	v_mfma_f32_16x16x32_bf16 v[0:3], v[44:47], v[132:135], v[0:3]
	v_mfma_f32_16x16x32_bf16 v[72:75], v[40:43], v[136:139], 0
	v_mfma_f32_16x16x32_bf16 v[112:115], v[44:47], v[140:143], v[72:75]
	v_mfma_f32_16x16x32_bf16 v[32:35], v[32:35], v[144:147], 0
	v_mfma_f32_16x16x32_bf16 v[32:35], v[36:39], v[148:151], v[32:35]
	v_mfma_f32_16x16x32_bf16 v[36:39], v[40:43], v[144:147], 0
	v_mfma_f32_16x16x32_bf16 v[36:39], v[44:47], v[148:151], v[36:39]
	s_setprio 0
	s_barrier
	s_nop 1
	s_add_i32 s24, 0, 0x18000
	v_add_u32_e32 v72, s24, v226
	s_add_i32 s25, 0, 0x1c000
	ds_read_b128 v[40:43], v72
	ds_read_b128 v[44:47], v72 offset:1024
	ds_read_b128 v[136:139], v72 offset:2048
	ds_read_b128 v[140:143], v72 offset:3072
	v_add_u32_e32 v72, s25, v226
	ds_read_b128 v[144:147], v72
	ds_read_b128 v[148:151], v72 offset:1024
	ds_read_b128 v[184:187], v72 offset:2048
	ds_read_b128 v[192:195], v72 offset:3072
	s_add_u32 s2, s22, 0x80000
	s_addc_u32 s3, s23, 0
	s_mov_b32 m0, s89
	ds_read_b128 v[72:75], v227 offset:32768
	ds_read_b128 v[84:87], v227 offset:33792
	ds_read_b128 v[100:103], v227 offset:34816
	ds_read_b128 v[128:131], v227 offset:35840
	ds_read_b128 v[172:175], v227 offset:36864
	ds_read_b128 v[180:183], v227 offset:37888
	ds_read_b128 v[188:191], v227 offset:38912
	ds_read_b128 v[196:199], v227 offset:39936
	global_load_lds_dwordx4 v218, s[2:3]
	v_lshl_add_u64 v[132:133], s[2:3], 0, v[222:223]
	s_mov_b32 m0, s76
	s_nop 0
	global_load_lds_dwordx4 v[132:133], off
	s_waitcnt vmcnt(8)
	s_waitcnt lgkmcnt(0)
	s_barrier
	s_setprio 1
	s_waitcnt lgkmcnt(0)
	v_mfma_f32_16x16x32_bf16 v[132:135], v[40:43], v[72:75], v[152:155]
	v_mfma_f32_16x16x32_bf16 v[164:167], v[44:47], v[84:87], v[132:135]
	v_mfma_f32_16x16x32_bf16 v[108:111], v[40:43], v[172:175], v[108:111]
	v_mfma_f32_16x16x32_bf16 v[108:111], v[44:47], v[180:183], v[108:111]
	v_mfma_f32_16x16x32_bf16 v[132:135], v[40:43], v[100:103], v[160:163]
	v_mfma_f32_16x16x32_bf16 v[160:163], v[44:47], v[128:131], v[132:135]
	v_mfma_f32_16x16x32_bf16 v[132:135], v[136:139], v[100:103], v[156:159]
	v_mfma_f32_16x16x32_bf16 v[156:159], v[140:143], v[128:131], v[132:135]
	v_mfma_f32_16x16x32_bf16 v[132:135], v[40:43], v[188:191], v[168:171]
	v_mfma_f32_16x16x32_bf16 v[168:171], v[44:47], v[196:199], v[132:135]
	v_mfma_f32_16x16x32_bf16 v[64:67], v[136:139], v[72:75], v[64:67]
	v_mfma_f32_16x16x32_bf16 v[64:67], v[140:143], v[84:87], v[64:67]
	v_mfma_f32_16x16x32_bf16 v[104:107], v[136:139], v[172:175], v[104:107]
	v_mfma_f32_16x16x32_bf16 v[104:107], v[140:143], v[180:183], v[104:107]
	v_mfma_f32_16x16x32_bf16 v[68:71], v[136:139], v[188:191], v[68:71]
	v_mfma_f32_16x16x32_bf16 v[68:71], v[140:143], v[196:199], v[68:71]
	s_setprio 0
	s_setprio 1
	v_mfma_f32_16x16x32_bf16 v[48:51], v[184:187], v[72:75], v[48:51]
	v_mfma_f32_16x16x32_bf16 v[88:91], v[144:147], v[72:75], v[88:91]
	v_mfma_f32_16x16x32_bf16 v[88:91], v[148:151], v[84:87], v[88:91]
	v_mfma_f32_16x16x32_bf16 v[72:75], v[192:195], v[84:87], v[48:51]
	v_mfma_f32_16x16x32_bf16 v[48:51], v[144:147], v[100:103], v[52:55]
	v_mfma_f32_16x16x32_bf16 v[132:135], v[148:151], v[128:131], v[48:51]
	v_mfma_f32_16x16x32_bf16 v[48:51], v[184:187], v[100:103], v[56:59]
	v_mfma_f32_16x16x32_bf16 v[128:131], v[192:195], v[128:131], v[48:51]
	v_mfma_f32_16x16x32_bf16 v[48:51], v[144:147], v[172:175], v[60:63]
	v_mfma_f32_16x16x32_bf16 v[100:103], v[148:151], v[180:183], v[48:51]
	v_mfma_f32_16x16x32_bf16 v[48:51], v[184:187], v[172:175], v[96:99]
	v_mfma_f32_16x16x32_bf16 v[96:99], v[192:195], v[180:183], v[48:51]
	v_mfma_f32_16x16x32_bf16 v[48:51], v[144:147], v[188:191], v[92:95]
	v_mfma_f32_16x16x32_bf16 v[92:95], v[148:151], v[196:199], v[48:51]
	v_mfma_f32_16x16x32_bf16 v[48:51], v[184:187], v[188:191], v[76:79]
	v_mfma_f32_16x16x32_bf16 v[76:79], v[192:195], v[196:199], v[48:51]
	s_setprio 0
	s_barrier
	s_nop 1
	s_add_i32 s2, s24, s79
	v_lshl_add_u64 v[84:85], v[214:215], 0, s[72:73]
	s_mov_b32 m0, s2
	s_nop 0
	ds_read_b128 v[48:51], v227 offset:49152
	ds_read_b128 v[52:55], v227 offset:50176
	ds_read_b128 v[56:59], v227 offset:51200
	ds_read_b128 v[60:63], v227 offset:52224
	ds_read_b128 v[152:155], v227 offset:53248
	ds_read_b128 v[180:183], v227 offset:54272
	ds_read_b128 v[204:207], v227 offset:55296
	ds_read_b128 v[208:211], v227 offset:56320
	global_load_lds_dwordx4 v[84:85], off
	s_add_i32 m0, s2, 0x2000
	s_add_u32 s2, s20, 0x80080
	v_lshl_add_u64 v[84:85], v[216:217], 0, s[72:73]
	s_addc_u32 s3, s21, 0
	s_add_i32 s20, s25, s79
	global_load_lds_dwordx4 v[84:85], off
	s_mov_b32 m0, s20
	s_nop 0
	global_load_lds_dwordx4 v220, s[2:3]
	s_add_i32 m0, s20, 0x2000
	s_nop 0
	global_load_lds_dwordx4 v224, s[2:3]
	v_lshl_add_u64 v[84:85], v[230:231], 0, s[72:73]
	s_mov_b32 m0, s67
	s_nop 0
	global_load_lds_dwordx4 v[84:85], off
	v_lshl_add_u64 v[84:85], v[232:233], 0, s[72:73]
	s_mov_b32 m0, s84
	s_nop 0
	global_load_lds_dwordx4 v[84:85], off
	s_waitcnt vmcnt(8)
	s_waitcnt lgkmcnt(0)
	s_barrier
	s_setprio 1
	s_waitcnt lgkmcnt(0)
	v_mfma_f32_16x16x32_bf16 v[84:87], v[136:139], v[48:51], v[176:179]
	v_mfma_f32_16x16x32_bf16 v[196:199], v[140:143], v[52:55], v[84:87]
	v_mfma_f32_16x16x32_bf16 v[12:15], v[40:43], v[56:59], v[12:15]
	v_mfma_f32_16x16x32_bf16 v[12:15], v[44:47], v[60:63], v[12:15]
	v_mfma_f32_16x16x32_bf16 v[84:87], v[40:43], v[152:155], v[124:127]
	v_mfma_f32_16x16x32_bf16 v[124:127], v[44:47], v[180:183], v[84:87]
	v_mfma_f32_16x16x32_bf16 v[84:87], v[136:139], v[152:155], v[120:123]
	v_mfma_f32_16x16x32_bf16 v[120:123], v[140:143], v[180:183], v[84:87]
	v_mfma_f32_16x16x32_bf16 v[16:19], v[40:43], v[204:207], v[16:19]
	v_mfma_f32_16x16x32_bf16 v[84:87], v[44:47], v[208:211], v[16:19]
	v_mfma_f32_16x16x32_bf16 v[80:83], v[40:43], v[48:51], v[80:83]
	v_mfma_f32_16x16x32_bf16 v[80:83], v[44:47], v[52:55], v[80:83]
	v_mfma_f32_16x16x32_bf16 v[8:11], v[136:139], v[56:59], v[8:11]
	v_mfma_f32_16x16x32_bf16 v[8:11], v[140:143], v[60:63], v[8:11]
	v_mfma_f32_16x16x32_bf16 v[16:19], v[136:139], v[204:207], v[20:23]
	v_mfma_f32_16x16x32_bf16 v[200:203], v[140:143], v[208:211], v[16:19]
	s_setprio 0
	s_setprio 1
	v_mfma_f32_16x16x32_bf16 v[4:7], v[144:147], v[56:59], v[4:7]
	v_mfma_f32_16x16x32_bf16 v[4:7], v[148:151], v[60:63], v[4:7]
	v_mfma_f32_16x16x32_bf16 v[16:19], v[144:147], v[48:51], v[24:27]
	v_mfma_f32_16x16x32_bf16 v[172:175], v[148:151], v[52:55], v[16:19]
	v_mfma_f32_16x16x32_bf16 v[16:19], v[184:187], v[48:51], v[28:31]
	v_mfma_f32_16x16x32_bf16 v[188:191], v[192:195], v[52:55], v[16:19]
	v_mfma_f32_16x16x32_bf16 v[16:19], v[144:147], v[152:155], v[116:119]
	v_mfma_f32_16x16x32_bf16 v[116:119], v[148:151], v[180:183], v[16:19]
	v_mfma_f32_16x16x32_bf16 v[16:19], v[184:187], v[152:155], v[112:115]
	v_mfma_f32_16x16x32_bf16 v[112:115], v[192:195], v[180:183], v[16:19]
	v_mfma_f32_16x16x32_bf16 v[16:19], v[144:147], v[204:207], v[32:35]
	v_mfma_f32_16x16x32_bf16 v[180:183], v[148:151], v[208:211], v[16:19]
	v_mfma_f32_16x16x32_bf16 v[0:3], v[184:187], v[56:59], v[0:3]
	v_mfma_f32_16x16x32_bf16 v[0:3], v[192:195], v[60:63], v[0:3]
	v_mfma_f32_16x16x32_bf16 v[16:19], v[184:187], v[204:207], v[36:39]
	v_mfma_f32_16x16x32_bf16 v[192:195], v[192:195], v[208:211], v[16:19]
	s_setprio 0
	s_barrier
	s_nop 1
	s_add_i32 s2, s9, 2
	s_cmp_gt_u32 s9, 29
	s_mov_b32 s9, s2
	s_cbranch_scc1 .LBB0_1436
	s_branch .LBB0_1414
.LBB0_1413:
	s_lshl_b32 s2, s9, 7
	s_add_u32 s3, s74, s2
	s_addc_u32 s24, s75, 0
	s_add_u32 s20, s3, 0x100
	s_addc_u32 s21, s24, 0
	s_add_u32 s2, s14, s2
	s_addc_u32 s22, s15, 0
	s_add_u32 s2, s2, 0x100
	s_addc_u32 s25, s22, 0
	s_cmp_eq_u32 s9, 30
	s_cselect_b32 s23, s5, s21
	s_cselect_b32 s22, s59, s20
	s_cselect_b32 s21, s57, s25
	s_cselect_b32 s20, s30, s2
	s_add_i32 s25, 0, 0x10000
	s_add_i32 s26, 0, 0x14000
	v_add_u32_e32 v28, s25, v226
	v_add_u32_e32 v44, s26, v226
	ds_read_b128 v[16:19], v28
	ds_read_b128 v[20:23], v28 offset:1024
	ds_read_b128 v[24:27], v28 offset:2048
	ds_read_b128 v[28:31], v28 offset:3072
	ds_read_b128 v[32:35], v44
	ds_read_b128 v[36:39], v44 offset:1024
	ds_read_b128 v[40:43], v44 offset:2048
	ds_read_b128 v[44:47], v44 offset:3072
	s_add_u32 s2, s3, 0x80080
	s_addc_u32 s3, s24, 0
	s_add_i32 m0, s11, 0xc000
	ds_read_b128 v[48:51], v227
	ds_read_b128 v[52:55], v227 offset:1024
	ds_read_b128 v[56:59], v227 offset:2048
	ds_read_b128 v[60:63], v227 offset:3072
	ds_read_b128 v[136:139], v227 offset:4096
	ds_read_b128 v[140:143], v227 offset:5120
	ds_read_b128 v[144:147], v227 offset:6144
	ds_read_b128 v[148:151], v227 offset:7168
	global_load_lds_dwordx4 v218, s[2:3]
	v_lshl_add_u64 v[152:153], s[2:3], 0, v[222:223]
	s_add_i32 m0, s11, 0xe000
	s_nop 0
	global_load_lds_dwordx4 v[152:153], off
	s_waitcnt vmcnt(8)
	s_waitcnt lgkmcnt(0)
	s_barrier
	s_setprio 1
	s_waitcnt lgkmcnt(0)
	v_mfma_f32_16x16x32_bf16 v[152:155], v[16:19], v[48:51], v[164:167]
	v_mfma_f32_16x16x32_bf16 v[152:155], v[20:23], v[52:55], v[152:155]
	v_mfma_f32_16x16x32_bf16 v[160:163], v[16:19], v[56:59], v[160:163]
	v_mfma_f32_16x16x32_bf16 v[160:163], v[20:23], v[60:63], v[160:163]
	v_mfma_f32_16x16x32_bf16 v[108:111], v[16:19], v[136:139], v[108:111]
	v_mfma_f32_16x16x32_bf16 v[108:111], v[20:23], v[140:143], v[108:111]
	v_mfma_f32_16x16x32_bf16 v[164:167], v[16:19], v[144:147], v[168:171]
	v_mfma_f32_16x16x32_bf16 v[168:171], v[20:23], v[148:151], v[164:167]
	v_mfma_f32_16x16x32_bf16 v[64:67], v[24:27], v[48:51], v[64:67]
	v_mfma_f32_16x16x32_bf16 v[64:67], v[28:31], v[52:55], v[64:67]
	v_mfma_f32_16x16x32_bf16 v[156:159], v[24:27], v[56:59], v[156:159]
	v_mfma_f32_16x16x32_bf16 v[156:159], v[28:31], v[60:63], v[156:159]
	v_mfma_f32_16x16x32_bf16 v[104:107], v[24:27], v[136:139], v[104:107]
	v_mfma_f32_16x16x32_bf16 v[104:107], v[28:31], v[140:143], v[104:107]
	v_mfma_f32_16x16x32_bf16 v[68:71], v[24:27], v[144:147], v[68:71]
	v_mfma_f32_16x16x32_bf16 v[68:71], v[28:31], v[148:151], v[68:71]
	s_setprio 0
	s_setprio 1
	v_mfma_f32_16x16x32_bf16 v[88:91], v[32:35], v[48:51], v[88:91]
	v_mfma_f32_16x16x32_bf16 v[88:91], v[36:39], v[52:55], v[88:91]
	v_mfma_f32_16x16x32_bf16 v[48:51], v[40:43], v[48:51], v[72:75]
	v_mfma_f32_16x16x32_bf16 v[48:51], v[44:47], v[52:55], v[48:51]
	v_mfma_f32_16x16x32_bf16 v[72:75], v[40:43], v[136:139], v[96:99]
	v_mfma_f32_16x16x32_bf16 v[96:99], v[44:47], v[140:143], v[72:75]
	v_mfma_f32_16x16x32_bf16 v[72:75], v[32:35], v[144:147], v[92:95]
	v_mfma_f32_16x16x32_bf16 v[92:95], v[36:39], v[148:151], v[72:75]
	v_mfma_f32_16x16x32_bf16 v[52:55], v[32:35], v[56:59], v[132:135]
	v_mfma_f32_16x16x32_bf16 v[52:55], v[36:39], v[60:63], v[52:55]
	v_mfma_f32_16x16x32_bf16 v[56:59], v[40:43], v[56:59], v[128:131]
	v_mfma_f32_16x16x32_bf16 v[56:59], v[44:47], v[60:63], v[56:59]
	v_mfma_f32_16x16x32_bf16 v[72:75], v[40:43], v[144:147], v[76:79]
	v_mfma_f32_16x16x32_bf16 v[76:79], v[44:47], v[148:151], v[72:75]
	v_mfma_f32_16x16x32_bf16 v[60:63], v[32:35], v[136:139], v[100:103]
	v_mfma_f32_16x16x32_bf16 v[60:63], v[36:39], v[140:143], v[60:63]
	s_setprio 0
	s_barrier
	s_nop 1
	s_add_i32 s2, s25, s79
	v_lshl_add_u64 v[214:215], s[20:21], 0, v[220:221]
	s_mov_b32 m0, s2
	ds_read_b128 v[72:75], v227 offset:16384
	ds_read_b128 v[100:103], v227 offset:17408
	ds_read_b128 v[128:131], v227 offset:18432
	ds_read_b128 v[132:135], v227 offset:19456
	ds_read_b128 v[136:139], v227 offset:20480
	ds_read_b128 v[140:143], v227 offset:21504
	ds_read_b128 v[144:147], v227 offset:22528
	ds_read_b128 v[148:151], v227 offset:23552
	global_load_lds_dwordx4 v[214:215], off
	s_add_i32 m0, s2, 0x2000
	s_add_u32 s2, s20, 0x80000
	v_lshl_add_u64 v[216:217], s[20:21], 0, v[224:225]
	s_addc_u32 s3, s21, 0
	s_add_i32 s24, s26, s79
	global_load_lds_dwordx4 v[216:217], off
	s_mov_b32 m0, s24
	v_lshl_add_u64 v[230:231], s[22:23], 0, v[218:219]
	global_load_lds_dwordx4 v220, s[2:3]
	v_lshl_add_u64 v[164:165], s[2:3], 0, v[224:225]
	s_add_i32 m0, s24, 0x2000
	v_lshl_add_u64 v[232:233], s[22:23], 0, v[222:223]
	global_load_lds_dwordx4 v[164:165], off
	s_mov_b32 m0, s11
	s_nop 0
	global_load_lds_dwordx4 v[230:231], off
	s_mov_b32 m0, s88
	s_nop 0
	global_load_lds_dwordx4 v[232:233], off
	s_waitcnt vmcnt(8)
	s_waitcnt lgkmcnt(0)
	s_barrier
	s_setprio 1
	s_waitcnt lgkmcnt(0)
	v_mfma_f32_16x16x32_bf16 v[80:83], v[16:19], v[72:75], v[80:83]
	v_mfma_f32_16x16x32_bf16 v[80:83], v[20:23], v[100:103], v[80:83]
	v_mfma_f32_16x16x32_bf16 v[12:15], v[16:19], v[128:131], v[12:15]
	v_mfma_f32_16x16x32_bf16 v[12:15], v[20:23], v[132:135], v[12:15]
	v_mfma_f32_16x16x32_bf16 v[124:127], v[16:19], v[136:139], v[124:127]
	v_mfma_f32_16x16x32_bf16 v[124:127], v[20:23], v[140:143], v[124:127]
	v_mfma_f32_16x16x32_bf16 v[8:11], v[24:27], v[128:131], v[8:11]
	v_mfma_f32_16x16x32_bf16 v[8:11], v[28:31], v[132:135], v[8:11]
	v_mfma_f32_16x16x32_bf16 v[120:123], v[24:27], v[136:139], v[120:123]
	v_mfma_f32_16x16x32_bf16 v[120:123], v[28:31], v[140:143], v[120:123]
	v_mfma_f32_16x16x32_bf16 v[16:19], v[16:19], v[144:147], v[84:87]
	v_mfma_f32_16x16x32_bf16 v[16:19], v[20:23], v[148:151], v[16:19]
	v_mfma_f32_16x16x32_bf16 v[164:167], v[24:27], v[72:75], v[196:199]
	v_mfma_f32_16x16x32_bf16 v[176:179], v[28:31], v[100:103], v[164:167]
	v_mfma_f32_16x16x32_bf16 v[20:23], v[24:27], v[144:147], v[200:203]
	v_mfma_f32_16x16x32_bf16 v[20:23], v[28:31], v[148:151], v[20:23]
	s_setprio 0
	s_setprio 1
	v_mfma_f32_16x16x32_bf16 v[24:27], v[32:35], v[72:75], v[172:175]
	v_mfma_f32_16x16x32_bf16 v[24:27], v[36:39], v[100:103], v[24:27]
	v_mfma_f32_16x16x32_bf16 v[4:7], v[32:35], v[128:131], v[4:7]
	v_mfma_f32_16x16x32_bf16 v[4:7], v[36:39], v[132:135], v[4:7]
	v_mfma_f32_16x16x32_bf16 v[28:31], v[40:43], v[72:75], v[188:191]
	v_mfma_f32_16x16x32_bf16 v[28:31], v[44:47], v[100:103], v[28:31]
	v_mfma_f32_16x16x32_bf16 v[72:75], v[32:35], v[136:139], v[116:119]
	v_mfma_f32_16x16x32_bf16 v[116:119], v[36:39], v[140:143], v[72:75]
	v_mfma_f32_16x16x32_bf16 v[0:3], v[40:43], v[128:131], v[0:3]
	v_mfma_f32_16x16x32_bf16 v[0:3], v[44:47], v[132:135], v[0:3]
	v_mfma_f32_16x16x32_bf16 v[72:75], v[40:43], v[136:139], v[112:115]
	v_mfma_f32_16x16x32_bf16 v[112:115], v[44:47], v[140:143], v[72:75]
	v_mfma_f32_16x16x32_bf16 v[32:35], v[32:35], v[144:147], v[180:183]
	v_mfma_f32_16x16x32_bf16 v[32:35], v[36:39], v[148:151], v[32:35]
	v_mfma_f32_16x16x32_bf16 v[36:39], v[40:43], v[144:147], v[192:195]
	v_mfma_f32_16x16x32_bf16 v[36:39], v[44:47], v[148:151], v[36:39]
	s_setprio 0
	s_barrier
	s_nop 1
	s_add_i32 s24, 0, 0x18000
	v_add_u32_e32 v72, s24, v226
	s_add_i32 s25, 0, 0x1c000
	ds_read_b128 v[40:43], v72
	ds_read_b128 v[44:47], v72 offset:1024
	ds_read_b128 v[136:139], v72 offset:2048
	ds_read_b128 v[140:143], v72 offset:3072
	v_add_u32_e32 v72, s25, v226
	ds_read_b128 v[144:147], v72
	ds_read_b128 v[148:151], v72 offset:1024
	ds_read_b128 v[184:187], v72 offset:2048
	ds_read_b128 v[192:195], v72 offset:3072
	s_add_u32 s2, s22, 0x80000
	s_addc_u32 s3, s23, 0
	s_mov_b32 m0, s89
	ds_read_b128 v[72:75], v227 offset:32768
	ds_read_b128 v[84:87], v227 offset:33792
	ds_read_b128 v[100:103], v227 offset:34816
	ds_read_b128 v[128:131], v227 offset:35840
	ds_read_b128 v[172:175], v227 offset:36864
	ds_read_b128 v[180:183], v227 offset:37888
	ds_read_b128 v[188:191], v227 offset:38912
	ds_read_b128 v[196:199], v227 offset:39936
	global_load_lds_dwordx4 v218, s[2:3]
	v_lshl_add_u64 v[132:133], s[2:3], 0, v[222:223]
	s_mov_b32 m0, s76
	s_nop 0
	global_load_lds_dwordx4 v[132:133], off
	s_waitcnt vmcnt(8)
	s_waitcnt lgkmcnt(0)
	s_barrier
	s_setprio 1
	s_waitcnt lgkmcnt(0)
	v_mfma_f32_16x16x32_bf16 v[132:135], v[40:43], v[72:75], v[152:155]
	v_mfma_f32_16x16x32_bf16 v[164:167], v[44:47], v[84:87], v[132:135]
	v_mfma_f32_16x16x32_bf16 v[108:111], v[40:43], v[172:175], v[108:111]
	v_mfma_f32_16x16x32_bf16 v[108:111], v[44:47], v[180:183], v[108:111]
	v_mfma_f32_16x16x32_bf16 v[132:135], v[40:43], v[100:103], v[160:163]
	v_mfma_f32_16x16x32_bf16 v[160:163], v[44:47], v[128:131], v[132:135]
	v_mfma_f32_16x16x32_bf16 v[132:135], v[136:139], v[100:103], v[156:159]
	v_mfma_f32_16x16x32_bf16 v[156:159], v[140:143], v[128:131], v[132:135]
	v_mfma_f32_16x16x32_bf16 v[132:135], v[40:43], v[188:191], v[168:171]
	v_mfma_f32_16x16x32_bf16 v[168:171], v[44:47], v[196:199], v[132:135]
	v_mfma_f32_16x16x32_bf16 v[64:67], v[136:139], v[72:75], v[64:67]
	v_mfma_f32_16x16x32_bf16 v[64:67], v[140:143], v[84:87], v[64:67]
	v_mfma_f32_16x16x32_bf16 v[104:107], v[136:139], v[172:175], v[104:107]
	v_mfma_f32_16x16x32_bf16 v[104:107], v[140:143], v[180:183], v[104:107]
	v_mfma_f32_16x16x32_bf16 v[68:71], v[136:139], v[188:191], v[68:71]
	v_mfma_f32_16x16x32_bf16 v[68:71], v[140:143], v[196:199], v[68:71]
	s_setprio 0
	s_setprio 1
	v_mfma_f32_16x16x32_bf16 v[48:51], v[184:187], v[72:75], v[48:51]
	v_mfma_f32_16x16x32_bf16 v[88:91], v[144:147], v[72:75], v[88:91]
	v_mfma_f32_16x16x32_bf16 v[88:91], v[148:151], v[84:87], v[88:91]
	v_mfma_f32_16x16x32_bf16 v[72:75], v[192:195], v[84:87], v[48:51]
	v_mfma_f32_16x16x32_bf16 v[48:51], v[144:147], v[100:103], v[52:55]
	v_mfma_f32_16x16x32_bf16 v[132:135], v[148:151], v[128:131], v[48:51]
	v_mfma_f32_16x16x32_bf16 v[48:51], v[184:187], v[100:103], v[56:59]
	v_mfma_f32_16x16x32_bf16 v[128:131], v[192:195], v[128:131], v[48:51]
	v_mfma_f32_16x16x32_bf16 v[48:51], v[144:147], v[172:175], v[60:63]
	v_mfma_f32_16x16x32_bf16 v[100:103], v[148:151], v[180:183], v[48:51]
	v_mfma_f32_16x16x32_bf16 v[48:51], v[184:187], v[172:175], v[96:99]
	v_mfma_f32_16x16x32_bf16 v[96:99], v[192:195], v[180:183], v[48:51]
	v_mfma_f32_16x16x32_bf16 v[48:51], v[144:147], v[188:191], v[92:95]
	v_mfma_f32_16x16x32_bf16 v[92:95], v[148:151], v[196:199], v[48:51]
	v_mfma_f32_16x16x32_bf16 v[48:51], v[184:187], v[188:191], v[76:79]
	v_mfma_f32_16x16x32_bf16 v[76:79], v[192:195], v[196:199], v[48:51]
	s_setprio 0
	s_barrier
	s_nop 1
	s_add_i32 s2, s24, s79
	v_lshl_add_u64 v[84:85], v[214:215], 0, s[72:73]
	s_mov_b32 m0, s2
	s_nop 0
	ds_read_b128 v[48:51], v227 offset:49152
	ds_read_b128 v[52:55], v227 offset:50176
	ds_read_b128 v[56:59], v227 offset:51200
	ds_read_b128 v[60:63], v227 offset:52224
	ds_read_b128 v[152:155], v227 offset:53248
	ds_read_b128 v[180:183], v227 offset:54272
	ds_read_b128 v[204:207], v227 offset:55296
	ds_read_b128 v[208:211], v227 offset:56320
	global_load_lds_dwordx4 v[84:85], off
	s_add_i32 m0, s2, 0x2000
	s_add_u32 s2, s20, 0x80080
	v_lshl_add_u64 v[84:85], v[216:217], 0, s[72:73]
	s_addc_u32 s3, s21, 0
	s_add_i32 s20, s25, s79
	global_load_lds_dwordx4 v[84:85], off
	s_mov_b32 m0, s20
	s_nop 0
	global_load_lds_dwordx4 v220, s[2:3]
	s_add_i32 m0, s20, 0x2000
	s_nop 0
	global_load_lds_dwordx4 v224, s[2:3]
	v_lshl_add_u64 v[84:85], v[230:231], 0, s[72:73]
	s_mov_b32 m0, s67
	s_nop 0
	global_load_lds_dwordx4 v[84:85], off
	v_lshl_add_u64 v[84:85], v[232:233], 0, s[72:73]
	s_mov_b32 m0, s84
	s_nop 0
	global_load_lds_dwordx4 v[84:85], off
	s_waitcnt vmcnt(8)
	s_waitcnt lgkmcnt(0)
	s_barrier
	s_setprio 1
	s_waitcnt lgkmcnt(0)
	v_mfma_f32_16x16x32_bf16 v[84:87], v[136:139], v[48:51], v[176:179]
	v_mfma_f32_16x16x32_bf16 v[196:199], v[140:143], v[52:55], v[84:87]
	v_mfma_f32_16x16x32_bf16 v[12:15], v[40:43], v[56:59], v[12:15]
	v_mfma_f32_16x16x32_bf16 v[12:15], v[44:47], v[60:63], v[12:15]
	v_mfma_f32_16x16x32_bf16 v[84:87], v[40:43], v[152:155], v[124:127]
	v_mfma_f32_16x16x32_bf16 v[124:127], v[44:47], v[180:183], v[84:87]
	v_mfma_f32_16x16x32_bf16 v[84:87], v[136:139], v[152:155], v[120:123]
	v_mfma_f32_16x16x32_bf16 v[120:123], v[140:143], v[180:183], v[84:87]
	v_mfma_f32_16x16x32_bf16 v[16:19], v[40:43], v[204:207], v[16:19]
	v_mfma_f32_16x16x32_bf16 v[84:87], v[44:47], v[208:211], v[16:19]
	v_mfma_f32_16x16x32_bf16 v[80:83], v[40:43], v[48:51], v[80:83]
	v_mfma_f32_16x16x32_bf16 v[80:83], v[44:47], v[52:55], v[80:83]
	v_mfma_f32_16x16x32_bf16 v[8:11], v[136:139], v[56:59], v[8:11]
	v_mfma_f32_16x16x32_bf16 v[8:11], v[140:143], v[60:63], v[8:11]
	v_mfma_f32_16x16x32_bf16 v[16:19], v[136:139], v[204:207], v[20:23]
	v_mfma_f32_16x16x32_bf16 v[200:203], v[140:143], v[208:211], v[16:19]
	s_setprio 0
	s_setprio 1
	v_mfma_f32_16x16x32_bf16 v[4:7], v[144:147], v[56:59], v[4:7]
	v_mfma_f32_16x16x32_bf16 v[4:7], v[148:151], v[60:63], v[4:7]
	v_mfma_f32_16x16x32_bf16 v[16:19], v[144:147], v[48:51], v[24:27]
	v_mfma_f32_16x16x32_bf16 v[172:175], v[148:151], v[52:55], v[16:19]
	v_mfma_f32_16x16x32_bf16 v[16:19], v[184:187], v[48:51], v[28:31]
	v_mfma_f32_16x16x32_bf16 v[188:191], v[192:195], v[52:55], v[16:19]
	v_mfma_f32_16x16x32_bf16 v[16:19], v[144:147], v[152:155], v[116:119]
	v_mfma_f32_16x16x32_bf16 v[116:119], v[148:151], v[180:183], v[16:19]
	v_mfma_f32_16x16x32_bf16 v[16:19], v[184:187], v[152:155], v[112:115]
	v_mfma_f32_16x16x32_bf16 v[112:115], v[192:195], v[180:183], v[16:19]
	v_mfma_f32_16x16x32_bf16 v[16:19], v[144:147], v[204:207], v[32:35]
	v_mfma_f32_16x16x32_bf16 v[180:183], v[148:151], v[208:211], v[16:19]
	v_mfma_f32_16x16x32_bf16 v[0:3], v[184:187], v[56:59], v[0:3]
	v_mfma_f32_16x16x32_bf16 v[0:3], v[192:195], v[60:63], v[0:3]
	v_mfma_f32_16x16x32_bf16 v[16:19], v[184:187], v[204:207], v[36:39]
	v_mfma_f32_16x16x32_bf16 v[192:195], v[192:195], v[208:211], v[16:19]
	s_setprio 0
	s_barrier
	s_nop 1
	s_add_i32 s2, s9, 2
	s_cmp_gt_u32 s9, 29
	s_mov_b32 s9, s2
	s_cbranch_scc1 .LBB0_1436

.LBB0_1659:
	s_ashr_i32 s63, s62, 31
	s_add_i32 s40, s17, -2
	s_lshl_b64 s[14:15], s[62:63], 7
	s_and_b64 s[18:19], s[38:39], exec
	s_cselect_b32 s14, s14, 0
	s_cselect_b32 s15, s15, 0
	s_add_u32 s74, s2, s14
	s_addc_u32 s75, s3, s15
	s_add_u32 s8, s8, s14
	s_mul_hi_i32 s2, s43, 0x78787879
	s_addc_u32 s9, s9, s15
	s_lshr_b32 s3, s2, 31
	s_ashr_i32 s2, s2, 3
	s_add_i32 s16, s2, s3
	s_mul_i32 s2, s16, 17
	s_lshl_b32 s14, s42, 8
	s_sub_i32 s2, s43, s2
	s_ashr_i32 s15, s14, 31
	s_cmp_lg_u32 s2, 0
	s_cselect_b32 s2, s16, 8
	s_ashr_i32 s3, s2, 31
	s_lshl_b64 s[18:19], s[2:3], 13
	s_cmpk_lg_i32 s17, 0x58
	s_cselect_b64 s[20:21], -1, 0
	s_cmpk_eq_i32 s17, 0x58
	s_mul_hi_i32 s29, s2, 0xc000
	s_mul_i32 s30, s2, 0xc000
	s_cselect_b64 s[2:3], -1, 0
	s_and_b64 s[22:23], s[56:57], s[2:3]
	s_add_u32 s2, s70, s18
	s_addc_u32 s3, s71, s19
	s_lshl_b64 s[18:19], s[14:15], 2
	s_add_u32 s24, s2, s18
	s_addc_u32 s25, s3, s19
	s_add_u32 s2, s64, s30
	s_addc_u32 s3, s68, s29
	s_add_u32 s38, s2, s18
	s_addc_u32 s39, s3, s19
	s_add_u32 s15, s26, 0x100
	s_addc_u32 s41, s27, 0
	s_add_u32 s2, s12, 0x160080
	s_addc_u32 s3, s13, 0
	s_mov_b32 s28, 0
	v_lshl_add_u64 v[68:69], s[2:3], 0, v[222:223]
	v_lshl_add_u64 v[70:71], s[2:3], 0, v[224:225]
	s_mov_b64 s[26:27], 0
	s_waitcnt lgkmcnt(0)
	s_add_i32 s2, s28, 2
	s_add_u32 s3, s12, s26
	s_addc_u32 s29, s13, s27
	s_add_u32 s3, s3, 0x100
	s_addc_u32 s29, s29, 0
	s_add_u32 s55, s15, s26
	s_addc_u32 s63, s41, s27
	s_cmp_eq_u32 s40, s28
	s_cselect_b32 s31, s75, s29
	s_cselect_b32 s30, s74, s3
	s_cselect_b32 s29, s9, s63
	s_cselect_b32 s28, s8, s55
	s_add_i32 s3, 0, 0x10000
	s_add_i32 s55, 0, 0x14000
	v_add_u32_e32 v112, s3, v238
	v_add_u32_e32 v160, s55, v238
	ds_read_b128 v[76:79], v112
	ds_read_b128 v[88:91], v112 offset:1024
	ds_read_b128 v[100:103], v112 offset:2048
	ds_read_b128 v[112:115], v112 offset:3072
	ds_read_b128 v[124:127], v160
	ds_read_b128 v[136:139], v160 offset:1024
	ds_read_b128 v[148:151], v160 offset:2048
	ds_read_b128 v[160:163], v160 offset:3072
	v_lshl_add_u64 v[196:197], v[68:69], 0, s[26:27]
	s_add_i32 m0, s11, 0xc000
	ds_read_b128 v[164:167], v241
	ds_read_b128 v[168:171], v241 offset:1024
	ds_read_b128 v[172:175], v241 offset:2048
	ds_read_b128 v[176:179], v241 offset:3072
	ds_read_b128 v[180:183], v241 offset:4096
	ds_read_b128 v[184:187], v241 offset:5120
	ds_read_b128 v[188:191], v241 offset:6144
	ds_read_b128 v[192:195], v241 offset:7168
	global_load_lds_dwordx4 v[196:197], off
	v_lshl_add_u64 v[196:197], v[70:71], 0, s[26:27]
	s_add_i32 m0, s11, 0xe000
	s_nop 0
	global_load_lds_dwordx4 v[196:197], off
	s_waitcnt vmcnt(8)
	s_waitcnt lgkmcnt(0)
	s_barrier
	s_setprio 1
	s_waitcnt lgkmcnt(0)
	v_mfma_f32_16x16x32_bf16 v[156:159], v[76:79], v[164:167], 0
	v_mfma_f32_16x16x32_bf16 v[156:159], v[88:91], v[168:171], v[156:159]
	v_mfma_f32_16x16x32_bf16 v[144:147], v[76:79], v[172:175], 0
	v_mfma_f32_16x16x32_bf16 v[144:147], v[88:91], v[176:179], v[144:147]
	v_mfma_f32_16x16x32_bf16 v[132:135], v[76:79], v[180:183], 0
	v_mfma_f32_16x16x32_bf16 v[132:135], v[88:91], v[184:187], v[132:135]
	v_mfma_f32_16x16x32_bf16 v[120:123], v[76:79], v[188:191], 0
	v_mfma_f32_16x16x32_bf16 v[120:123], v[88:91], v[192:195], v[120:123]
	v_mfma_f32_16x16x32_bf16 v[152:155], v[100:103], v[164:167], 0
	v_mfma_f32_16x16x32_bf16 v[152:155], v[112:115], v[168:171], v[152:155]
	v_mfma_f32_16x16x32_bf16 v[140:143], v[100:103], v[172:175], 0
	v_mfma_f32_16x16x32_bf16 v[140:143], v[112:115], v[176:179], v[140:143]
	v_mfma_f32_16x16x32_bf16 v[128:131], v[100:103], v[180:183], 0
	v_mfma_f32_16x16x32_bf16 v[128:131], v[112:115], v[184:187], v[128:131]
	v_mfma_f32_16x16x32_bf16 v[116:119], v[100:103], v[188:191], 0
	v_mfma_f32_16x16x32_bf16 v[116:119], v[112:115], v[192:195], v[116:119]
	s_setprio 0
	s_setprio 1
	v_mfma_f32_16x16x32_bf16 v[108:111], v[124:127], v[164:167], 0
	v_mfma_f32_16x16x32_bf16 v[108:111], v[136:139], v[168:171], v[108:111]
	v_mfma_f32_16x16x32_bf16 v[96:99], v[124:127], v[172:175], 0
	v_mfma_f32_16x16x32_bf16 v[96:99], v[136:139], v[176:179], v[96:99]
	v_mfma_f32_16x16x32_bf16 v[84:87], v[124:127], v[180:183], 0
	v_mfma_f32_16x16x32_bf16 v[84:87], v[136:139], v[184:187], v[84:87]
	v_mfma_f32_16x16x32_bf16 v[72:75], v[124:127], v[188:191], 0
	v_mfma_f32_16x16x32_bf16 v[72:75], v[136:139], v[192:195], v[72:75]
	v_mfma_f32_16x16x32_bf16 v[104:107], v[148:151], v[164:167], 0
	v_mfma_f32_16x16x32_bf16 v[104:107], v[160:163], v[168:171], v[104:107]
	v_mfma_f32_16x16x32_bf16 v[92:95], v[148:151], v[172:175], 0
	v_mfma_f32_16x16x32_bf16 v[92:95], v[160:163], v[176:179], v[92:95]
	v_mfma_f32_16x16x32_bf16 v[80:83], v[148:151], v[180:183], 0
	v_mfma_f32_16x16x32_bf16 v[80:83], v[160:163], v[184:187], v[80:83]
	v_mfma_f32_16x16x32_bf16 v[64:67], v[148:151], v[188:191], 0
	v_mfma_f32_16x16x32_bf16 v[64:67], v[160:163], v[192:195], v[64:67]
	s_setprio 0
	s_barrier
	s_nop 1
	s_add_i32 s3, s3, s33
	v_lshl_add_u64 v[196:197], s[28:29], 0, v[210:211]
	s_mov_b32 m0, s3
	ds_read_b128 v[164:167], v241 offset:16384
	ds_read_b128 v[168:171], v241 offset:17408
	ds_read_b128 v[172:175], v241 offset:18432
	ds_read_b128 v[176:179], v241 offset:19456
	ds_read_b128 v[180:183], v241 offset:20480
	ds_read_b128 v[184:187], v241 offset:21504
	ds_read_b128 v[188:191], v241 offset:22528
	ds_read_b128 v[192:195], v241 offset:23552
	global_load_lds_dwordx4 v[196:197], off
	s_add_i32 m0, s3, 0x2000
	s_add_u32 vcc_lo, s28, 0x160000
	v_lshl_add_u64 v[198:199], s[28:29], 0, v[220:221]
	s_addc_u32 vcc_hi, s29, 0
	s_add_i32 s3, s55, s33
	global_load_lds_dwordx4 v[198:199], off
	v_lshl_add_u64 v[200:201], vcc, 0, v[210:211]
	s_mov_b32 m0, s3
	v_lshl_add_u64 v[202:203], s[30:31], 0, v[218:219]
	global_load_lds_dwordx4 v[200:201], off
	v_lshl_add_u64 v[200:201], vcc, 0, v[220:221]
	s_add_i32 m0, s3, 0x2000
	s_nop 0
	global_load_lds_dwordx4 v[200:201], off
	v_lshl_add_u64 v[200:201], s[30:31], 0, v[208:209]
	s_mov_b32 m0, s11
	s_nop 0
	global_load_lds_dwordx4 v[200:201], off
	s_mov_b32 m0, s65
	s_nop 0
	global_load_lds_dwordx4 v[202:203], off
	s_waitcnt vmcnt(8)
	s_waitcnt lgkmcnt(0)
	s_barrier
	s_setprio 1
	s_waitcnt lgkmcnt(0)
	v_mfma_f32_16x16x32_bf16 v[60:63], v[76:79], v[164:167], 0
	v_mfma_f32_16x16x32_bf16 v[60:63], v[88:91], v[168:171], v[60:63]
	v_mfma_f32_16x16x32_bf16 v[52:55], v[76:79], v[172:175], 0
	v_mfma_f32_16x16x32_bf16 v[52:55], v[88:91], v[176:179], v[52:55]
	v_mfma_f32_16x16x32_bf16 v[44:47], v[76:79], v[180:183], 0
	v_mfma_f32_16x16x32_bf16 v[44:47], v[88:91], v[184:187], v[44:47]
	v_mfma_f32_16x16x32_bf16 v[36:39], v[76:79], v[188:191], 0
	v_mfma_f32_16x16x32_bf16 v[36:39], v[88:91], v[192:195], v[36:39]
	v_mfma_f32_16x16x32_bf16 v[56:59], v[100:103], v[164:167], 0
	v_mfma_f32_16x16x32_bf16 v[56:59], v[112:115], v[168:171], v[56:59]
	v_mfma_f32_16x16x32_bf16 v[48:51], v[100:103], v[172:175], 0
	v_mfma_f32_16x16x32_bf16 v[48:51], v[112:115], v[176:179], v[48:51]
	v_mfma_f32_16x16x32_bf16 v[40:43], v[100:103], v[180:183], 0
	v_mfma_f32_16x16x32_bf16 v[40:43], v[112:115], v[184:187], v[40:43]
	v_mfma_f32_16x16x32_bf16 v[32:35], v[100:103], v[188:191], 0
	v_mfma_f32_16x16x32_bf16 v[32:35], v[112:115], v[192:195], v[32:35]
	s_setprio 0
	s_setprio 1
	v_mfma_f32_16x16x32_bf16 v[28:31], v[124:127], v[164:167], 0
	v_mfma_f32_16x16x32_bf16 v[28:31], v[136:139], v[168:171], v[28:31]
	v_mfma_f32_16x16x32_bf16 v[20:23], v[124:127], v[172:175], 0
	v_mfma_f32_16x16x32_bf16 v[20:23], v[136:139], v[176:179], v[20:23]
	v_mfma_f32_16x16x32_bf16 v[12:15], v[124:127], v[180:183], 0
	v_mfma_f32_16x16x32_bf16 v[12:15], v[136:139], v[184:187], v[12:15]
	v_mfma_f32_16x16x32_bf16 v[4:7], v[124:127], v[188:191], 0
	v_mfma_f32_16x16x32_bf16 v[4:7], v[136:139], v[192:195], v[4:7]
	v_mfma_f32_16x16x32_bf16 v[24:27], v[148:151], v[164:167], 0
	v_mfma_f32_16x16x32_bf16 v[24:27], v[160:163], v[168:171], v[24:27]
	v_mfma_f32_16x16x32_bf16 v[16:19], v[148:151], v[172:175], 0
	v_mfma_f32_16x16x32_bf16 v[16:19], v[160:163], v[176:179], v[16:19]
	v_mfma_f32_16x16x32_bf16 v[8:11], v[148:151], v[180:183], 0
	v_mfma_f32_16x16x32_bf16 v[8:11], v[160:163], v[184:187], v[8:11]
	v_mfma_f32_16x16x32_bf16 v[0:3], v[148:151], v[188:191], 0
	v_mfma_f32_16x16x32_bf16 v[0:3], v[160:163], v[192:195], v[0:3]
	s_setprio 0
	s_barrier
	s_nop 1
	s_add_i32 s3, 0, 0x18000
	s_add_i32 s55, 0, 0x1c000
	v_add_u32_e32 v112, s3, v238
	v_add_u32_e32 v160, s55, v238
	ds_read_b128 v[76:79], v112
	ds_read_b128 v[88:91], v112 offset:1024
	ds_read_b128 v[100:103], v112 offset:2048
	ds_read_b128 v[112:115], v112 offset:3072
	ds_read_b128 v[124:127], v160
	ds_read_b128 v[136:139], v160 offset:1024
	ds_read_b128 v[148:151], v160 offset:2048
	ds_read_b128 v[160:163], v160 offset:3072
	s_add_u32 s30, s30, 0x160000
	s_addc_u32 s31, s31, 0
	s_mov_b32 m0, s34
	ds_read_b128 v[164:167], v241 offset:32768
	ds_read_b128 v[168:171], v241 offset:33792
	ds_read_b128 v[172:175], v241 offset:34816
	ds_read_b128 v[176:179], v241 offset:35840
	ds_read_b128 v[180:183], v241 offset:36864
	ds_read_b128 v[184:187], v241 offset:37888
	ds_read_b128 v[188:191], v241 offset:38912
	ds_read_b128 v[192:195], v241 offset:39936
	global_load_lds_dwordx4 v208, s[30:31]
	v_lshl_add_u64 v[204:205], s[30:31], 0, v[218:219]
	s_mov_b32 m0, s67
	s_nop 0
	global_load_lds_dwordx4 v[204:205], off
	s_waitcnt vmcnt(8)
	s_waitcnt lgkmcnt(0)
	s_barrier
	s_setprio 1
	s_waitcnt lgkmcnt(0)
	v_mfma_f32_16x16x32_bf16 v[156:159], v[76:79], v[164:167], v[156:159]
	v_mfma_f32_16x16x32_bf16 v[156:159], v[88:91], v[168:171], v[156:159]
	v_mfma_f32_16x16x32_bf16 v[144:147], v[76:79], v[172:175], v[144:147]
	v_mfma_f32_16x16x32_bf16 v[144:147], v[88:91], v[176:179], v[144:147]
	v_mfma_f32_16x16x32_bf16 v[132:135], v[76:79], v[180:183], v[132:135]
	v_mfma_f32_16x16x32_bf16 v[132:135], v[88:91], v[184:187], v[132:135]
	v_mfma_f32_16x16x32_bf16 v[120:123], v[76:79], v[188:191], v[120:123]
	v_mfma_f32_16x16x32_bf16 v[120:123], v[88:91], v[192:195], v[120:123]
	v_mfma_f32_16x16x32_bf16 v[152:155], v[100:103], v[164:167], v[152:155]
	v_mfma_f32_16x16x32_bf16 v[152:155], v[112:115], v[168:171], v[152:155]
	v_mfma_f32_16x16x32_bf16 v[140:143], v[100:103], v[172:175], v[140:143]
	v_mfma_f32_16x16x32_bf16 v[140:143], v[112:115], v[176:179], v[140:143]
	v_mfma_f32_16x16x32_bf16 v[128:131], v[100:103], v[180:183], v[128:131]
	v_mfma_f32_16x16x32_bf16 v[128:131], v[112:115], v[184:187], v[128:131]
	v_mfma_f32_16x16x32_bf16 v[116:119], v[100:103], v[188:191], v[116:119]
	v_mfma_f32_16x16x32_bf16 v[116:119], v[112:115], v[192:195], v[116:119]
	s_setprio 0
	s_setprio 1
	v_mfma_f32_16x16x32_bf16 v[108:111], v[124:127], v[164:167], v[108:111]
	v_mfma_f32_16x16x32_bf16 v[108:111], v[136:139], v[168:171], v[108:111]
	v_mfma_f32_16x16x32_bf16 v[96:99], v[124:127], v[172:175], v[96:99]
	v_mfma_f32_16x16x32_bf16 v[96:99], v[136:139], v[176:179], v[96:99]
	v_mfma_f32_16x16x32_bf16 v[84:87], v[124:127], v[180:183], v[84:87]
	v_mfma_f32_16x16x32_bf16 v[84:87], v[136:139], v[184:187], v[84:87]
	v_mfma_f32_16x16x32_bf16 v[72:75], v[124:127], v[188:191], v[72:75]
	v_mfma_f32_16x16x32_bf16 v[72:75], v[136:139], v[192:195], v[72:75]
	v_mfma_f32_16x16x32_bf16 v[104:107], v[148:151], v[164:167], v[104:107]
	v_mfma_f32_16x16x32_bf16 v[104:107], v[160:163], v[168:171], v[104:107]
	v_mfma_f32_16x16x32_bf16 v[92:95], v[148:151], v[172:175], v[92:95]
	v_mfma_f32_16x16x32_bf16 v[92:95], v[160:163], v[176:179], v[92:95]
	v_mfma_f32_16x16x32_bf16 v[80:83], v[148:151], v[180:183], v[80:83]
	v_mfma_f32_16x16x32_bf16 v[80:83], v[160:163], v[184:187], v[80:83]
	v_mfma_f32_16x16x32_bf16 v[64:67], v[148:151], v[188:191], v[64:67]
	v_mfma_f32_16x16x32_bf16 v[64:67], v[160:163], v[192:195], v[64:67]
	s_setprio 0
	s_barrier
	s_nop 1
	s_add_i32 s3, s3, s33
	v_lshl_add_u64 v[196:197], v[196:197], 0, s[72:73]
	s_mov_b32 m0, s3
	ds_read_b128 v[164:167], v241 offset:49152
	ds_read_b128 v[168:171], v241 offset:50176
	ds_read_b128 v[172:175], v241 offset:51200
	ds_read_b128 v[176:179], v241 offset:52224
	ds_read_b128 v[180:183], v241 offset:53248
	ds_read_b128 v[184:187], v241 offset:54272
	ds_read_b128 v[188:191], v241 offset:55296
	ds_read_b128 v[192:195], v241 offset:56320
	global_load_lds_dwordx4 v[196:197], off
	s_add_i32 m0, s3, 0x2000
	s_add_u32 s28, s28, 0x160080
	v_lshl_add_u64 v[196:197], v[198:199], 0, s[72:73]
	s_addc_u32 s29, s29, 0
	s_add_i32 s3, s55, s33
	global_load_lds_dwordx4 v[196:197], off
	s_mov_b32 m0, s3
	s_nop 0
	global_load_lds_dwordx4 v210, s[28:29]
	s_add_i32 m0, s3, 0x2000
	s_nop 0
	global_load_lds_dwordx4 v220, s[28:29]
	v_lshl_add_u64 v[196:197], v[200:201], 0, s[72:73]
	s_mov_b32 m0, s81
	s_nop 0
	global_load_lds_dwordx4 v[196:197], off
	v_lshl_add_u64 v[196:197], v[202:203], 0, s[72:73]
	s_mov_b32 m0, s82
	s_nop 0
	global_load_lds_dwordx4 v[196:197], off
	s_waitcnt vmcnt(8)
	s_waitcnt lgkmcnt(0)
	s_barrier
	s_setprio 1
	s_waitcnt lgkmcnt(0)
	v_mfma_f32_16x16x32_bf16 v[60:63], v[76:79], v[164:167], v[60:63]
	v_mfma_f32_16x16x32_bf16 v[60:63], v[88:91], v[168:171], v[60:63]
	v_mfma_f32_16x16x32_bf16 v[52:55], v[76:79], v[172:175], v[52:55]
	v_mfma_f32_16x16x32_bf16 v[52:55], v[88:91], v[176:179], v[52:55]
	v_mfma_f32_16x16x32_bf16 v[44:47], v[76:79], v[180:183], v[44:47]
	v_mfma_f32_16x16x32_bf16 v[44:47], v[88:91], v[184:187], v[44:47]
	v_mfma_f32_16x16x32_bf16 v[36:39], v[76:79], v[188:191], v[36:39]
	v_mfma_f32_16x16x32_bf16 v[36:39], v[88:91], v[192:195], v[36:39]
	v_mfma_f32_16x16x32_bf16 v[56:59], v[100:103], v[164:167], v[56:59]
	v_mfma_f32_16x16x32_bf16 v[56:59], v[112:115], v[168:171], v[56:59]
	v_mfma_f32_16x16x32_bf16 v[48:51], v[100:103], v[172:175], v[48:51]
	v_mfma_f32_16x16x32_bf16 v[48:51], v[112:115], v[176:179], v[48:51]
	v_mfma_f32_16x16x32_bf16 v[40:43], v[100:103], v[180:183], v[40:43]
	v_mfma_f32_16x16x32_bf16 v[40:43], v[112:115], v[184:187], v[40:43]
	v_mfma_f32_16x16x32_bf16 v[32:35], v[100:103], v[188:191], v[32:35]
	v_mfma_f32_16x16x32_bf16 v[32:35], v[112:115], v[192:195], v[32:35]
	s_setprio 0
	s_setprio 1
	v_mfma_f32_16x16x32_bf16 v[28:31], v[124:127], v[164:167], v[28:31]
	v_mfma_f32_16x16x32_bf16 v[28:31], v[136:139], v[168:171], v[28:31]
	v_mfma_f32_16x16x32_bf16 v[20:23], v[124:127], v[172:175], v[20:23]
	v_mfma_f32_16x16x32_bf16 v[20:23], v[136:139], v[176:179], v[20:23]
	v_mfma_f32_16x16x32_bf16 v[12:15], v[124:127], v[180:183], v[12:15]
	v_mfma_f32_16x16x32_bf16 v[12:15], v[136:139], v[184:187], v[12:15]
	v_mfma_f32_16x16x32_bf16 v[4:7], v[124:127], v[188:191], v[4:7]
	v_mfma_f32_16x16x32_bf16 v[4:7], v[136:139], v[192:195], v[4:7]
	v_mfma_f32_16x16x32_bf16 v[24:27], v[148:151], v[164:167], v[24:27]
	v_mfma_f32_16x16x32_bf16 v[24:27], v[160:163], v[168:171], v[24:27]
	v_mfma_f32_16x16x32_bf16 v[16:19], v[148:151], v[172:175], v[16:19]
	v_mfma_f32_16x16x32_bf16 v[16:19], v[160:163], v[176:179], v[16:19]
	v_mfma_f32_16x16x32_bf16 v[8:11], v[148:151], v[180:183], v[8:11]
	v_mfma_f32_16x16x32_bf16 v[8:11], v[160:163], v[184:187], v[8:11]
	v_mfma_f32_16x16x32_bf16 v[0:3], v[148:151], v[188:191], v[0:3]
	v_mfma_f32_16x16x32_bf16 v[0:3], v[160:163], v[192:195], v[0:3]
	s_setprio 0
	s_barrier
	s_nop 1
	s_add_u32 s26, s26, 0x100
	s_addc_u32 s27, s27, 0
	s_cmp_ge_i32 s2, s17
	s_mov_b32 s28, s2
	s_cbranch_scc1 .LBB0_1669
	s_branch .LBB0_1661
.LBB0_1660:
	s_add_i32 s2, s28, 2
	s_add_u32 s3, s12, s26
	s_addc_u32 s29, s13, s27
	s_add_u32 s3, s3, 0x100
	s_addc_u32 s29, s29, 0
	s_add_u32 s55, s15, s26
	s_addc_u32 s63, s41, s27
	s_cmp_eq_u32 s40, s28
	s_cselect_b32 s31, s75, s29
	s_cselect_b32 s30, s74, s3
	s_cselect_b32 s29, s9, s63
	s_cselect_b32 s28, s8, s55
	s_add_i32 s3, 0, 0x10000
	s_add_i32 s55, 0, 0x14000
	v_add_u32_e32 v112, s3, v238
	v_add_u32_e32 v160, s55, v238
	ds_read_b128 v[76:79], v112
	ds_read_b128 v[88:91], v112 offset:1024
	ds_read_b128 v[100:103], v112 offset:2048
	ds_read_b128 v[112:115], v112 offset:3072
	ds_read_b128 v[124:127], v160
	ds_read_b128 v[136:139], v160 offset:1024
	ds_read_b128 v[148:151], v160 offset:2048
	ds_read_b128 v[160:163], v160 offset:3072
	v_lshl_add_u64 v[196:197], v[68:69], 0, s[26:27]
	s_add_i32 m0, s11, 0xc000
	ds_read_b128 v[164:167], v241
	ds_read_b128 v[168:171], v241 offset:1024
	ds_read_b128 v[172:175], v241 offset:2048
	ds_read_b128 v[176:179], v241 offset:3072
	ds_read_b128 v[180:183], v241 offset:4096
	ds_read_b128 v[184:187], v241 offset:5120
	ds_read_b128 v[188:191], v241 offset:6144
	ds_read_b128 v[192:195], v241 offset:7168
	global_load_lds_dwordx4 v[196:197], off
	v_lshl_add_u64 v[196:197], v[70:71], 0, s[26:27]
	s_add_i32 m0, s11, 0xe000
	s_nop 0
	global_load_lds_dwordx4 v[196:197], off
	s_waitcnt vmcnt(8)
	s_waitcnt lgkmcnt(0)
	s_barrier
	s_setprio 1
	s_waitcnt lgkmcnt(0)
	v_mfma_f32_16x16x32_bf16 v[156:159], v[76:79], v[164:167], v[156:159]
	v_mfma_f32_16x16x32_bf16 v[156:159], v[88:91], v[168:171], v[156:159]
	v_mfma_f32_16x16x32_bf16 v[144:147], v[76:79], v[172:175], v[144:147]
	v_mfma_f32_16x16x32_bf16 v[144:147], v[88:91], v[176:179], v[144:147]
	v_mfma_f32_16x16x32_bf16 v[132:135], v[76:79], v[180:183], v[132:135]
	v_mfma_f32_16x16x32_bf16 v[132:135], v[88:91], v[184:187], v[132:135]
	v_mfma_f32_16x16x32_bf16 v[120:123], v[76:79], v[188:191], v[120:123]
	v_mfma_f32_16x16x32_bf16 v[120:123], v[88:91], v[192:195], v[120:123]
	v_mfma_f32_16x16x32_bf16 v[152:155], v[100:103], v[164:167], v[152:155]
	v_mfma_f32_16x16x32_bf16 v[152:155], v[112:115], v[168:171], v[152:155]
	v_mfma_f32_16x16x32_bf16 v[140:143], v[100:103], v[172:175], v[140:143]
	v_mfma_f32_16x16x32_bf16 v[140:143], v[112:115], v[176:179], v[140:143]
	v_mfma_f32_16x16x32_bf16 v[128:131], v[100:103], v[180:183], v[128:131]
	v_mfma_f32_16x16x32_bf16 v[128:131], v[112:115], v[184:187], v[128:131]
	v_mfma_f32_16x16x32_bf16 v[116:119], v[100:103], v[188:191], v[116:119]
	v_mfma_f32_16x16x32_bf16 v[116:119], v[112:115], v[192:195], v[116:119]
	s_setprio 0
	s_setprio 1
	v_mfma_f32_16x16x32_bf16 v[108:111], v[124:127], v[164:167], v[108:111]
	v_mfma_f32_16x16x32_bf16 v[108:111], v[136:139], v[168:171], v[108:111]
	v_mfma_f32_16x16x32_bf16 v[96:99], v[124:127], v[172:175], v[96:99]
	v_mfma_f32_16x16x32_bf16 v[96:99], v[136:139], v[176:179], v[96:99]
	v_mfma_f32_16x16x32_bf16 v[84:87], v[124:127], v[180:183], v[84:87]
	v_mfma_f32_16x16x32_bf16 v[84:87], v[136:139], v[184:187], v[84:87]
	v_mfma_f32_16x16x32_bf16 v[72:75], v[124:127], v[188:191], v[72:75]
	v_mfma_f32_16x16x32_bf16 v[72:75], v[136:139], v[192:195], v[72:75]
	v_mfma_f32_16x16x32_bf16 v[104:107], v[148:151], v[164:167], v[104:107]
	v_mfma_f32_16x16x32_bf16 v[104:107], v[160:163], v[168:171], v[104:107]
	v_mfma_f32_16x16x32_bf16 v[92:95], v[148:151], v[172:175], v[92:95]
	v_mfma_f32_16x16x32_bf16 v[92:95], v[160:163], v[176:179], v[92:95]
	v_mfma_f32_16x16x32_bf16 v[80:83], v[148:151], v[180:183], v[80:83]
	v_mfma_f32_16x16x32_bf16 v[80:83], v[160:163], v[184:187], v[80:83]
	v_mfma_f32_16x16x32_bf16 v[64:67], v[148:151], v[188:191], v[64:67]
	v_mfma_f32_16x16x32_bf16 v[64:67], v[160:163], v[192:195], v[64:67]
	s_setprio 0
	s_barrier
	s_nop 1
	s_add_i32 s3, s3, s33
	v_lshl_add_u64 v[196:197], s[28:29], 0, v[210:211]
	s_mov_b32 m0, s3
	ds_read_b128 v[164:167], v241 offset:16384
	ds_read_b128 v[168:171], v241 offset:17408
	ds_read_b128 v[172:175], v241 offset:18432
	ds_read_b128 v[176:179], v241 offset:19456
	ds_read_b128 v[180:183], v241 offset:20480
	ds_read_b128 v[184:187], v241 offset:21504
	ds_read_b128 v[188:191], v241 offset:22528
	ds_read_b128 v[192:195], v241 offset:23552
	global_load_lds_dwordx4 v[196:197], off
	s_add_i32 m0, s3, 0x2000
	s_add_u32 vcc_lo, s28, 0x160000
	v_lshl_add_u64 v[198:199], s[28:29], 0, v[220:221]
	s_addc_u32 vcc_hi, s29, 0
	s_add_i32 s3, s55, s33
	global_load_lds_dwordx4 v[198:199], off
	v_lshl_add_u64 v[200:201], vcc, 0, v[210:211]
	s_mov_b32 m0, s3
	v_lshl_add_u64 v[202:203], s[30:31], 0, v[218:219]
	global_load_lds_dwordx4 v[200:201], off
	v_lshl_add_u64 v[200:201], vcc, 0, v[220:221]
	s_add_i32 m0, s3, 0x2000
	s_nop 0
	global_load_lds_dwordx4 v[200:201], off
	v_lshl_add_u64 v[200:201], s[30:31], 0, v[208:209]
	s_mov_b32 m0, s11
	s_nop 0
	global_load_lds_dwordx4 v[200:201], off
	s_mov_b32 m0, s65
	s_nop 0
	global_load_lds_dwordx4 v[202:203], off
	s_waitcnt vmcnt(8)
	s_waitcnt lgkmcnt(0)
	s_barrier
	s_setprio 1
	s_waitcnt lgkmcnt(0)
	v_mfma_f32_16x16x32_bf16 v[60:63], v[76:79], v[164:167], v[60:63]
	v_mfma_f32_16x16x32_bf16 v[60:63], v[88:91], v[168:171], v[60:63]
	v_mfma_f32_16x16x32_bf16 v[52:55], v[76:79], v[172:175], v[52:55]
	v_mfma_f32_16x16x32_bf16 v[52:55], v[88:91], v[176:179], v[52:55]
	v_mfma_f32_16x16x32_bf16 v[44:47], v[76:79], v[180:183], v[44:47]
	v_mfma_f32_16x16x32_bf16 v[44:47], v[88:91], v[184:187], v[44:47]
	v_mfma_f32_16x16x32_bf16 v[36:39], v[76:79], v[188:191], v[36:39]
	v_mfma_f32_16x16x32_bf16 v[36:39], v[88:91], v[192:195], v[36:39]
	v_mfma_f32_16x16x32_bf16 v[56:59], v[100:103], v[164:167], v[56:59]
	v_mfma_f32_16x16x32_bf16 v[56:59], v[112:115], v[168:171], v[56:59]
	v_mfma_f32_16x16x32_bf16 v[48:51], v[100:103], v[172:175], v[48:51]
	v_mfma_f32_16x16x32_bf16 v[48:51], v[112:115], v[176:179], v[48:51]
	v_mfma_f32_16x16x32_bf16 v[40:43], v[100:103], v[180:183], v[40:43]
	v_mfma_f32_16x16x32_bf16 v[40:43], v[112:115], v[184:187], v[40:43]
	v_mfma_f32_16x16x32_bf16 v[32:35], v[100:103], v[188:191], v[32:35]
	v_mfma_f32_16x16x32_bf16 v[32:35], v[112:115], v[192:195], v[32:35]
	s_setprio 0
	s_setprio 1
	v_mfma_f32_16x16x32_bf16 v[28:31], v[124:127], v[164:167], v[28:31]
	v_mfma_f32_16x16x32_bf16 v[28:31], v[136:139], v[168:171], v[28:31]
	v_mfma_f32_16x16x32_bf16 v[20:23], v[124:127], v[172:175], v[20:23]
	v_mfma_f32_16x16x32_bf16 v[20:23], v[136:139], v[176:179], v[20:23]
	v_mfma_f32_16x16x32_bf16 v[12:15], v[124:127], v[180:183], v[12:15]
	v_mfma_f32_16x16x32_bf16 v[12:15], v[136:139], v[184:187], v[12:15]
	v_mfma_f32_16x16x32_bf16 v[4:7], v[124:127], v[188:191], v[4:7]
	v_mfma_f32_16x16x32_bf16 v[4:7], v[136:139], v[192:195], v[4:7]
	v_mfma_f32_16x16x32_bf16 v[24:27], v[148:151], v[164:167], v[24:27]
	v_mfma_f32_16x16x32_bf16 v[24:27], v[160:163], v[168:171], v[24:27]
	v_mfma_f32_16x16x32_bf16 v[16:19], v[148:151], v[172:175], v[16:19]
	v_mfma_f32_16x16x32_bf16 v[16:19], v[160:163], v[176:179], v[16:19]
	v_mfma_f32_16x16x32_bf16 v[8:11], v[148:151], v[180:183], v[8:11]
	v_mfma_f32_16x16x32_bf16 v[8:11], v[160:163], v[184:187], v[8:11]
	v_mfma_f32_16x16x32_bf16 v[0:3], v[148:151], v[188:191], v[0:3]
	v_mfma_f32_16x16x32_bf16 v[0:3], v[160:163], v[192:195], v[0:3]
	s_setprio 0
	s_barrier
	s_nop 1
	s_add_i32 s3, 0, 0x18000
	s_add_i32 s55, 0, 0x1c000
	v_add_u32_e32 v112, s3, v238
	v_add_u32_e32 v160, s55, v238
	ds_read_b128 v[76:79], v112
	ds_read_b128 v[88:91], v112 offset:1024
	ds_read_b128 v[100:103], v112 offset:2048
	ds_read_b128 v[112:115], v112 offset:3072
	ds_read_b128 v[124:127], v160
	ds_read_b128 v[136:139], v160 offset:1024
	ds_read_b128 v[148:151], v160 offset:2048
	ds_read_b128 v[160:163], v160 offset:3072
	s_add_u32 s30, s30, 0x160000
	s_addc_u32 s31, s31, 0
	s_mov_b32 m0, s34
	ds_read_b128 v[164:167], v241 offset:32768
	ds_read_b128 v[168:171], v241 offset:33792
	ds_read_b128 v[172:175], v241 offset:34816
	ds_read_b128 v[176:179], v241 offset:35840
	ds_read_b128 v[180:183], v241 offset:36864
	ds_read_b128 v[184:187], v241 offset:37888
	ds_read_b128 v[188:191], v241 offset:38912
	ds_read_b128 v[192:195], v241 offset:39936
	global_load_lds_dwordx4 v208, s[30:31]
	v_lshl_add_u64 v[204:205], s[30:31], 0, v[218:219]
	s_mov_b32 m0, s67
	s_nop 0
	global_load_lds_dwordx4 v[204:205], off
	s_waitcnt vmcnt(8)
	s_waitcnt lgkmcnt(0)
	s_barrier
	s_setprio 1
	s_waitcnt lgkmcnt(0)
	v_mfma_f32_16x16x32_bf16 v[156:159], v[76:79], v[164:167], v[156:159]
	v_mfma_f32_16x16x32_bf16 v[156:159], v[88:91], v[168:171], v[156:159]
	v_mfma_f32_16x16x32_bf16 v[144:147], v[76:79], v[172:175], v[144:147]
	v_mfma_f32_16x16x32_bf16 v[144:147], v[88:91], v[176:179], v[144:147]
	v_mfma_f32_16x16x32_bf16 v[132:135], v[76:79], v[180:183], v[132:135]
	v_mfma_f32_16x16x32_bf16 v[132:135], v[88:91], v[184:187], v[132:135]
	v_mfma_f32_16x16x32_bf16 v[120:123], v[76:79], v[188:191], v[120:123]
	v_mfma_f32_16x16x32_bf16 v[120:123], v[88:91], v[192:195], v[120:123]
	v_mfma_f32_16x16x32_bf16 v[152:155], v[100:103], v[164:167], v[152:155]
	v_mfma_f32_16x16x32_bf16 v[152:155], v[112:115], v[168:171], v[152:155]
	v_mfma_f32_16x16x32_bf16 v[140:143], v[100:103], v[172:175], v[140:143]
	v_mfma_f32_16x16x32_bf16 v[140:143], v[112:115], v[176:179], v[140:143]
	v_mfma_f32_16x16x32_bf16 v[128:131], v[100:103], v[180:183], v[128:131]
	v_mfma_f32_16x16x32_bf16 v[128:131], v[112:115], v[184:187], v[128:131]
	v_mfma_f32_16x16x32_bf16 v[116:119], v[100:103], v[188:191], v[116:119]
	v_mfma_f32_16x16x32_bf16 v[116:119], v[112:115], v[192:195], v[116:119]
	s_setprio 0
	s_setprio 1
	v_mfma_f32_16x16x32_bf16 v[108:111], v[124:127], v[164:167], v[108:111]
	v_mfma_f32_16x16x32_bf16 v[108:111], v[136:139], v[168:171], v[108:111]
	v_mfma_f32_16x16x32_bf16 v[96:99], v[124:127], v[172:175], v[96:99]
	v_mfma_f32_16x16x32_bf16 v[96:99], v[136:139], v[176:179], v[96:99]
	v_mfma_f32_16x16x32_bf16 v[84:87], v[124:127], v[180:183], v[84:87]
	v_mfma_f32_16x16x32_bf16 v[84:87], v[136:139], v[184:187], v[84:87]
	v_mfma_f32_16x16x32_bf16 v[72:75], v[124:127], v[188:191], v[72:75]
	v_mfma_f32_16x16x32_bf16 v[72:75], v[136:139], v[192:195], v[72:75]
	v_mfma_f32_16x16x32_bf16 v[104:107], v[148:151], v[164:167], v[104:107]
	v_mfma_f32_16x16x32_bf16 v[104:107], v[160:163], v[168:171], v[104:107]
	v_mfma_f32_16x16x32_bf16 v[92:95], v[148:151], v[172:175], v[92:95]
	v_mfma_f32_16x16x32_bf16 v[92:95], v[160:163], v[176:179], v[92:95]
	v_mfma_f32_16x16x32_bf16 v[80:83], v[148:151], v[180:183], v[80:83]
	v_mfma_f32_16x16x32_bf16 v[80:83], v[160:163], v[184:187], v[80:83]
	v_mfma_f32_16x16x32_bf16 v[64:67], v[148:151], v[188:191], v[64:67]
	v_mfma_f32_16x16x32_bf16 v[64:67], v[160:163], v[192:195], v[64:67]
	s_setprio 0
	s_barrier
	s_nop 1
	s_add_i32 s3, s3, s33
	v_lshl_add_u64 v[196:197], v[196:197], 0, s[72:73]
	s_mov_b32 m0, s3
	ds_read_b128 v[164:167], v241 offset:49152
	ds_read_b128 v[168:171], v241 offset:50176
	ds_read_b128 v[172:175], v241 offset:51200
	ds_read_b128 v[176:179], v241 offset:52224
	ds_read_b128 v[180:183], v241 offset:53248
	ds_read_b128 v[184:187], v241 offset:54272
	ds_read_b128 v[188:191], v241 offset:55296
	ds_read_b128 v[192:195], v241 offset:56320
	global_load_lds_dwordx4 v[196:197], off
	s_add_i32 m0, s3, 0x2000
	s_add_u32 s28, s28, 0x160080
	v_lshl_add_u64 v[196:197], v[198:199], 0, s[72:73]
	s_addc_u32 s29, s29, 0
	s_add_i32 s3, s55, s33
	global_load_lds_dwordx4 v[196:197], off
	s_mov_b32 m0, s3
	s_nop 0
	global_load_lds_dwordx4 v210, s[28:29]
	s_add_i32 m0, s3, 0x2000
	s_nop 0
	global_load_lds_dwordx4 v220, s[28:29]
	v_lshl_add_u64 v[196:197], v[200:201], 0, s[72:73]
	s_mov_b32 m0, s81
	s_nop 0
	global_load_lds_dwordx4 v[196:197], off
	v_lshl_add_u64 v[196:197], v[202:203], 0, s[72:73]
	s_mov_b32 m0, s82
	s_nop 0
	global_load_lds_dwordx4 v[196:197], off
	s_waitcnt vmcnt(8)
	s_waitcnt lgkmcnt(0)
	s_barrier
	s_setprio 1
	s_waitcnt lgkmcnt(0)
	v_mfma_f32_16x16x32_bf16 v[60:63], v[76:79], v[164:167], v[60:63]
	v_mfma_f32_16x16x32_bf16 v[60:63], v[88:91], v[168:171], v[60:63]
	v_mfma_f32_16x16x32_bf16 v[52:55], v[76:79], v[172:175], v[52:55]
	v_mfma_f32_16x16x32_bf16 v[52:55], v[88:91], v[176:179], v[52:55]
	v_mfma_f32_16x16x32_bf16 v[44:47], v[76:79], v[180:183], v[44:47]
	v_mfma_f32_16x16x32_bf16 v[44:47], v[88:91], v[184:187], v[44:47]
	v_mfma_f32_16x16x32_bf16 v[36:39], v[76:79], v[188:191], v[36:39]
	v_mfma_f32_16x16x32_bf16 v[36:39], v[88:91], v[192:195], v[36:39]
	v_mfma_f32_16x16x32_bf16 v[56:59], v[100:103], v[164:167], v[56:59]
	v_mfma_f32_16x16x32_bf16 v[56:59], v[112:115], v[168:171], v[56:59]
	v_mfma_f32_16x16x32_bf16 v[48:51], v[100:103], v[172:175], v[48:51]
	v_mfma_f32_16x16x32_bf16 v[48:51], v[112:115], v[176:179], v[48:51]
	v_mfma_f32_16x16x32_bf16 v[40:43], v[100:103], v[180:183], v[40:43]
	v_mfma_f32_16x16x32_bf16 v[40:43], v[112:115], v[184:187], v[40:43]
	v_mfma_f32_16x16x32_bf16 v[32:35], v[100:103], v[188:191], v[32:35]
	v_mfma_f32_16x16x32_bf16 v[32:35], v[112:115], v[192:195], v[32:35]
	s_setprio 0
	s_setprio 1
	v_mfma_f32_16x16x32_bf16 v[28:31], v[124:127], v[164:167], v[28:31]
	v_mfma_f32_16x16x32_bf16 v[28:31], v[136:139], v[168:171], v[28:31]
	v_mfma_f32_16x16x32_bf16 v[20:23], v[124:127], v[172:175], v[20:23]
	v_mfma_f32_16x16x32_bf16 v[20:23], v[136:139], v[176:179], v[20:23]
	v_mfma_f32_16x16x32_bf16 v[12:15], v[124:127], v[180:183], v[12:15]
	v_mfma_f32_16x16x32_bf16 v[12:15], v[136:139], v[184:187], v[12:15]
	v_mfma_f32_16x16x32_bf16 v[4:7], v[124:127], v[188:191], v[4:7]
	v_mfma_f32_16x16x32_bf16 v[4:7], v[136:139], v[192:195], v[4:7]
	v_mfma_f32_16x16x32_bf16 v[24:27], v[148:151], v[164:167], v[24:27]
	v_mfma_f32_16x16x32_bf16 v[24:27], v[160:163], v[168:171], v[24:27]
	v_mfma_f32_16x16x32_bf16 v[16:19], v[148:151], v[172:175], v[16:19]
	v_mfma_f32_16x16x32_bf16 v[16:19], v[160:163], v[176:179], v[16:19]
	v_mfma_f32_16x16x32_bf16 v[8:11], v[148:151], v[180:183], v[8:11]
	v_mfma_f32_16x16x32_bf16 v[8:11], v[160:163], v[184:187], v[8:11]
	v_mfma_f32_16x16x32_bf16 v[0:3], v[148:151], v[188:191], v[0:3]
	v_mfma_f32_16x16x32_bf16 v[0:3], v[160:163], v[192:195], v[0:3]
	s_setprio 0
	s_barrier
	s_nop 1
	s_add_u32 s26, s26, 0x100
	s_addc_u32 s27, s27, 0
	s_cmp_ge_i32 s2, s17
	s_mov_b32 s28, s2
	s_cbranch_scc1 .LBB0_1669
